# conv_t ladders in the W2-phase slack (16 loops) and 2 phase-0 loops batched: all loads issued before the LDS stores, counted vmcnt
# speedup vs baseline: 1.0059x; 1.0059x over previous
.LBB0_111:
	s_lshl_b32 s17, s3, 1
	s_lshl_b32 s18, s1, 1
	v_add_u32_e32 v42, s17, v24
	v_add_u32_e32 v44, s18, v21
	v_mad_i64_i32 v[42:43], s[20:21], v42, s60, v[22:23]
	v_mad_i64_i32 v[44:45], s[20:21], v44, s60, v[22:23]
	global_load_dword v200, v[42:43], off
	global_load_dword v201, v[44:45], off
	v_add_u32_e32 v42, s17, v26
	v_add_u32_e32 v44, s18, v25
	v_mad_i64_i32 v[42:43], s[20:21], v42, s60, v[22:23]
	v_mad_i64_i32 v[44:45], s[20:21], v44, s60, v[22:23]
	global_load_dword v202, v[42:43], off
	global_load_dword v203, v[44:45], off
	v_add_u32_e32 v42, s17, v28
	v_add_u32_e32 v44, s18, v27
	v_mad_i64_i32 v[42:43], s[20:21], v42, s60, v[22:23]
	v_mad_i64_i32 v[44:45], s[20:21], v44, s60, v[22:23]
	global_load_dword v204, v[42:43], off
	global_load_dword v205, v[44:45], off
	v_add_u32_e32 v42, s17, v30
	v_add_u32_e32 v44, s18, v29
	v_mad_i64_i32 v[42:43], s[20:21], v42, s60, v[22:23]
	v_mad_i64_i32 v[44:45], s[20:21], v44, s60, v[22:23]
	global_load_dword v206, v[42:43], off
	global_load_dword v207, v[44:45], off
	v_add_u32_e32 v42, s17, v32
	v_add_u32_e32 v44, s18, v31
	v_mad_i64_i32 v[42:43], s[20:21], v42, s60, v[22:23]
	v_mad_i64_i32 v[44:45], s[20:21], v44, s60, v[22:23]
	global_load_dword v208, v[42:43], off
	global_load_dword v209, v[44:45], off
	v_add_u32_e32 v42, s17, v34
	v_add_u32_e32 v44, s18, v33
	v_mad_i64_i32 v[42:43], s[20:21], v42, s60, v[22:23]
	v_mad_i64_i32 v[44:45], s[20:21], v44, s60, v[22:23]
	global_load_dword v210, v[42:43], off
	global_load_dword v211, v[44:45], off
	v_add_u32_e32 v42, s17, v36
	v_add_u32_e32 v44, s18, v35
	v_mad_i64_i32 v[42:43], s[20:21], v42, s60, v[22:23]
	v_mad_i64_i32 v[44:45], s[20:21], v44, s60, v[22:23]
	global_load_dword v212, v[42:43], off
	global_load_dword v213, v[44:45], off
	v_add_u32_e32 v42, s17, v38
	v_add_u32_e32 v44, s18, v37
	v_mad_i64_i32 v[42:43], s[20:21], v42, s60, v[22:23]
	v_mad_i64_i32 v[44:45], s[20:21], v44, s60, v[22:23]
	global_load_dword v214, v[42:43], off
	global_load_dword v215, v[44:45], off
	v_add_u32_e32 v46, s17, v0
	v_add_u32_e32 v41, s18, v1
	v_mad_u64_u32 v[42:43], s[20:21], v46, s59, v[2:3]
	v_mad_u64_u32 v[44:45], s[20:21], v41, s59, v[2:3]
	v_add_u32_e32 v46, s17, v8
	v_add_u32_e32 v41, s18, v3
	s_add_i32 s3, s3, 16
	s_add_i32 s1, s1, 16
	s_add_i32 s5, s5, -16
	s_cmp_lg_u32 s5, 0
	s_waitcnt vmcnt(14)
	ds_write_b32 v42, v200
	ds_write_b32 v44, v201
	v_mad_u64_u32 v[42:43], s[20:21], v46, s59, v[2:3]
	v_mad_u64_u32 v[44:45], s[20:21], v41, s59, v[2:3]
	v_add_u32_e32 v46, s17, v10
	v_add_u32_e32 v41, s18, v9
	s_waitcnt vmcnt(12)
	ds_write_b32 v42, v202
	ds_write_b32 v44, v203
	v_mad_u64_u32 v[42:43], s[20:21], v46, s59, v[2:3]
	v_mad_u64_u32 v[44:45], s[20:21], v41, s59, v[2:3]
	v_add_u32_e32 v46, s17, v12
	v_add_u32_e32 v41, s18, v11
	s_waitcnt vmcnt(10)
	ds_write_b32 v42, v204
	ds_write_b32 v44, v205
	v_mad_u64_u32 v[42:43], s[20:21], v46, s59, v[2:3]
	v_mad_u64_u32 v[44:45], s[20:21], v41, s59, v[2:3]
	v_add_u32_e32 v46, s17, v14
	v_add_u32_e32 v41, s18, v13
	s_waitcnt vmcnt(8)
	ds_write_b32 v42, v206
	ds_write_b32 v44, v207
	v_mad_u64_u32 v[42:43], s[20:21], v46, s59, v[2:3]
	v_mad_u64_u32 v[44:45], s[20:21], v41, s59, v[2:3]
	v_add_u32_e32 v46, s17, v16
	v_add_u32_e32 v41, s18, v15
	s_waitcnt vmcnt(6)
	ds_write_b32 v42, v208
	ds_write_b32 v44, v209
	v_mad_u64_u32 v[42:43], s[20:21], v46, s59, v[2:3]
	v_mad_u64_u32 v[44:45], s[20:21], v41, s59, v[2:3]
	v_add_u32_e32 v46, s17, v18
	v_add_u32_e32 v41, s18, v17
	s_waitcnt vmcnt(4)
	ds_write_b32 v42, v210
	ds_write_b32 v44, v211
	v_mad_u64_u32 v[42:43], s[20:21], v46, s59, v[2:3]
	v_mad_u64_u32 v[44:45], s[20:21], v41, s59, v[2:3]
	v_add_u32_e32 v41, s18, v19
	v_add_u32_e32 v46, s17, v20
	s_waitcnt vmcnt(2)
	ds_write_b32 v42, v212
	ds_write_b32 v44, v213
	v_mad_u64_u32 v[42:43], s[18:19], v46, s59, v[2:3]
	v_mad_u64_u32 v[44:45], s[18:19], v41, s59, v[2:3]
	s_waitcnt vmcnt(0)
	ds_write_b32 v42, v214
	ds_write_b32 v44, v215
	s_cbranch_scc1 .LBB0_111
	s_waitcnt lgkmcnt(0)
	ds_read2_b32 v[22:23], v40 offset1:33
	s_waitcnt lgkmcnt(0)
	v_cvt_pk_bf16_f32 v22, v22, v23
	ds_read2_b32 v[24:25], v40 offset0:66 offset1:99
	s_waitcnt lgkmcnt(0)
	v_cvt_pk_bf16_f32 v23, v24, v25
	ds_read2_b32 v[24:25], v40 offset0:132 offset1:165
	s_waitcnt lgkmcnt(0)
	v_cvt_pk_bf16_f32 v24, v24, v25
	ds_read2_b32 v[28:29], v40 offset0:198 offset1:231
	s_waitcnt lgkmcnt(0)
	v_cvt_pk_bf16_f32 v25, v28, v29
	v_add_u32_e32 v28, s0, v39
	s_ashr_i32 s3, s2, 31
	v_ashrrev_i32_e32 v29, 31, v28
	v_lshl_add_u64 v[26:27], s[2:3], 1, v[6:7]
	v_lshlrev_b64 v[30:31], 11, v[28:29]
	v_lshl_add_u64 v[30:31], v[26:27], 0, v[30:31]
	global_store_dwordx4 v[30:31], v[22:25], off
	ds_read2_b32 v[22:23], v40 offset0:8 offset1:41
	s_add_i32 s4, s4, s11
	s_waitcnt lgkmcnt(0)
	v_cvt_pk_bf16_f32 v22, v22, v23
	ds_read2_b32 v[24:25], v40 offset0:74 offset1:107
	s_waitcnt lgkmcnt(0)
	v_cvt_pk_bf16_f32 v23, v24, v25
	ds_read2_b32 v[24:25], v40 offset0:140 offset1:173
	s_waitcnt lgkmcnt(0)
	v_cvt_pk_bf16_f32 v24, v24, v25
	ds_read2_b32 v[30:31], v40 offset0:206 offset1:239
	s_waitcnt lgkmcnt(0)
	v_cvt_pk_bf16_f32 v25, v30, v31
	v_add_u32_e32 v30, 8, v28
	v_ashrrev_i32_e32 v31, 31, v30
	v_lshlrev_b64 v[30:31], 11, v[30:31]
	v_lshl_add_u64 v[30:31], v[26:27], 0, v[30:31]
	global_store_dwordx4 v[30:31], v[22:25], off
	ds_read2_b32 v[22:23], v40 offset0:16 offset1:49
	s_cmpk_lt_i32 s4, 0x600
	s_waitcnt lgkmcnt(0)
	v_cvt_pk_bf16_f32 v22, v22, v23
	ds_read2_b32 v[24:25], v40 offset0:82 offset1:115
	s_waitcnt lgkmcnt(0)
	v_cvt_pk_bf16_f32 v23, v24, v25
	ds_read2_b32 v[24:25], v40 offset0:148 offset1:181
	s_waitcnt lgkmcnt(0)
	v_cvt_pk_bf16_f32 v24, v24, v25
	ds_read2_b32 v[30:31], v40 offset0:214 offset1:247
	s_waitcnt lgkmcnt(0)
	v_cvt_pk_bf16_f32 v25, v30, v31
	v_add_u32_e32 v30, 16, v28
	v_ashrrev_i32_e32 v31, 31, v30
	v_lshlrev_b64 v[30:31], 11, v[30:31]
	v_lshl_add_u64 v[30:31], v[26:27], 0, v[30:31]
	v_add_u32_e32 v28, 24, v28
	global_store_dwordx4 v[30:31], v[22:25], off
	ds_read2_b32 v[22:23], v40 offset0:24 offset1:57
	v_ashrrev_i32_e32 v29, 31, v28
	s_waitcnt lgkmcnt(0)
	v_cvt_pk_bf16_f32 v22, v22, v23
	ds_read2_b32 v[24:25], v40 offset0:90 offset1:123
	v_lshlrev_b64 v[28:29], 11, v[28:29]
	s_waitcnt lgkmcnt(0)
	v_cvt_pk_bf16_f32 v23, v24, v25
	ds_read2_b32 v[24:25], v40 offset0:156 offset1:189
	v_lshl_add_u64 v[26:27], v[26:27], 0, v[28:29]
	s_waitcnt lgkmcnt(0)
	v_cvt_pk_bf16_f32 v24, v24, v25
	ds_read2_b32 v[30:31], v40 offset0:222 offset1:255
	s_waitcnt lgkmcnt(0)
	v_cvt_pk_bf16_f32 v25, v30, v31
	global_store_dwordx4 v[26:27], v[22:25], off
	s_waitcnt lgkmcnt(0)
	s_cbranch_scc1 .LBB0_110

.LBB0_116:
	s_lshl_b32 s20, s1, 1
	s_lshl_b32 s21, s3, 1
	v_add_u32_e32 v44, s20, v24
	v_add_u32_e32 v42, s21, v21
	v_ashrrev_i32_e32 v45, 31, v44
	v_ashrrev_i32_e32 v43, 31, v42
	v_lshlrev_b64 v[44:45], 12, v[44:45]
	v_lshlrev_b64 v[42:43], 12, v[42:43]
	v_lshl_add_u64 v[44:45], v[22:23], 0, v[44:45]
	v_lshl_add_u64 v[42:43], v[22:23], 0, v[42:43]
	global_load_dword v200, v[44:45], off
	global_load_dword v201, v[42:43], off
	v_add_u32_e32 v44, s20, v26
	v_add_u32_e32 v42, s21, v25
	v_ashrrev_i32_e32 v45, 31, v44
	v_ashrrev_i32_e32 v43, 31, v42
	v_lshlrev_b64 v[44:45], 12, v[44:45]
	v_lshlrev_b64 v[42:43], 12, v[42:43]
	v_lshl_add_u64 v[44:45], v[22:23], 0, v[44:45]
	v_lshl_add_u64 v[42:43], v[22:23], 0, v[42:43]
	global_load_dword v202, v[44:45], off
	global_load_dword v203, v[42:43], off
	v_add_u32_e32 v44, s20, v28
	v_add_u32_e32 v42, s21, v27
	v_ashrrev_i32_e32 v45, 31, v44
	v_ashrrev_i32_e32 v43, 31, v42
	v_lshlrev_b64 v[44:45], 12, v[44:45]
	v_lshlrev_b64 v[42:43], 12, v[42:43]
	v_lshl_add_u64 v[44:45], v[22:23], 0, v[44:45]
	v_lshl_add_u64 v[42:43], v[22:23], 0, v[42:43]
	global_load_dword v204, v[44:45], off
	global_load_dword v205, v[42:43], off
	v_add_u32_e32 v44, s20, v30
	v_add_u32_e32 v42, s21, v29
	v_ashrrev_i32_e32 v45, 31, v44
	v_ashrrev_i32_e32 v43, 31, v42
	v_lshlrev_b64 v[44:45], 12, v[44:45]
	v_lshlrev_b64 v[42:43], 12, v[42:43]
	v_lshl_add_u64 v[44:45], v[22:23], 0, v[44:45]
	v_lshl_add_u64 v[42:43], v[22:23], 0, v[42:43]
	global_load_dword v206, v[44:45], off
	global_load_dword v207, v[42:43], off
	v_add_u32_e32 v44, s20, v32
	v_add_u32_e32 v42, s21, v31
	v_ashrrev_i32_e32 v45, 31, v44
	v_ashrrev_i32_e32 v43, 31, v42
	v_lshlrev_b64 v[44:45], 12, v[44:45]
	v_lshlrev_b64 v[42:43], 12, v[42:43]
	v_lshl_add_u64 v[44:45], v[22:23], 0, v[44:45]
	v_lshl_add_u64 v[42:43], v[22:23], 0, v[42:43]
	global_load_dword v208, v[44:45], off
	global_load_dword v209, v[42:43], off
	v_add_u32_e32 v44, s20, v34
	v_add_u32_e32 v42, s21, v33
	v_ashrrev_i32_e32 v45, 31, v44
	v_ashrrev_i32_e32 v43, 31, v42
	v_lshlrev_b64 v[44:45], 12, v[44:45]
	v_lshlrev_b64 v[42:43], 12, v[42:43]
	v_lshl_add_u64 v[44:45], v[22:23], 0, v[44:45]
	v_lshl_add_u64 v[42:43], v[22:23], 0, v[42:43]
	global_load_dword v210, v[44:45], off
	global_load_dword v211, v[42:43], off
	v_add_u32_e32 v44, s20, v36
	v_add_u32_e32 v42, s21, v35
	v_ashrrev_i32_e32 v45, 31, v44
	v_ashrrev_i32_e32 v43, 31, v42
	v_lshlrev_b64 v[44:45], 12, v[44:45]
	v_lshlrev_b64 v[42:43], 12, v[42:43]
	v_lshl_add_u64 v[44:45], v[22:23], 0, v[44:45]
	v_lshl_add_u64 v[42:43], v[22:23], 0, v[42:43]
	global_load_dword v212, v[44:45], off
	global_load_dword v213, v[42:43], off
	v_add_u32_e32 v44, s20, v38
	v_add_u32_e32 v42, s21, v37
	v_ashrrev_i32_e32 v45, 31, v44
	v_ashrrev_i32_e32 v43, 31, v42
	v_lshlrev_b64 v[44:45], 12, v[44:45]
	v_lshlrev_b64 v[42:43], 12, v[42:43]
	v_lshl_add_u64 v[44:45], v[22:23], 0, v[44:45]
	v_lshl_add_u64 v[42:43], v[22:23], 0, v[42:43]
	global_load_dword v214, v[44:45], off
	global_load_dword v215, v[42:43], off
	v_add_u32_e32 v41, s21, v1
	v_add_u32_e32 v46, s20, v0
	v_mad_u64_u32 v[42:43], s[24:25], v46, s59, v[2:3]
	v_mad_u64_u32 v[44:45], s[24:25], v41, s59, v[2:3]
	v_add_u32_e32 v41, s21, v3
	v_add_u32_e32 v46, s20, v8
	s_add_i32 s1, s1, 16
	s_add_i32 s3, s3, 16
	s_add_i32 s19, s19, -16
	s_cmp_lg_u32 s19, 0
	s_waitcnt vmcnt(14)
	ds_write_b32 v42, v200
	ds_write_b32 v44, v201
	v_mad_u64_u32 v[42:43], s[24:25], v46, s59, v[2:3]
	v_mad_u64_u32 v[44:45], s[24:25], v41, s59, v[2:3]
	v_add_u32_e32 v41, s21, v9
	v_add_u32_e32 v46, s20, v10
	s_waitcnt vmcnt(12)
	ds_write_b32 v42, v202
	ds_write_b32 v44, v203
	v_mad_u64_u32 v[42:43], s[24:25], v46, s59, v[2:3]
	v_mad_u64_u32 v[44:45], s[24:25], v41, s59, v[2:3]
	v_add_u32_e32 v41, s21, v11
	v_add_u32_e32 v46, s20, v12
	s_waitcnt vmcnt(10)
	ds_write_b32 v42, v204
	ds_write_b32 v44, v205
	v_mad_u64_u32 v[42:43], s[24:25], v46, s59, v[2:3]
	v_mad_u64_u32 v[44:45], s[24:25], v41, s59, v[2:3]
	v_add_u32_e32 v41, s21, v13
	v_add_u32_e32 v46, s20, v14
	s_waitcnt vmcnt(8)
	ds_write_b32 v42, v206
	ds_write_b32 v44, v207
	v_mad_u64_u32 v[42:43], s[24:25], v46, s59, v[2:3]
	v_mad_u64_u32 v[44:45], s[24:25], v41, s59, v[2:3]
	v_add_u32_e32 v41, s21, v15
	v_add_u32_e32 v46, s20, v16
	s_waitcnt vmcnt(6)
	ds_write_b32 v42, v208
	ds_write_b32 v44, v209
	v_mad_u64_u32 v[42:43], s[24:25], v46, s59, v[2:3]
	v_mad_u64_u32 v[44:45], s[24:25], v41, s59, v[2:3]
	v_add_u32_e32 v41, s21, v17
	v_add_u32_e32 v46, s20, v18
	s_waitcnt vmcnt(4)
	ds_write_b32 v42, v210
	ds_write_b32 v44, v211
	v_mad_u64_u32 v[42:43], s[24:25], v46, s59, v[2:3]
	v_mad_u64_u32 v[44:45], s[24:25], v41, s59, v[2:3]
	v_add_u32_e32 v46, s20, v20
	v_add_u32_e32 v41, s21, v19
	s_waitcnt vmcnt(2)
	ds_write_b32 v42, v212
	ds_write_b32 v44, v213
	v_mad_u64_u32 v[42:43], s[20:21], v46, s59, v[2:3]
	v_mad_u64_u32 v[44:45], s[20:21], v41, s59, v[2:3]
	s_waitcnt vmcnt(0)
	ds_write_b32 v42, v214
	ds_write_b32 v44, v215
	s_cbranch_scc1 .LBB0_116
	s_waitcnt lgkmcnt(0)
	ds_read2_b32 v[22:23], v40 offset1:33
	s_waitcnt lgkmcnt(0)
	v_cvt_pk_bf16_f32 v22, v22, v23
	ds_read2_b32 v[24:25], v40 offset0:66 offset1:99
	s_waitcnt lgkmcnt(0)
	v_cvt_pk_bf16_f32 v23, v24, v25
	ds_read2_b32 v[24:25], v40 offset0:132 offset1:165
	s_waitcnt lgkmcnt(0)
	v_cvt_pk_bf16_f32 v24, v24, v25
	ds_read2_b32 v[28:29], v40 offset0:198 offset1:231
	s_waitcnt lgkmcnt(0)
	v_cvt_pk_bf16_f32 v25, v28, v29
	v_add_u32_e32 v28, s0, v39
	s_ashr_i32 s3, s2, 31
	v_ashrrev_i32_e32 v29, 31, v28
	v_lshl_add_u64 v[26:27], s[2:3], 1, v[6:7]
	v_lshlrev_b64 v[30:31], 11, v[28:29]
	v_lshl_add_u64 v[30:31], v[26:27], 0, v[30:31]
	global_store_dwordx4 v[30:31], v[22:25], off
	ds_read2_b32 v[22:23], v40 offset0:8 offset1:41
	s_add_i32 s5, s5, s11
	s_waitcnt lgkmcnt(0)
	v_cvt_pk_bf16_f32 v22, v22, v23
	ds_read2_b32 v[24:25], v40 offset0:74 offset1:107
	s_waitcnt lgkmcnt(0)
	v_cvt_pk_bf16_f32 v23, v24, v25
	ds_read2_b32 v[24:25], v40 offset0:140 offset1:173
	s_waitcnt lgkmcnt(0)
	v_cvt_pk_bf16_f32 v24, v24, v25
	ds_read2_b32 v[30:31], v40 offset0:206 offset1:239
	s_waitcnt lgkmcnt(0)
	v_cvt_pk_bf16_f32 v25, v30, v31
	v_add_u32_e32 v30, 8, v28
	v_ashrrev_i32_e32 v31, 31, v30
	v_lshlrev_b64 v[30:31], 11, v[30:31]
	v_lshl_add_u64 v[30:31], v[26:27], 0, v[30:31]
	global_store_dwordx4 v[30:31], v[22:25], off
	ds_read2_b32 v[22:23], v40 offset0:16 offset1:49
	s_cmpk_lt_i32 s5, 0x200
	s_waitcnt lgkmcnt(0)
	v_cvt_pk_bf16_f32 v22, v22, v23
	ds_read2_b32 v[24:25], v40 offset0:82 offset1:115
	s_waitcnt lgkmcnt(0)
	v_cvt_pk_bf16_f32 v23, v24, v25
	ds_read2_b32 v[24:25], v40 offset0:148 offset1:181
	s_waitcnt lgkmcnt(0)
	v_cvt_pk_bf16_f32 v24, v24, v25
	ds_read2_b32 v[30:31], v40 offset0:214 offset1:247
	s_waitcnt lgkmcnt(0)
	v_cvt_pk_bf16_f32 v25, v30, v31
	v_add_u32_e32 v30, 16, v28
	v_ashrrev_i32_e32 v31, 31, v30
	v_lshlrev_b64 v[30:31], 11, v[30:31]
	v_lshl_add_u64 v[30:31], v[26:27], 0, v[30:31]
	v_add_u32_e32 v28, 24, v28
	global_store_dwordx4 v[30:31], v[22:25], off
	ds_read2_b32 v[22:23], v40 offset0:24 offset1:57
	v_ashrrev_i32_e32 v29, 31, v28
	s_waitcnt lgkmcnt(0)
	v_cvt_pk_bf16_f32 v22, v22, v23
	ds_read2_b32 v[24:25], v40 offset0:90 offset1:123
	v_lshlrev_b64 v[28:29], 11, v[28:29]
	s_waitcnt lgkmcnt(0)
	v_cvt_pk_bf16_f32 v23, v24, v25
	ds_read2_b32 v[24:25], v40 offset0:156 offset1:189
	v_lshl_add_u64 v[26:27], v[26:27], 0, v[28:29]
	s_waitcnt lgkmcnt(0)
	v_cvt_pk_bf16_f32 v24, v24, v25
	ds_read2_b32 v[30:31], v40 offset0:222 offset1:255
	s_waitcnt lgkmcnt(0)
	v_cvt_pk_bf16_f32 v25, v30, v31
	global_store_dwordx4 v[26:27], v[22:25], off
	s_waitcnt lgkmcnt(0)
	s_cbranch_scc1 .LBB0_115

.LBB0_121:
	s_lshl_b32 s20, s3, 1
	s_lshl_b32 s21, s1, 1
	v_add_u32_e32 v44, s20, v24
	v_add_u32_e32 v42, s21, v21
	v_ashrrev_i32_e32 v45, 31, v44
	v_ashrrev_i32_e32 v43, 31, v42
	v_lshlrev_b64 v[44:45], 14, v[44:45]
	v_lshlrev_b64 v[42:43], 14, v[42:43]
	v_lshl_add_u64 v[44:45], v[22:23], 0, v[44:45]
	v_lshl_add_u64 v[42:43], v[22:23], 0, v[42:43]
	global_load_dword v200, v[44:45], off
	global_load_dword v201, v[42:43], off
	v_add_u32_e32 v44, s20, v26
	v_add_u32_e32 v42, s21, v25
	v_ashrrev_i32_e32 v45, 31, v44
	v_ashrrev_i32_e32 v43, 31, v42
	v_lshlrev_b64 v[44:45], 14, v[44:45]
	v_lshlrev_b64 v[42:43], 14, v[42:43]
	v_lshl_add_u64 v[44:45], v[22:23], 0, v[44:45]
	v_lshl_add_u64 v[42:43], v[22:23], 0, v[42:43]
	global_load_dword v202, v[44:45], off
	global_load_dword v203, v[42:43], off
	v_add_u32_e32 v44, s20, v28
	v_add_u32_e32 v42, s21, v27
	v_ashrrev_i32_e32 v45, 31, v44
	v_ashrrev_i32_e32 v43, 31, v42
	v_lshlrev_b64 v[44:45], 14, v[44:45]
	v_lshlrev_b64 v[42:43], 14, v[42:43]
	v_lshl_add_u64 v[44:45], v[22:23], 0, v[44:45]
	v_lshl_add_u64 v[42:43], v[22:23], 0, v[42:43]
	global_load_dword v204, v[44:45], off
	global_load_dword v205, v[42:43], off
	v_add_u32_e32 v44, s20, v30
	v_add_u32_e32 v42, s21, v29
	v_ashrrev_i32_e32 v45, 31, v44
	v_ashrrev_i32_e32 v43, 31, v42
	v_lshlrev_b64 v[44:45], 14, v[44:45]
	v_lshlrev_b64 v[42:43], 14, v[42:43]
	v_lshl_add_u64 v[44:45], v[22:23], 0, v[44:45]
	v_lshl_add_u64 v[42:43], v[22:23], 0, v[42:43]
	global_load_dword v206, v[44:45], off
	global_load_dword v207, v[42:43], off
	v_add_u32_e32 v44, s20, v32
	v_add_u32_e32 v42, s21, v31
	v_ashrrev_i32_e32 v45, 31, v44
	v_ashrrev_i32_e32 v43, 31, v42
	v_lshlrev_b64 v[44:45], 14, v[44:45]
	v_lshlrev_b64 v[42:43], 14, v[42:43]
	v_lshl_add_u64 v[44:45], v[22:23], 0, v[44:45]
	v_lshl_add_u64 v[42:43], v[22:23], 0, v[42:43]
	global_load_dword v208, v[44:45], off
	global_load_dword v209, v[42:43], off
	v_add_u32_e32 v44, s20, v34
	v_add_u32_e32 v42, s21, v33
	v_ashrrev_i32_e32 v45, 31, v44
	v_ashrrev_i32_e32 v43, 31, v42
	v_lshlrev_b64 v[44:45], 14, v[44:45]
	v_lshlrev_b64 v[42:43], 14, v[42:43]
	v_lshl_add_u64 v[44:45], v[22:23], 0, v[44:45]
	v_lshl_add_u64 v[42:43], v[22:23], 0, v[42:43]
	global_load_dword v210, v[44:45], off
	global_load_dword v211, v[42:43], off
	v_add_u32_e32 v44, s20, v36
	v_add_u32_e32 v42, s21, v35
	v_ashrrev_i32_e32 v45, 31, v44
	v_ashrrev_i32_e32 v43, 31, v42
	v_lshlrev_b64 v[44:45], 14, v[44:45]
	v_lshlrev_b64 v[42:43], 14, v[42:43]
	v_lshl_add_u64 v[44:45], v[22:23], 0, v[44:45]
	v_lshl_add_u64 v[42:43], v[22:23], 0, v[42:43]
	global_load_dword v212, v[44:45], off
	global_load_dword v213, v[42:43], off
	v_add_u32_e32 v44, s20, v38
	v_add_u32_e32 v42, s21, v37
	v_ashrrev_i32_e32 v45, 31, v44
	v_ashrrev_i32_e32 v43, 31, v42
	v_lshlrev_b64 v[44:45], 14, v[44:45]
	v_lshlrev_b64 v[42:43], 14, v[42:43]
	v_lshl_add_u64 v[44:45], v[22:23], 0, v[44:45]
	v_lshl_add_u64 v[42:43], v[22:23], 0, v[42:43]
	global_load_dword v214, v[44:45], off
	global_load_dword v215, v[42:43], off
	v_add_u32_e32 v41, s21, v1
	v_add_u32_e32 v46, s20, v0
	v_mad_u64_u32 v[42:43], s[24:25], v46, s59, v[2:3]
	v_mad_u64_u32 v[44:45], s[24:25], v41, s59, v[2:3]
	v_add_u32_e32 v41, s21, v3
	v_add_u32_e32 v46, s20, v8
	s_add_i32 s3, s3, 16
	s_add_i32 s1, s1, 16
	s_add_i32 s5, s5, -16
	s_cmp_lg_u32 s5, 0
	s_waitcnt vmcnt(14)
	ds_write_b32 v42, v200
	ds_write_b32 v44, v201
	v_mad_u64_u32 v[42:43], s[24:25], v46, s59, v[2:3]
	v_mad_u64_u32 v[44:45], s[24:25], v41, s59, v[2:3]
	v_add_u32_e32 v41, s21, v9
	v_add_u32_e32 v46, s20, v10
	s_waitcnt vmcnt(12)
	ds_write_b32 v42, v202
	ds_write_b32 v44, v203
	v_mad_u64_u32 v[42:43], s[24:25], v46, s59, v[2:3]
	v_mad_u64_u32 v[44:45], s[24:25], v41, s59, v[2:3]
	v_add_u32_e32 v41, s21, v11
	v_add_u32_e32 v46, s20, v12
	s_waitcnt vmcnt(10)
	ds_write_b32 v42, v204
	ds_write_b32 v44, v205
	v_mad_u64_u32 v[42:43], s[24:25], v46, s59, v[2:3]
	v_mad_u64_u32 v[44:45], s[24:25], v41, s59, v[2:3]
	v_add_u32_e32 v41, s21, v13
	v_add_u32_e32 v46, s20, v14
	s_waitcnt vmcnt(8)
	ds_write_b32 v42, v206
	ds_write_b32 v44, v207
	v_mad_u64_u32 v[42:43], s[24:25], v46, s59, v[2:3]
	v_mad_u64_u32 v[44:45], s[24:25], v41, s59, v[2:3]
	v_add_u32_e32 v41, s21, v15
	v_add_u32_e32 v46, s20, v16
	s_waitcnt vmcnt(6)
	ds_write_b32 v42, v208
	ds_write_b32 v44, v209
	v_mad_u64_u32 v[42:43], s[24:25], v46, s59, v[2:3]
	v_mad_u64_u32 v[44:45], s[24:25], v41, s59, v[2:3]
	v_add_u32_e32 v41, s21, v17
	v_add_u32_e32 v46, s20, v18
	s_waitcnt vmcnt(4)
	ds_write_b32 v42, v210
	ds_write_b32 v44, v211
	v_mad_u64_u32 v[42:43], s[24:25], v46, s59, v[2:3]
	v_mad_u64_u32 v[44:45], s[24:25], v41, s59, v[2:3]
	v_add_u32_e32 v46, s20, v20
	v_add_u32_e32 v41, s21, v19
	s_waitcnt vmcnt(2)
	ds_write_b32 v42, v212
	ds_write_b32 v44, v213
	v_mad_u64_u32 v[42:43], s[20:21], v46, s59, v[2:3]
	v_mad_u64_u32 v[44:45], s[20:21], v41, s59, v[2:3]
	s_waitcnt vmcnt(0)
	ds_write_b32 v42, v214
	ds_write_b32 v44, v215
	s_cbranch_scc1 .LBB0_121
	s_waitcnt lgkmcnt(0)
	ds_read2_b32 v[22:23], v40 offset1:33
	s_waitcnt lgkmcnt(0)
	v_cvt_pk_bf16_f32 v22, v22, v23
	ds_read2_b32 v[24:25], v40 offset0:66 offset1:99
	s_waitcnt lgkmcnt(0)
	v_cvt_pk_bf16_f32 v23, v24, v25
	ds_read2_b32 v[24:25], v40 offset0:132 offset1:165
	s_waitcnt lgkmcnt(0)
	v_cvt_pk_bf16_f32 v24, v24, v25
	ds_read2_b32 v[28:29], v40 offset0:198 offset1:231
	s_waitcnt lgkmcnt(0)
	v_cvt_pk_bf16_f32 v25, v28, v29
	v_add_u32_e32 v28, s0, v39
	s_ashr_i32 s3, s2, 31
	v_ashrrev_i32_e32 v29, 31, v28
	v_lshl_add_u64 v[26:27], s[2:3], 1, v[6:7]
	v_lshlrev_b64 v[30:31], 11, v[28:29]
	v_lshl_add_u64 v[30:31], v[26:27], 0, v[30:31]
	global_store_dwordx4 v[30:31], v[22:25], off
	ds_read2_b32 v[22:23], v40 offset0:8 offset1:41
	s_add_i32 s4, s4, s11
	s_waitcnt lgkmcnt(0)
	v_cvt_pk_bf16_f32 v22, v22, v23
	ds_read2_b32 v[24:25], v40 offset0:74 offset1:107
	s_waitcnt lgkmcnt(0)
	v_cvt_pk_bf16_f32 v23, v24, v25
	ds_read2_b32 v[24:25], v40 offset0:140 offset1:173
	s_waitcnt lgkmcnt(0)
	v_cvt_pk_bf16_f32 v24, v24, v25
	ds_read2_b32 v[30:31], v40 offset0:206 offset1:239
	s_waitcnt lgkmcnt(0)
	v_cvt_pk_bf16_f32 v25, v30, v31
	v_add_u32_e32 v30, 8, v28
	v_ashrrev_i32_e32 v31, 31, v30
	v_lshlrev_b64 v[30:31], 11, v[30:31]
	v_lshl_add_u64 v[30:31], v[26:27], 0, v[30:31]
	global_store_dwordx4 v[30:31], v[22:25], off
	ds_read2_b32 v[22:23], v40 offset0:16 offset1:49
	s_cmpk_lt_i32 s4, 0x800
	s_waitcnt lgkmcnt(0)
	v_cvt_pk_bf16_f32 v22, v22, v23
	ds_read2_b32 v[24:25], v40 offset0:82 offset1:115
	s_waitcnt lgkmcnt(0)
	v_cvt_pk_bf16_f32 v23, v24, v25
	ds_read2_b32 v[24:25], v40 offset0:148 offset1:181
	s_waitcnt lgkmcnt(0)
	v_cvt_pk_bf16_f32 v24, v24, v25
	ds_read2_b32 v[30:31], v40 offset0:214 offset1:247
	s_waitcnt lgkmcnt(0)
	v_cvt_pk_bf16_f32 v25, v30, v31
	v_add_u32_e32 v30, 16, v28
	v_ashrrev_i32_e32 v31, 31, v30
	v_lshlrev_b64 v[30:31], 11, v[30:31]
	v_lshl_add_u64 v[30:31], v[26:27], 0, v[30:31]
	v_add_u32_e32 v28, 24, v28
	global_store_dwordx4 v[30:31], v[22:25], off
	ds_read2_b32 v[22:23], v40 offset0:24 offset1:57
	v_ashrrev_i32_e32 v29, 31, v28
	s_waitcnt lgkmcnt(0)
	v_cvt_pk_bf16_f32 v22, v22, v23
	ds_read2_b32 v[24:25], v40 offset0:90 offset1:123
	v_lshlrev_b64 v[28:29], 11, v[28:29]
	s_waitcnt lgkmcnt(0)
	v_cvt_pk_bf16_f32 v23, v24, v25
	ds_read2_b32 v[24:25], v40 offset0:156 offset1:189
	v_lshl_add_u64 v[26:27], v[26:27], 0, v[28:29]
	s_waitcnt lgkmcnt(0)
	v_cvt_pk_bf16_f32 v24, v24, v25
	ds_read2_b32 v[30:31], v40 offset0:222 offset1:255
	s_waitcnt lgkmcnt(0)
	v_cvt_pk_bf16_f32 v25, v30, v31
	global_store_dwordx4 v[26:27], v[22:25], off
	s_waitcnt lgkmcnt(0)
	s_cbranch_scc1 .LBB0_120

.LBB0_131:
	s_lshl_b32 s34, s3, 1
	s_lshl_b32 s35, s1, 1
	v_add_u32_e32 v40, s34, v22
	v_add_u32_e32 v38, s35, v17
	v_ashrrev_i32_e32 v41, 31, v40
	v_ashrrev_i32_e32 v39, 31, v38
	v_lshlrev_b64 v[40:41], 8, v[40:41]
	v_lshlrev_b64 v[38:39], 8, v[38:39]
	v_lshl_add_u64 v[40:41], v[20:21], 0, v[40:41]
	v_lshl_add_u64 v[38:39], v[20:21], 0, v[38:39]
	global_load_dword v200, v[40:41], off
	global_load_dword v201, v[38:39], off
	v_add_u32_e32 v40, s34, v24
	v_add_u32_e32 v38, s35, v19
	v_ashrrev_i32_e32 v41, 31, v40
	v_ashrrev_i32_e32 v39, 31, v38
	v_lshlrev_b64 v[40:41], 8, v[40:41]
	v_lshlrev_b64 v[38:39], 8, v[38:39]
	v_lshl_add_u64 v[40:41], v[20:21], 0, v[40:41]
	v_lshl_add_u64 v[38:39], v[20:21], 0, v[38:39]
	global_load_dword v202, v[40:41], off
	global_load_dword v203, v[38:39], off
	v_add_u32_e32 v40, s34, v26
	v_add_u32_e32 v38, s35, v23
	v_ashrrev_i32_e32 v41, 31, v40
	v_ashrrev_i32_e32 v39, 31, v38
	v_lshlrev_b64 v[40:41], 8, v[40:41]
	v_lshlrev_b64 v[38:39], 8, v[38:39]
	v_lshl_add_u64 v[40:41], v[20:21], 0, v[40:41]
	v_lshl_add_u64 v[38:39], v[20:21], 0, v[38:39]
	global_load_dword v204, v[40:41], off
	global_load_dword v205, v[38:39], off
	v_add_u32_e32 v40, s34, v28
	v_add_u32_e32 v38, s35, v25
	v_ashrrev_i32_e32 v41, 31, v40
	v_ashrrev_i32_e32 v39, 31, v38
	v_lshlrev_b64 v[40:41], 8, v[40:41]
	v_lshlrev_b64 v[38:39], 8, v[38:39]
	v_lshl_add_u64 v[40:41], v[20:21], 0, v[40:41]
	v_lshl_add_u64 v[38:39], v[20:21], 0, v[38:39]
	global_load_dword v206, v[40:41], off
	global_load_dword v207, v[38:39], off
	v_add_u32_e32 v40, s34, v30
	v_add_u32_e32 v38, s35, v27
	v_ashrrev_i32_e32 v41, 31, v40
	v_ashrrev_i32_e32 v39, 31, v38
	v_lshlrev_b64 v[40:41], 8, v[40:41]
	v_lshlrev_b64 v[38:39], 8, v[38:39]
	v_lshl_add_u64 v[40:41], v[20:21], 0, v[40:41]
	v_lshl_add_u64 v[38:39], v[20:21], 0, v[38:39]
	global_load_dword v208, v[40:41], off
	global_load_dword v209, v[38:39], off
	v_add_u32_e32 v40, s34, v32
	v_add_u32_e32 v38, s35, v29
	v_ashrrev_i32_e32 v41, 31, v40
	v_ashrrev_i32_e32 v39, 31, v38
	v_lshlrev_b64 v[40:41], 8, v[40:41]
	v_lshlrev_b64 v[38:39], 8, v[38:39]
	v_lshl_add_u64 v[40:41], v[20:21], 0, v[40:41]
	v_lshl_add_u64 v[38:39], v[20:21], 0, v[38:39]
	global_load_dword v210, v[40:41], off
	global_load_dword v211, v[38:39], off
	v_add_u32_e32 v40, s34, v34
	v_add_u32_e32 v38, s35, v31
	v_ashrrev_i32_e32 v41, 31, v40
	v_ashrrev_i32_e32 v39, 31, v38
	v_lshlrev_b64 v[40:41], 8, v[40:41]
	v_lshlrev_b64 v[38:39], 8, v[38:39]
	v_lshl_add_u64 v[40:41], v[20:21], 0, v[40:41]
	v_lshl_add_u64 v[38:39], v[20:21], 0, v[38:39]
	global_load_dword v212, v[40:41], off
	global_load_dword v213, v[38:39], off
	v_add_u32_e32 v40, s34, v36
	v_add_u32_e32 v38, s35, v33
	v_ashrrev_i32_e32 v41, 31, v40
	v_ashrrev_i32_e32 v39, 31, v38
	v_lshlrev_b64 v[40:41], 8, v[40:41]
	v_lshlrev_b64 v[38:39], 8, v[38:39]
	v_lshl_add_u64 v[40:41], v[20:21], 0, v[40:41]
	v_lshl_add_u64 v[38:39], v[20:21], 0, v[38:39]
	global_load_dword v214, v[40:41], off
	global_load_dword v215, v[38:39], off
	v_add_u32_e32 v42, s35, v1
	v_add_u32_e32 v43, s34, v0
	v_mad_u64_u32 v[38:39], s[38:39], v43, s59, v[2:3]
	v_mad_u64_u32 v[40:41], s[38:39], v42, s59, v[2:3]
	v_add_u32_e32 v42, s35, v3
	v_add_u32_e32 v43, s34, v4
	s_add_i32 s3, s3, 16
	s_add_i32 s1, s1, 16
	s_add_i32 s33, s33, -16
	s_cmp_lg_u32 s33, 0
	s_waitcnt vmcnt(14)
	ds_write_b32 v38, v200
	ds_write_b32 v40, v201
	v_mad_u64_u32 v[38:39], s[38:39], v43, s59, v[2:3]
	v_mad_u64_u32 v[40:41], s[38:39], v42, s59, v[2:3]
	v_add_u32_e32 v42, s35, v5
	v_add_u32_e32 v43, s34, v6
	s_waitcnt vmcnt(12)
	ds_write_b32 v38, v202
	ds_write_b32 v40, v203
	v_mad_u64_u32 v[38:39], s[38:39], v43, s59, v[2:3]
	v_mad_u64_u32 v[40:41], s[38:39], v42, s59, v[2:3]
	v_add_u32_e32 v42, s35, v7
	v_add_u32_e32 v43, s34, v8
	s_waitcnt vmcnt(10)
	ds_write_b32 v38, v204
	ds_write_b32 v40, v205
	v_mad_u64_u32 v[38:39], s[38:39], v43, s59, v[2:3]
	v_mad_u64_u32 v[40:41], s[38:39], v42, s59, v[2:3]
	v_add_u32_e32 v42, s35, v9
	v_add_u32_e32 v43, s34, v10
	s_waitcnt vmcnt(8)
	ds_write_b32 v38, v206
	ds_write_b32 v40, v207
	v_mad_u64_u32 v[38:39], s[38:39], v43, s59, v[2:3]
	v_mad_u64_u32 v[40:41], s[38:39], v42, s59, v[2:3]
	v_add_u32_e32 v42, s35, v11
	v_add_u32_e32 v43, s34, v12
	s_waitcnt vmcnt(6)
	ds_write_b32 v38, v208
	ds_write_b32 v40, v209
	v_mad_u64_u32 v[38:39], s[38:39], v43, s59, v[2:3]
	v_mad_u64_u32 v[40:41], s[38:39], v42, s59, v[2:3]
	v_add_u32_e32 v42, s35, v13
	v_add_u32_e32 v43, s34, v14
	s_waitcnt vmcnt(4)
	ds_write_b32 v38, v210
	ds_write_b32 v40, v211
	v_mad_u64_u32 v[38:39], s[38:39], v43, s59, v[2:3]
	v_mad_u64_u32 v[40:41], s[38:39], v42, s59, v[2:3]
	v_add_u32_e32 v43, s34, v16
	v_add_u32_e32 v42, s35, v15
	s_waitcnt vmcnt(2)
	ds_write_b32 v38, v212
	ds_write_b32 v40, v213
	v_mad_u64_u32 v[38:39], s[34:35], v43, s59, v[2:3]
	v_mad_u64_u32 v[40:41], s[34:35], v42, s59, v[2:3]
	s_waitcnt vmcnt(0)
	ds_write_b32 v38, v214
	ds_write_b32 v40, v215
	s_cbranch_scc1 .LBB0_131
	s_lshl_b64 s[4:5], s[4:5], 1
	v_add_u32_e32 v24, s2, v35
	s_add_u32 s2, s30, s4
	s_addc_u32 s3, s31, s5
	s_ashr_i32 s1, s0, 31
	s_lshl_b64 s[0:1], s[0:1], 1
	s_waitcnt lgkmcnt(0)
	s_add_u32 s0, s2, s0
	ds_read2_b32 v[20:21], v37 offset1:33
	v_mov_b32_e32 v19, v149
	v_ashrrev_i32_e32 v25, 31, v24
	s_addc_u32 s1, s3, s1
	s_waitcnt lgkmcnt(0)
	v_cvt_pk_bf16_f32 v20, v20, v21
	ds_read2_b32 v[22:23], v37 offset0:66 offset1:99
	v_lshlrev_b64 v[28:29], 9, v[24:25]
	v_lshl_add_u64 v[30:31], s[0:1], 0, v[18:19]
	s_waitcnt lgkmcnt(0)
	v_cvt_pk_bf16_f32 v21, v22, v23
	ds_read2_b32 v[22:23], v37 offset0:132 offset1:165
	v_lshl_add_u64 v[28:29], v[30:31], 0, v[28:29]
	s_waitcnt lgkmcnt(0)
	v_cvt_pk_bf16_f32 v22, v22, v23
	ds_read2_b32 v[26:27], v37 offset0:198 offset1:231
	s_waitcnt lgkmcnt(0)
	v_cvt_pk_bf16_f32 v23, v26, v27
	global_store_dwordx4 v[28:29], v[20:23], off
	v_add_u32_e32 v28, 8, v24
	v_ashrrev_i32_e32 v29, 31, v28
	ds_read2_b32 v[26:27], v37 offset0:8 offset1:41
	s_waitcnt lgkmcnt(0)
	v_cvt_pk_bf16_f32 v20, v26, v27
	ds_read2_b32 v[22:23], v37 offset0:74 offset1:107
	v_lshlrev_b64 v[28:29], 9, v[28:29]
	s_waitcnt lgkmcnt(0)
	v_cvt_pk_bf16_f32 v21, v22, v23
	ds_read2_b32 v[22:23], v37 offset0:140 offset1:173
	v_lshl_add_u64 v[28:29], v[30:31], 0, v[28:29]
	s_waitcnt lgkmcnt(0)
	v_cvt_pk_bf16_f32 v22, v22, v23
	ds_read2_b32 v[26:27], v37 offset0:206 offset1:239
	s_waitcnt lgkmcnt(0)
	v_cvt_pk_bf16_f32 v23, v26, v27
	global_store_dwordx4 v[28:29], v[20:23], off
	v_add_u32_e32 v28, 16, v24
	ds_read2_b32 v[26:27], v37 offset0:16 offset1:49
	s_waitcnt lgkmcnt(0)
	v_cvt_pk_bf16_f32 v20, v26, v27
	ds_read2_b32 v[22:23], v37 offset0:82 offset1:115
	v_ashrrev_i32_e32 v29, 31, v28
	s_waitcnt lgkmcnt(0)
	v_cvt_pk_bf16_f32 v21, v22, v23
	ds_read2_b32 v[22:23], v37 offset0:148 offset1:181
	v_lshlrev_b64 v[28:29], 9, v[28:29]
	v_add_u32_e32 v24, 24, v24
	s_waitcnt lgkmcnt(0)
	v_cvt_pk_bf16_f32 v22, v22, v23
	ds_read2_b32 v[26:27], v37 offset0:214 offset1:247
	s_waitcnt lgkmcnt(0)
	v_cvt_pk_bf16_f32 v23, v26, v27
	v_lshl_add_u64 v[28:29], v[30:31], 0, v[28:29]
	v_ashrrev_i32_e32 v25, 31, v24
	ds_read2_b32 v[26:27], v37 offset0:24 offset1:57
	global_store_dwordx4 v[28:29], v[20:23], off
	v_lshlrev_b64 v[24:25], 9, v[24:25]
	v_lshl_add_u64 v[24:25], v[30:31], 0, v[24:25]
	s_waitcnt lgkmcnt(0)
	v_cvt_pk_bf16_f32 v20, v26, v27
	ds_read2_b32 v[22:23], v37 offset0:90 offset1:123
	s_waitcnt lgkmcnt(0)
	v_cvt_pk_bf16_f32 v21, v22, v23
	ds_read2_b32 v[22:23], v37 offset0:156 offset1:189
	s_waitcnt lgkmcnt(0)
	v_cvt_pk_bf16_f32 v22, v22, v23
	ds_read2_b32 v[26:27], v37 offset0:222 offset1:255
	s_waitcnt lgkmcnt(0)
	v_cvt_pk_bf16_f32 v23, v26, v27
	global_store_dwordx4 v[24:25], v[20:23], off
	s_waitcnt lgkmcnt(0)
	s_add_i32 s27, s27, s11
	s_cmpk_lt_i32 s27, 0x80
	s_cbranch_scc1 .LBB0_130
	v_readlane_b32 s30, v255, 13
	v_readlane_b32 s34, v255, 15
	v_readlane_b32 s38, v255, 17
	v_readlane_b32 s31, v255, 14
	v_readlane_b32 s35, v255, 16
	v_readlane_b32 s39, v255, 18
	s_branch .LBB0_127

.LBB0_141:
	s_lshl_b32 s30, s27, 1
	s_lshl_b32 s31, s17, 1
	v_add_u32_e32 v60, s30, v32
	v_add_u32_e32 v48, s31, v1
	v_ashrrev_i32_e32 v61, 31, v60
	v_ashrrev_i32_e32 v49, 31, v48
	v_lshlrev_b64 v[60:61], 12, v[60:61]
	v_lshlrev_b64 v[48:49], 12, v[48:49]
	v_lshl_add_u64 v[60:61], v[30:31], 0, v[60:61]
	v_lshl_add_u64 v[48:49], v[30:31], 0, v[48:49]
	global_load_dword v200, v[60:61], off
	global_load_dword v201, v[48:49], off
	v_add_u32_e32 v60, s30, v34
	v_add_u32_e32 v48, s31, v3
	v_ashrrev_i32_e32 v61, 31, v60
	v_ashrrev_i32_e32 v49, 31, v48
	v_lshlrev_b64 v[60:61], 12, v[60:61]
	v_lshlrev_b64 v[48:49], 12, v[48:49]
	v_lshl_add_u64 v[60:61], v[30:31], 0, v[60:61]
	v_lshl_add_u64 v[48:49], v[30:31], 0, v[48:49]
	global_load_dword v202, v[60:61], off
	global_load_dword v203, v[48:49], off
	v_add_u32_e32 v60, s30, v36
	v_add_u32_e32 v48, s31, v21
	v_ashrrev_i32_e32 v61, 31, v60
	v_ashrrev_i32_e32 v49, 31, v48
	v_lshlrev_b64 v[60:61], 12, v[60:61]
	v_lshlrev_b64 v[48:49], 12, v[48:49]
	v_lshl_add_u64 v[60:61], v[30:31], 0, v[60:61]
	v_lshl_add_u64 v[48:49], v[30:31], 0, v[48:49]
	global_load_dword v204, v[60:61], off
	global_load_dword v205, v[48:49], off
	v_add_u32_e32 v60, s30, v38
	v_add_u32_e32 v48, s31, v33
	v_ashrrev_i32_e32 v61, 31, v60
	v_ashrrev_i32_e32 v49, 31, v48
	v_lshlrev_b64 v[60:61], 12, v[60:61]
	v_lshlrev_b64 v[48:49], 12, v[48:49]
	v_lshl_add_u64 v[60:61], v[30:31], 0, v[60:61]
	v_lshl_add_u64 v[48:49], v[30:31], 0, v[48:49]
	global_load_dword v206, v[60:61], off
	global_load_dword v207, v[48:49], off
	v_add_u32_e32 v60, s30, v40
	v_add_u32_e32 v48, s31, v35
	v_ashrrev_i32_e32 v61, 31, v60
	v_ashrrev_i32_e32 v49, 31, v48
	v_lshlrev_b64 v[60:61], 12, v[60:61]
	v_lshlrev_b64 v[48:49], 12, v[48:49]
	v_lshl_add_u64 v[60:61], v[30:31], 0, v[60:61]
	v_lshl_add_u64 v[48:49], v[30:31], 0, v[48:49]
	global_load_dword v208, v[60:61], off
	global_load_dword v209, v[48:49], off
	v_add_u32_e32 v60, s30, v42
	v_add_u32_e32 v48, s31, v37
	v_ashrrev_i32_e32 v61, 31, v60
	v_ashrrev_i32_e32 v49, 31, v48
	v_lshlrev_b64 v[60:61], 12, v[60:61]
	v_lshlrev_b64 v[48:49], 12, v[48:49]
	v_lshl_add_u64 v[60:61], v[30:31], 0, v[60:61]
	v_lshl_add_u64 v[48:49], v[30:31], 0, v[48:49]
	global_load_dword v210, v[60:61], off
	global_load_dword v211, v[48:49], off
	v_add_u32_e32 v60, s30, v44
	v_add_u32_e32 v48, s31, v39
	v_ashrrev_i32_e32 v61, 31, v60
	v_ashrrev_i32_e32 v49, 31, v48
	v_lshlrev_b64 v[60:61], 12, v[60:61]
	v_lshlrev_b64 v[48:49], 12, v[48:49]
	v_lshl_add_u64 v[60:61], v[30:31], 0, v[60:61]
	v_lshl_add_u64 v[48:49], v[30:31], 0, v[48:49]
	global_load_dword v212, v[60:61], off
	global_load_dword v213, v[48:49], off
	v_add_u32_e32 v60, s30, v46
	v_add_u32_e32 v48, s31, v41
	v_ashrrev_i32_e32 v61, 31, v60
	v_ashrrev_i32_e32 v49, 31, v48
	v_lshlrev_b64 v[60:61], 12, v[60:61]
	v_lshlrev_b64 v[48:49], 12, v[48:49]
	v_lshl_add_u64 v[60:61], v[30:31], 0, v[60:61]
	v_lshl_add_u64 v[48:49], v[30:31], 0, v[48:49]
	global_load_dword v214, v[60:61], off
	global_load_dword v215, v[48:49], off
	v_add_u32_e32 v43, s31, v5
	v_add_u32_e32 v45, s30, v4
	v_mad_u64_u32 v[48:49], s[34:35], v45, s59, v[6:7]
	v_mad_u64_u32 v[60:61], s[34:35], v43, s59, v[6:7]
	v_add_u32_e32 v43, s31, v7
	v_add_u32_e32 v45, s30, v8
	s_add_i32 s27, s27, 16
	s_add_i32 s17, s17, 16
	s_add_i32 s29, s29, -16
	s_cmp_lg_u32 s29, 0
	s_waitcnt vmcnt(14)
	ds_write_b32 v48, v200
	ds_write_b32 v60, v201
	v_mad_u64_u32 v[48:49], s[34:35], v45, s59, v[6:7]
	v_mad_u64_u32 v[60:61], s[34:35], v43, s59, v[6:7]
	v_add_u32_e32 v43, s31, v9
	v_add_u32_e32 v45, s30, v10
	s_waitcnt vmcnt(12)
	ds_write_b32 v48, v202
	ds_write_b32 v60, v203
	v_mad_u64_u32 v[48:49], s[34:35], v45, s59, v[6:7]
	v_mad_u64_u32 v[60:61], s[34:35], v43, s59, v[6:7]
	v_add_u32_e32 v43, s31, v11
	v_add_u32_e32 v45, s30, v12
	s_waitcnt vmcnt(10)
	ds_write_b32 v48, v204
	ds_write_b32 v60, v205
	v_mad_u64_u32 v[48:49], s[34:35], v45, s59, v[6:7]
	v_mad_u64_u32 v[60:61], s[34:35], v43, s59, v[6:7]
	v_add_u32_e32 v43, s31, v13
	v_add_u32_e32 v45, s30, v14
	s_waitcnt vmcnt(8)
	ds_write_b32 v48, v206
	ds_write_b32 v60, v207
	v_mad_u64_u32 v[48:49], s[34:35], v45, s59, v[6:7]
	v_mad_u64_u32 v[60:61], s[34:35], v43, s59, v[6:7]
	v_add_u32_e32 v43, s31, v15
	v_add_u32_e32 v45, s30, v16
	s_waitcnt vmcnt(6)
	ds_write_b32 v48, v208
	ds_write_b32 v60, v209
	v_mad_u64_u32 v[48:49], s[34:35], v45, s59, v[6:7]
	v_mad_u64_u32 v[60:61], s[34:35], v43, s59, v[6:7]
	v_add_u32_e32 v43, s31, v17
	v_add_u32_e32 v45, s30, v18
	s_waitcnt vmcnt(4)
	ds_write_b32 v48, v210
	ds_write_b32 v60, v211
	v_mad_u64_u32 v[48:49], s[34:35], v45, s59, v[6:7]
	v_mad_u64_u32 v[60:61], s[34:35], v43, s59, v[6:7]
	v_add_u32_e32 v45, s30, v20
	v_add_u32_e32 v43, s31, v19
	s_waitcnt vmcnt(2)
	ds_write_b32 v48, v212
	ds_write_b32 v60, v213
	v_mad_u64_u32 v[48:49], s[30:31], v45, s59, v[6:7]
	v_mad_u64_u32 v[60:61], s[30:31], v43, s59, v[6:7]
	s_waitcnt vmcnt(0)
	ds_write_b32 v48, v214
	ds_write_b32 v60, v215
	s_cbranch_scc1 .LBB0_141
	s_waitcnt lgkmcnt(0)
	ds_read2_b32 v[32:33], v51 offset1:33
	s_waitcnt lgkmcnt(0)
	v_cvt_pk_bf16_f32 v32, v32, v33
	ds_read2_b32 v[34:35], v51 offset0:66 offset1:99
	s_waitcnt lgkmcnt(0)
	v_cvt_pk_bf16_f32 v33, v34, v35
	ds_read2_b32 v[34:35], v51 offset0:132 offset1:165
	s_waitcnt lgkmcnt(0)
	v_cvt_pk_bf16_f32 v34, v34, v35
	ds_read2_b32 v[36:37], v51 offset0:198 offset1:231
	s_waitcnt lgkmcnt(0)
	v_cvt_pk_bf16_f32 v35, v36, v37
	v_add_u32_e32 v36, s26, v50
	s_ashr_i32 s29, s28, 31
	v_ashrrev_i32_e32 v37, 31, v36
	v_lshl_add_u64 v[30:31], s[28:29], 1, v[28:29]
	v_lshlrev_b64 v[36:37], 12, v[36:37]
	v_lshl_add_u64 v[36:37], v[30:31], 0, v[36:37]
	global_store_dwordx4 v[36:37], v[32:35], off
	ds_read2_b32 v[32:33], v51 offset0:8 offset1:41
	s_add_i32 s16, s16, s48
	s_waitcnt lgkmcnt(0)
	v_cvt_pk_bf16_f32 v32, v32, v33
	ds_read2_b32 v[34:35], v51 offset0:74 offset1:107
	s_waitcnt lgkmcnt(0)
	v_cvt_pk_bf16_f32 v33, v34, v35
	ds_read2_b32 v[34:35], v51 offset0:140 offset1:173
	s_waitcnt lgkmcnt(0)
	v_cvt_pk_bf16_f32 v34, v34, v35
	ds_read2_b32 v[36:37], v51 offset0:206 offset1:239
	s_waitcnt lgkmcnt(0)
	v_cvt_pk_bf16_f32 v35, v36, v37
	v_add_u32_e32 v36, s26, v52
	v_ashrrev_i32_e32 v37, 31, v36
	v_lshlrev_b64 v[36:37], 12, v[36:37]
	v_lshl_add_u64 v[36:37], v[30:31], 0, v[36:37]
	global_store_dwordx4 v[36:37], v[32:35], off
	ds_read2_b32 v[32:33], v51 offset0:16 offset1:49
	s_cmpk_lt_i32 s16, 0x200
	s_waitcnt lgkmcnt(0)
	v_cvt_pk_bf16_f32 v32, v32, v33
	ds_read2_b32 v[34:35], v51 offset0:82 offset1:115
	s_waitcnt lgkmcnt(0)
	v_cvt_pk_bf16_f32 v33, v34, v35
	ds_read2_b32 v[34:35], v51 offset0:148 offset1:181
	s_waitcnt lgkmcnt(0)
	v_cvt_pk_bf16_f32 v34, v34, v35
	ds_read2_b32 v[36:37], v51 offset0:214 offset1:247
	s_waitcnt lgkmcnt(0)
	v_cvt_pk_bf16_f32 v35, v36, v37
	v_add_u32_e32 v36, s26, v53
	v_ashrrev_i32_e32 v37, 31, v36
	v_lshlrev_b64 v[36:37], 12, v[36:37]
	v_lshl_add_u64 v[36:37], v[30:31], 0, v[36:37]
	global_store_dwordx4 v[36:37], v[32:35], off
	ds_read2_b32 v[32:33], v51 offset0:24 offset1:57
	s_waitcnt lgkmcnt(0)
	v_cvt_pk_bf16_f32 v32, v32, v33
	ds_read2_b32 v[34:35], v51 offset0:90 offset1:123
	s_waitcnt lgkmcnt(0)
	v_cvt_pk_bf16_f32 v33, v34, v35
	ds_read2_b32 v[34:35], v51 offset0:156 offset1:189
	s_waitcnt lgkmcnt(0)
	v_cvt_pk_bf16_f32 v34, v34, v35
	ds_read2_b32 v[36:37], v51 offset0:222 offset1:255
	s_waitcnt lgkmcnt(0)
	v_cvt_pk_bf16_f32 v35, v36, v37
	v_add_u32_e32 v36, s26, v54
	v_ashrrev_i32_e32 v37, 31, v36
	v_lshlrev_b64 v[36:37], 12, v[36:37]
	v_lshl_add_u64 v[30:31], v[30:31], 0, v[36:37]
	global_store_dwordx4 v[30:31], v[32:35], off
	s_waitcnt lgkmcnt(0)
	s_cbranch_scc1 .LBB0_140

.LBB0_169:
	s_lshl_b32 s30, s25, 1
	s_lshl_b32 s31, s21, 1
	v_add_u32_e32 v56, s30, v32
	v_add_u32_e32 v48, s31, v1
	v_ashrrev_i32_e32 v57, 31, v56
	v_ashrrev_i32_e32 v49, 31, v48
	v_lshlrev_b64 v[56:57], 8, v[56:57]
	v_lshlrev_b64 v[48:49], 8, v[48:49]
	v_lshl_add_u64 v[56:57], v[30:31], 0, v[56:57]
	v_lshl_add_u64 v[48:49], v[30:31], 0, v[48:49]
	global_load_dword v200, v[56:57], off
	global_load_dword v201, v[48:49], off
	v_add_u32_e32 v56, s30, v34
	v_add_u32_e32 v48, s31, v21
	v_ashrrev_i32_e32 v57, 31, v56
	v_ashrrev_i32_e32 v49, 31, v48
	v_lshlrev_b64 v[56:57], 8, v[56:57]
	v_lshlrev_b64 v[48:49], 8, v[48:49]
	v_lshl_add_u64 v[56:57], v[30:31], 0, v[56:57]
	v_lshl_add_u64 v[48:49], v[30:31], 0, v[48:49]
	global_load_dword v202, v[56:57], off
	global_load_dword v203, v[48:49], off
	v_add_u32_e32 v56, s30, v36
	v_add_u32_e32 v48, s31, v23
	v_ashrrev_i32_e32 v57, 31, v56
	v_ashrrev_i32_e32 v49, 31, v48
	v_lshlrev_b64 v[56:57], 8, v[56:57]
	v_lshlrev_b64 v[48:49], 8, v[48:49]
	v_lshl_add_u64 v[56:57], v[30:31], 0, v[56:57]
	v_lshl_add_u64 v[48:49], v[30:31], 0, v[48:49]
	global_load_dword v204, v[56:57], off
	global_load_dword v205, v[48:49], off
	v_add_u32_e32 v56, s30, v38
	v_add_u32_e32 v48, s31, v33
	v_ashrrev_i32_e32 v57, 31, v56
	v_ashrrev_i32_e32 v49, 31, v48
	v_lshlrev_b64 v[56:57], 8, v[56:57]
	v_lshlrev_b64 v[48:49], 8, v[48:49]
	v_lshl_add_u64 v[56:57], v[30:31], 0, v[56:57]
	v_lshl_add_u64 v[48:49], v[30:31], 0, v[48:49]
	global_load_dword v206, v[56:57], off
	global_load_dword v207, v[48:49], off
	v_add_u32_e32 v56, s30, v40
	v_add_u32_e32 v48, s31, v35
	v_ashrrev_i32_e32 v57, 31, v56
	v_ashrrev_i32_e32 v49, 31, v48
	v_lshlrev_b64 v[56:57], 8, v[56:57]
	v_lshlrev_b64 v[48:49], 8, v[48:49]
	v_lshl_add_u64 v[56:57], v[30:31], 0, v[56:57]
	v_lshl_add_u64 v[48:49], v[30:31], 0, v[48:49]
	global_load_dword v208, v[56:57], off
	global_load_dword v209, v[48:49], off
	v_add_u32_e32 v56, s30, v42
	v_add_u32_e32 v48, s31, v37
	v_ashrrev_i32_e32 v57, 31, v56
	v_ashrrev_i32_e32 v49, 31, v48
	v_lshlrev_b64 v[56:57], 8, v[56:57]
	v_lshlrev_b64 v[48:49], 8, v[48:49]
	v_lshl_add_u64 v[56:57], v[30:31], 0, v[56:57]
	v_lshl_add_u64 v[48:49], v[30:31], 0, v[48:49]
	global_load_dword v210, v[56:57], off
	global_load_dword v211, v[48:49], off
	v_add_u32_e32 v56, s30, v44
	v_add_u32_e32 v48, s31, v39
	v_ashrrev_i32_e32 v57, 31, v56
	v_ashrrev_i32_e32 v49, 31, v48
	v_lshlrev_b64 v[56:57], 8, v[56:57]
	v_lshlrev_b64 v[48:49], 8, v[48:49]
	v_lshl_add_u64 v[56:57], v[30:31], 0, v[56:57]
	v_lshl_add_u64 v[48:49], v[30:31], 0, v[48:49]
	global_load_dword v212, v[56:57], off
	global_load_dword v213, v[48:49], off
	v_add_u32_e32 v56, s30, v46
	v_add_u32_e32 v48, s31, v41
	v_ashrrev_i32_e32 v57, 31, v56
	v_ashrrev_i32_e32 v49, 31, v48
	v_lshlrev_b64 v[56:57], 8, v[56:57]
	v_lshlrev_b64 v[48:49], 8, v[48:49]
	v_lshl_add_u64 v[56:57], v[30:31], 0, v[56:57]
	v_lshl_add_u64 v[48:49], v[30:31], 0, v[48:49]
	global_load_dword v214, v[56:57], off
	global_load_dword v215, v[48:49], off
	v_add_u32_e32 v43, s31, v5
	v_add_u32_e32 v45, s30, v4
	v_mad_u64_u32 v[48:49], s[34:35], v45, s59, v[6:7]
	v_mad_u64_u32 v[56:57], s[34:35], v43, s59, v[6:7]
	v_add_u32_e32 v43, s31, v7
	v_add_u32_e32 v45, s30, v8
	s_add_i32 s25, s25, 16
	s_add_i32 s21, s21, 16
	s_add_i32 s27, s27, -16
	s_cmp_lg_u32 s27, 0
	s_waitcnt vmcnt(14)
	ds_write_b32 v48, v200
	ds_write_b32 v56, v201
	v_mad_u64_u32 v[48:49], s[34:35], v45, s59, v[6:7]
	v_mad_u64_u32 v[56:57], s[34:35], v43, s59, v[6:7]
	v_add_u32_e32 v43, s31, v9
	v_add_u32_e32 v45, s30, v10
	s_waitcnt vmcnt(12)
	ds_write_b32 v48, v202
	ds_write_b32 v56, v203
	v_mad_u64_u32 v[48:49], s[34:35], v45, s59, v[6:7]
	v_mad_u64_u32 v[56:57], s[34:35], v43, s59, v[6:7]
	v_add_u32_e32 v43, s31, v11
	v_add_u32_e32 v45, s30, v12
	s_waitcnt vmcnt(10)
	ds_write_b32 v48, v204
	ds_write_b32 v56, v205
	v_mad_u64_u32 v[48:49], s[34:35], v45, s59, v[6:7]
	v_mad_u64_u32 v[56:57], s[34:35], v43, s59, v[6:7]
	v_add_u32_e32 v43, s31, v13
	v_add_u32_e32 v45, s30, v14
	s_waitcnt vmcnt(8)
	ds_write_b32 v48, v206
	ds_write_b32 v56, v207
	v_mad_u64_u32 v[48:49], s[34:35], v45, s59, v[6:7]
	v_mad_u64_u32 v[56:57], s[34:35], v43, s59, v[6:7]
	v_add_u32_e32 v43, s31, v15
	v_add_u32_e32 v45, s30, v16
	s_waitcnt vmcnt(6)
	ds_write_b32 v48, v208
	ds_write_b32 v56, v209
	v_mad_u64_u32 v[48:49], s[34:35], v45, s59, v[6:7]
	v_mad_u64_u32 v[56:57], s[34:35], v43, s59, v[6:7]
	v_add_u32_e32 v43, s31, v17
	v_add_u32_e32 v45, s30, v18
	s_waitcnt vmcnt(4)
	ds_write_b32 v48, v210
	ds_write_b32 v56, v211
	v_mad_u64_u32 v[48:49], s[34:35], v45, s59, v[6:7]
	v_mad_u64_u32 v[56:57], s[34:35], v43, s59, v[6:7]
	v_add_u32_e32 v45, s30, v20
	v_add_u32_e32 v43, s31, v19
	s_waitcnt vmcnt(2)
	ds_write_b32 v48, v212
	ds_write_b32 v56, v213
	v_mad_u64_u32 v[48:49], s[30:31], v45, s59, v[6:7]
	v_mad_u64_u32 v[56:57], s[30:31], v43, s59, v[6:7]
	s_waitcnt vmcnt(0)
	ds_write_b32 v48, v214
	ds_write_b32 v56, v215
	s_cbranch_scc1 .LBB0_169
	s_waitcnt lgkmcnt(0)
	ds_read2_b32 v[32:33], v51 offset1:33
	s_waitcnt lgkmcnt(0)
	v_cvt_pk_bf16_f32 v32, v32, v33
	ds_read2_b32 v[34:35], v51 offset0:66 offset1:99
	s_waitcnt lgkmcnt(0)
	v_cvt_pk_bf16_f32 v33, v34, v35
	ds_read2_b32 v[34:35], v51 offset0:132 offset1:165
	s_waitcnt lgkmcnt(0)
	v_cvt_pk_bf16_f32 v34, v34, v35
	ds_read2_b32 v[36:37], v51 offset0:198 offset1:231
	s_waitcnt lgkmcnt(0)
	v_cvt_pk_bf16_f32 v35, v36, v37
	v_add_u32_e32 v36, s24, v50
	s_ashr_i32 s27, s26, 31
	v_ashrrev_i32_e32 v37, 31, v36
	v_lshl_add_u64 v[30:31], s[26:27], 1, v[28:29]
	v_lshlrev_b64 v[36:37], 12, v[36:37]
	v_lshl_add_u64 v[36:37], v[30:31], 0, v[36:37]
	global_store_dwordx4 v[36:37], v[32:35], off
	ds_read2_b32 v[32:33], v51 offset0:8 offset1:41
	s_add_i32 s20, s20, s48
	s_waitcnt lgkmcnt(0)
	v_cvt_pk_bf16_f32 v32, v32, v33
	ds_read2_b32 v[34:35], v51 offset0:74 offset1:107
	s_waitcnt lgkmcnt(0)
	v_cvt_pk_bf16_f32 v33, v34, v35
	ds_read2_b32 v[34:35], v51 offset0:140 offset1:173
	s_waitcnt lgkmcnt(0)
	v_cvt_pk_bf16_f32 v34, v34, v35
	ds_read2_b32 v[36:37], v51 offset0:206 offset1:239
	s_waitcnt lgkmcnt(0)
	v_cvt_pk_bf16_f32 v35, v36, v37
	v_add_u32_e32 v36, s24, v52
	v_ashrrev_i32_e32 v37, 31, v36
	v_lshlrev_b64 v[36:37], 12, v[36:37]
	v_lshl_add_u64 v[36:37], v[30:31], 0, v[36:37]
	global_store_dwordx4 v[36:37], v[32:35], off
	ds_read2_b32 v[32:33], v51 offset0:16 offset1:49
	s_cmp_lt_i32 s20, 32
	s_waitcnt lgkmcnt(0)
	v_cvt_pk_bf16_f32 v32, v32, v33
	ds_read2_b32 v[34:35], v51 offset0:82 offset1:115
	s_waitcnt lgkmcnt(0)
	v_cvt_pk_bf16_f32 v33, v34, v35
	ds_read2_b32 v[34:35], v51 offset0:148 offset1:181
	s_waitcnt lgkmcnt(0)
	v_cvt_pk_bf16_f32 v34, v34, v35
	ds_read2_b32 v[36:37], v51 offset0:214 offset1:247
	s_waitcnt lgkmcnt(0)
	v_cvt_pk_bf16_f32 v35, v36, v37
	v_add_u32_e32 v36, s24, v53
	v_ashrrev_i32_e32 v37, 31, v36
	v_lshlrev_b64 v[36:37], 12, v[36:37]
	v_lshl_add_u64 v[36:37], v[30:31], 0, v[36:37]
	global_store_dwordx4 v[36:37], v[32:35], off
	ds_read2_b32 v[32:33], v51 offset0:24 offset1:57
	s_waitcnt lgkmcnt(0)
	v_cvt_pk_bf16_f32 v32, v32, v33
	ds_read2_b32 v[34:35], v51 offset0:90 offset1:123
	s_waitcnt lgkmcnt(0)
	v_cvt_pk_bf16_f32 v33, v34, v35
	ds_read2_b32 v[34:35], v51 offset0:156 offset1:189
	s_waitcnt lgkmcnt(0)
	v_cvt_pk_bf16_f32 v34, v34, v35
	ds_read2_b32 v[36:37], v51 offset0:222 offset1:255
	s_waitcnt lgkmcnt(0)
	v_cvt_pk_bf16_f32 v35, v36, v37
	v_add_u32_e32 v36, s24, v54
	v_ashrrev_i32_e32 v37, 31, v36
	v_lshlrev_b64 v[36:37], 12, v[36:37]
	v_lshl_add_u64 v[30:31], v[30:31], 0, v[36:37]
	global_store_dwordx4 v[30:31], v[32:35], off
	s_waitcnt lgkmcnt(0)
	s_cbranch_scc1 .LBB0_168

.LBB0_174:
	s_lshl_b32 s26, s21, 1
	s_lshl_b32 s27, s5, 1
	v_add_u32_e32 v56, s26, v32
	v_add_u32_e32 v48, s27, v1
	v_ashrrev_i32_e32 v57, 31, v56
	v_ashrrev_i32_e32 v49, 31, v48
	v_lshlrev_b64 v[60:61], 8, v[56:57]
	v_lshlrev_b64 v[58:59], 8, v[48:49]
	v_lshl_add_u64 v[60:61], v[30:31], 0, v[60:61]
	v_lshl_add_u64 v[56:57], v[56:57], 2, s[10:11]
	v_lshl_add_u64 v[58:59], v[30:31], 0, v[58:59]
	global_load_dword v202, v[60:61], off
	s_nop 0
	global_load_dword v203, v[58:59], off
	v_lshl_add_u64 v[48:49], v[48:49], 2, s[10:11]
	global_load_dword v200, v[56:57], off
	s_nop 0
	global_load_dword v201, v[48:49], off
	v_add_u32_e32 v56, s26, v34
	v_add_u32_e32 v48, s27, v21
	v_ashrrev_i32_e32 v57, 31, v56
	v_ashrrev_i32_e32 v49, 31, v48
	v_lshlrev_b64 v[60:61], 8, v[56:57]
	v_lshlrev_b64 v[58:59], 8, v[48:49]
	v_lshl_add_u64 v[60:61], v[30:31], 0, v[60:61]
	v_lshl_add_u64 v[56:57], v[56:57], 2, s[10:11]
	v_lshl_add_u64 v[58:59], v[30:31], 0, v[58:59]
	global_load_dword v206, v[60:61], off
	s_nop 0
	global_load_dword v207, v[58:59], off
	v_lshl_add_u64 v[48:49], v[48:49], 2, s[10:11]
	global_load_dword v204, v[56:57], off
	s_nop 0
	global_load_dword v205, v[48:49], off
	v_add_u32_e32 v56, s26, v36
	v_add_u32_e32 v48, s27, v23
	v_ashrrev_i32_e32 v57, 31, v56
	v_ashrrev_i32_e32 v49, 31, v48
	v_lshlrev_b64 v[60:61], 8, v[56:57]
	v_lshlrev_b64 v[58:59], 8, v[48:49]
	v_lshl_add_u64 v[60:61], v[30:31], 0, v[60:61]
	v_lshl_add_u64 v[56:57], v[56:57], 2, s[10:11]
	v_lshl_add_u64 v[58:59], v[30:31], 0, v[58:59]
	global_load_dword v210, v[60:61], off
	s_nop 0
	global_load_dword v211, v[58:59], off
	v_lshl_add_u64 v[48:49], v[48:49], 2, s[10:11]
	global_load_dword v208, v[56:57], off
	s_nop 0
	global_load_dword v209, v[48:49], off
	v_add_u32_e32 v56, s26, v38
	v_add_u32_e32 v48, s27, v33
	v_ashrrev_i32_e32 v57, 31, v56
	v_ashrrev_i32_e32 v49, 31, v48
	v_lshlrev_b64 v[60:61], 8, v[56:57]
	v_lshlrev_b64 v[58:59], 8, v[48:49]
	v_lshl_add_u64 v[60:61], v[30:31], 0, v[60:61]
	v_lshl_add_u64 v[56:57], v[56:57], 2, s[10:11]
	v_lshl_add_u64 v[58:59], v[30:31], 0, v[58:59]
	global_load_dword v214, v[60:61], off
	s_nop 0
	global_load_dword v215, v[58:59], off
	v_lshl_add_u64 v[48:49], v[48:49], 2, s[10:11]
	global_load_dword v212, v[56:57], off
	s_nop 0
	global_load_dword v213, v[48:49], off
	v_add_u32_e32 v56, s26, v40
	v_add_u32_e32 v48, s27, v35
	v_ashrrev_i32_e32 v57, 31, v56
	v_ashrrev_i32_e32 v49, 31, v48
	v_lshlrev_b64 v[60:61], 8, v[56:57]
	v_lshlrev_b64 v[58:59], 8, v[48:49]
	v_lshl_add_u64 v[60:61], v[30:31], 0, v[60:61]
	v_lshl_add_u64 v[56:57], v[56:57], 2, s[10:11]
	v_lshl_add_u64 v[58:59], v[30:31], 0, v[58:59]
	global_load_dword v218, v[60:61], off
	s_nop 0
	global_load_dword v219, v[58:59], off
	v_lshl_add_u64 v[48:49], v[48:49], 2, s[10:11]
	global_load_dword v216, v[56:57], off
	s_nop 0
	global_load_dword v217, v[48:49], off
	v_add_u32_e32 v56, s26, v42
	v_add_u32_e32 v48, s27, v37
	v_ashrrev_i32_e32 v57, 31, v56
	v_ashrrev_i32_e32 v49, 31, v48
	v_lshlrev_b64 v[60:61], 8, v[56:57]
	v_lshlrev_b64 v[58:59], 8, v[48:49]
	v_lshl_add_u64 v[60:61], v[30:31], 0, v[60:61]
	v_lshl_add_u64 v[56:57], v[56:57], 2, s[10:11]
	v_lshl_add_u64 v[58:59], v[30:31], 0, v[58:59]
	global_load_dword v222, v[60:61], off
	s_nop 0
	global_load_dword v223, v[58:59], off
	v_lshl_add_u64 v[48:49], v[48:49], 2, s[10:11]
	global_load_dword v220, v[56:57], off
	s_nop 0
	global_load_dword v221, v[48:49], off
	v_add_u32_e32 v56, s26, v44
	v_add_u32_e32 v48, s27, v39
	v_ashrrev_i32_e32 v57, 31, v56
	v_ashrrev_i32_e32 v49, 31, v48
	v_lshlrev_b64 v[60:61], 8, v[56:57]
	v_lshlrev_b64 v[58:59], 8, v[48:49]
	v_lshl_add_u64 v[60:61], v[30:31], 0, v[60:61]
	v_lshl_add_u64 v[56:57], v[56:57], 2, s[10:11]
	v_lshl_add_u64 v[58:59], v[30:31], 0, v[58:59]
	global_load_dword v226, v[60:61], off
	s_nop 0
	global_load_dword v227, v[58:59], off
	v_lshl_add_u64 v[48:49], v[48:49], 2, s[10:11]
	global_load_dword v224, v[56:57], off
	s_nop 0
	global_load_dword v225, v[48:49], off
	v_add_u32_e32 v56, s26, v46
	v_add_u32_e32 v48, s27, v41
	v_ashrrev_i32_e32 v57, 31, v56
	v_ashrrev_i32_e32 v49, 31, v48
	v_lshlrev_b64 v[60:61], 8, v[56:57]
	v_lshlrev_b64 v[58:59], 8, v[48:49]
	v_lshl_add_u64 v[60:61], v[30:31], 0, v[60:61]
	v_lshl_add_u64 v[56:57], v[56:57], 2, s[10:11]
	v_lshl_add_u64 v[58:59], v[30:31], 0, v[58:59]
	global_load_dword v230, v[60:61], off
	s_nop 0
	global_load_dword v231, v[58:59], off
	v_lshl_add_u64 v[48:49], v[48:49], 2, s[10:11]
	global_load_dword v228, v[56:57], off
	s_nop 0
	global_load_dword v229, v[48:49], off
	v_add_u32_e32 v45, s26, v4
	v_add_u32_e32 v43, s27, v5
	v_mad_u64_u32 v[58:59], s[30:31], v43, s59, v[6:7]
	v_add_u32_e32 v43, s27, v7
	s_add_i32 s21, s21, 16
	s_add_i32 s5, s5, 16
	s_add_i32 s25, s25, -16
	s_cmp_lg_u32 s25, 0
	s_waitcnt vmcnt(28)
	v_pk_mul_f32 v[48:49], v[202:203], v[200:201]
	v_mad_u64_u32 v[56:57], s[30:31], v45, s59, v[6:7]
	ds_write_b32 v56, v48
	ds_write_b32 v58, v49
	v_add_u32_e32 v45, s26, v8
	v_mad_u64_u32 v[58:59], s[30:31], v43, s59, v[6:7]
	v_add_u32_e32 v43, s27, v9
	s_waitcnt vmcnt(24)
	v_pk_mul_f32 v[48:49], v[206:207], v[204:205]
	v_mad_u64_u32 v[56:57], s[30:31], v45, s59, v[6:7]
	ds_write_b32 v56, v48
	ds_write_b32 v58, v49
	v_add_u32_e32 v45, s26, v10
	v_mad_u64_u32 v[58:59], s[30:31], v43, s59, v[6:7]
	v_add_u32_e32 v43, s27, v11
	s_waitcnt vmcnt(20)
	v_pk_mul_f32 v[48:49], v[210:211], v[208:209]
	v_mad_u64_u32 v[56:57], s[30:31], v45, s59, v[6:7]
	ds_write_b32 v56, v48
	ds_write_b32 v58, v49
	v_add_u32_e32 v45, s26, v12
	v_mad_u64_u32 v[58:59], s[30:31], v43, s59, v[6:7]
	v_add_u32_e32 v43, s27, v13
	s_waitcnt vmcnt(16)
	v_pk_mul_f32 v[48:49], v[214:215], v[212:213]
	v_mad_u64_u32 v[56:57], s[30:31], v45, s59, v[6:7]
	ds_write_b32 v56, v48
	ds_write_b32 v58, v49
	v_add_u32_e32 v45, s26, v14
	v_mad_u64_u32 v[58:59], s[30:31], v43, s59, v[6:7]
	v_add_u32_e32 v43, s27, v15
	s_waitcnt vmcnt(12)
	v_pk_mul_f32 v[48:49], v[218:219], v[216:217]
	v_mad_u64_u32 v[56:57], s[30:31], v45, s59, v[6:7]
	ds_write_b32 v56, v48
	ds_write_b32 v58, v49
	v_add_u32_e32 v45, s26, v16
	v_mad_u64_u32 v[58:59], s[30:31], v43, s59, v[6:7]
	v_add_u32_e32 v43, s27, v17
	s_waitcnt vmcnt(8)
	v_pk_mul_f32 v[48:49], v[222:223], v[220:221]
	v_mad_u64_u32 v[56:57], s[30:31], v45, s59, v[6:7]
	ds_write_b32 v56, v48
	ds_write_b32 v58, v49
	v_add_u32_e32 v45, s26, v18
	v_mad_u64_u32 v[58:59], s[30:31], v43, s59, v[6:7]
	v_add_u32_e32 v43, s27, v19
	s_waitcnt vmcnt(4)
	v_pk_mul_f32 v[48:49], v[226:227], v[224:225]
	v_mad_u64_u32 v[56:57], s[30:31], v45, s59, v[6:7]
	ds_write_b32 v56, v48
	ds_write_b32 v58, v49
	v_add_u32_e32 v45, s26, v20
	v_mad_u64_u32 v[58:59], s[26:27], v43, s59, v[6:7]
	s_waitcnt vmcnt(0)
	v_pk_mul_f32 v[48:49], v[230:231], v[228:229]
	v_mad_u64_u32 v[56:57], s[26:27], v45, s59, v[6:7]
	ds_write_b32 v56, v48
	ds_write_b32 v58, v49
	s_cbranch_scc1 .LBB0_174
	s_waitcnt lgkmcnt(0)
	ds_read2_b32 v[32:33], v51 offset1:33
	s_waitcnt lgkmcnt(0)
	v_cvt_pk_bf16_f32 v32, v32, v33
	ds_read2_b32 v[34:35], v51 offset0:66 offset1:99
	s_waitcnt lgkmcnt(0)
	v_cvt_pk_bf16_f32 v33, v34, v35
	ds_read2_b32 v[34:35], v51 offset0:132 offset1:165
	s_waitcnt lgkmcnt(0)
	v_cvt_pk_bf16_f32 v34, v34, v35
	ds_read2_b32 v[36:37], v51 offset0:198 offset1:231
	s_waitcnt lgkmcnt(0)
	v_cvt_pk_bf16_f32 v35, v36, v37
	v_add_u32_e32 v36, s4, v50
	s_ashr_i32 s25, s24, 31
	v_ashrrev_i32_e32 v37, 31, v36
	v_lshl_add_u64 v[30:31], s[24:25], 1, v[28:29]
	v_lshlrev_b64 v[36:37], 12, v[36:37]
	v_lshl_add_u64 v[36:37], v[30:31], 0, v[36:37]
	global_store_dwordx4 v[36:37], v[32:35], off
	ds_read2_b32 v[32:33], v51 offset0:8 offset1:41
	s_add_i32 s20, s20, s48
	s_waitcnt lgkmcnt(0)
	v_cvt_pk_bf16_f32 v32, v32, v33
	ds_read2_b32 v[34:35], v51 offset0:74 offset1:107
	s_waitcnt lgkmcnt(0)
	v_cvt_pk_bf16_f32 v33, v34, v35
	ds_read2_b32 v[34:35], v51 offset0:140 offset1:173
	s_waitcnt lgkmcnt(0)
	v_cvt_pk_bf16_f32 v34, v34, v35
	ds_read2_b32 v[36:37], v51 offset0:206 offset1:239
	s_waitcnt lgkmcnt(0)
	v_cvt_pk_bf16_f32 v35, v36, v37
	v_add_u32_e32 v36, s4, v52
	v_ashrrev_i32_e32 v37, 31, v36
	v_lshlrev_b64 v[36:37], 12, v[36:37]
	v_lshl_add_u64 v[36:37], v[30:31], 0, v[36:37]
	global_store_dwordx4 v[36:37], v[32:35], off
	ds_read2_b32 v[32:33], v51 offset0:16 offset1:49
	s_cmp_lt_i32 s20, 32
	s_waitcnt lgkmcnt(0)
	v_cvt_pk_bf16_f32 v32, v32, v33
	ds_read2_b32 v[34:35], v51 offset0:82 offset1:115
	s_waitcnt lgkmcnt(0)
	v_cvt_pk_bf16_f32 v33, v34, v35
	ds_read2_b32 v[34:35], v51 offset0:148 offset1:181
	s_waitcnt lgkmcnt(0)
	v_cvt_pk_bf16_f32 v34, v34, v35
	ds_read2_b32 v[36:37], v51 offset0:214 offset1:247
	s_waitcnt lgkmcnt(0)
	v_cvt_pk_bf16_f32 v35, v36, v37
	v_add_u32_e32 v36, s4, v53
	v_ashrrev_i32_e32 v37, 31, v36
	v_lshlrev_b64 v[36:37], 12, v[36:37]
	v_lshl_add_u64 v[36:37], v[30:31], 0, v[36:37]
	global_store_dwordx4 v[36:37], v[32:35], off
	ds_read2_b32 v[32:33], v51 offset0:24 offset1:57
	s_waitcnt lgkmcnt(0)
	v_cvt_pk_bf16_f32 v32, v32, v33
	ds_read2_b32 v[34:35], v51 offset0:90 offset1:123
	s_waitcnt lgkmcnt(0)
	v_cvt_pk_bf16_f32 v33, v34, v35
	ds_read2_b32 v[34:35], v51 offset0:156 offset1:189
	s_waitcnt lgkmcnt(0)
	v_cvt_pk_bf16_f32 v34, v34, v35
	ds_read2_b32 v[36:37], v51 offset0:222 offset1:255
	s_waitcnt lgkmcnt(0)
	v_cvt_pk_bf16_f32 v35, v36, v37
	v_add_u32_e32 v36, s4, v54
	v_ashrrev_i32_e32 v37, 31, v36
	v_lshlrev_b64 v[36:37], 12, v[36:37]
	v_lshl_add_u64 v[30:31], v[30:31], 0, v[36:37]
	global_store_dwordx4 v[30:31], v[32:35], off
	s_waitcnt lgkmcnt(0)
	s_cbranch_scc1 .LBB0_173

.LBB0_179:
	s_lshl_b32 s25, s20, 1
	s_lshl_b32 s27, s19, 1
	v_add_u32_e32 v56, s25, v32
	v_add_u32_e32 v48, s27, v1
	v_ashrrev_i32_e32 v57, 31, v56
	v_ashrrev_i32_e32 v49, 31, v48
	v_lshlrev_b64 v[56:57], 8, v[56:57]
	v_lshlrev_b64 v[48:49], 8, v[48:49]
	v_lshl_add_u64 v[56:57], v[30:31], 0, v[56:57]
	v_lshl_add_u64 v[48:49], v[30:31], 0, v[48:49]
	global_load_dword v200, v[56:57], off
	global_load_dword v201, v[48:49], off
	v_add_u32_e32 v56, s25, v34
	v_add_u32_e32 v48, s27, v21
	v_ashrrev_i32_e32 v57, 31, v56
	v_ashrrev_i32_e32 v49, 31, v48
	v_lshlrev_b64 v[56:57], 8, v[56:57]
	v_lshlrev_b64 v[48:49], 8, v[48:49]
	v_lshl_add_u64 v[56:57], v[30:31], 0, v[56:57]
	v_lshl_add_u64 v[48:49], v[30:31], 0, v[48:49]
	global_load_dword v202, v[56:57], off
	global_load_dword v203, v[48:49], off
	v_add_u32_e32 v56, s25, v36
	v_add_u32_e32 v48, s27, v23
	v_ashrrev_i32_e32 v57, 31, v56
	v_ashrrev_i32_e32 v49, 31, v48
	v_lshlrev_b64 v[56:57], 8, v[56:57]
	v_lshlrev_b64 v[48:49], 8, v[48:49]
	v_lshl_add_u64 v[56:57], v[30:31], 0, v[56:57]
	v_lshl_add_u64 v[48:49], v[30:31], 0, v[48:49]
	global_load_dword v204, v[56:57], off
	global_load_dword v205, v[48:49], off
	v_add_u32_e32 v56, s25, v38
	v_add_u32_e32 v48, s27, v33
	v_ashrrev_i32_e32 v57, 31, v56
	v_ashrrev_i32_e32 v49, 31, v48
	v_lshlrev_b64 v[56:57], 8, v[56:57]
	v_lshlrev_b64 v[48:49], 8, v[48:49]
	v_lshl_add_u64 v[56:57], v[30:31], 0, v[56:57]
	v_lshl_add_u64 v[48:49], v[30:31], 0, v[48:49]
	global_load_dword v206, v[56:57], off
	global_load_dword v207, v[48:49], off
	v_add_u32_e32 v56, s25, v40
	v_add_u32_e32 v48, s27, v35
	v_ashrrev_i32_e32 v57, 31, v56
	v_ashrrev_i32_e32 v49, 31, v48
	v_lshlrev_b64 v[56:57], 8, v[56:57]
	v_lshlrev_b64 v[48:49], 8, v[48:49]
	v_lshl_add_u64 v[56:57], v[30:31], 0, v[56:57]
	v_lshl_add_u64 v[48:49], v[30:31], 0, v[48:49]
	global_load_dword v208, v[56:57], off
	global_load_dword v209, v[48:49], off
	v_add_u32_e32 v56, s25, v42
	v_add_u32_e32 v48, s27, v37
	v_ashrrev_i32_e32 v57, 31, v56
	v_ashrrev_i32_e32 v49, 31, v48
	v_lshlrev_b64 v[56:57], 8, v[56:57]
	v_lshlrev_b64 v[48:49], 8, v[48:49]
	v_lshl_add_u64 v[56:57], v[30:31], 0, v[56:57]
	v_lshl_add_u64 v[48:49], v[30:31], 0, v[48:49]
	global_load_dword v210, v[56:57], off
	global_load_dword v211, v[48:49], off
	v_add_u32_e32 v56, s25, v44
	v_add_u32_e32 v48, s27, v39
	v_ashrrev_i32_e32 v57, 31, v56
	v_ashrrev_i32_e32 v49, 31, v48
	v_lshlrev_b64 v[56:57], 8, v[56:57]
	v_lshlrev_b64 v[48:49], 8, v[48:49]
	v_lshl_add_u64 v[56:57], v[30:31], 0, v[56:57]
	v_lshl_add_u64 v[48:49], v[30:31], 0, v[48:49]
	global_load_dword v212, v[56:57], off
	global_load_dword v213, v[48:49], off
	v_add_u32_e32 v56, s25, v46
	v_add_u32_e32 v48, s27, v41
	v_ashrrev_i32_e32 v57, 31, v56
	v_ashrrev_i32_e32 v49, 31, v48
	v_lshlrev_b64 v[56:57], 8, v[56:57]
	v_lshlrev_b64 v[48:49], 8, v[48:49]
	v_lshl_add_u64 v[56:57], v[30:31], 0, v[56:57]
	v_lshl_add_u64 v[48:49], v[30:31], 0, v[48:49]
	global_load_dword v214, v[56:57], off
	global_load_dword v215, v[48:49], off
	v_add_u32_e32 v43, s27, v5
	v_add_u32_e32 v45, s25, v4
	v_mad_u64_u32 v[48:49], s[30:31], v45, s59, v[6:7]
	v_mad_u64_u32 v[56:57], s[30:31], v43, s59, v[6:7]
	v_add_u32_e32 v43, s27, v7
	v_add_u32_e32 v45, s25, v8
	s_add_i32 s20, s20, 16
	s_add_i32 s19, s19, 16
	s_add_i32 s21, s21, -16
	s_cmp_lg_u32 s21, 0
	s_waitcnt vmcnt(14)
	ds_write_b32 v48, v200
	ds_write_b32 v56, v201
	v_mad_u64_u32 v[48:49], s[30:31], v45, s59, v[6:7]
	v_mad_u64_u32 v[56:57], s[30:31], v43, s59, v[6:7]
	v_add_u32_e32 v43, s27, v9
	v_add_u32_e32 v45, s25, v10
	s_waitcnt vmcnt(12)
	ds_write_b32 v48, v202
	ds_write_b32 v56, v203
	v_mad_u64_u32 v[48:49], s[30:31], v45, s59, v[6:7]
	v_mad_u64_u32 v[56:57], s[30:31], v43, s59, v[6:7]
	v_add_u32_e32 v43, s27, v11
	v_add_u32_e32 v45, s25, v12
	s_waitcnt vmcnt(10)
	ds_write_b32 v48, v204
	ds_write_b32 v56, v205
	v_mad_u64_u32 v[48:49], s[30:31], v45, s59, v[6:7]
	v_mad_u64_u32 v[56:57], s[30:31], v43, s59, v[6:7]
	v_add_u32_e32 v43, s27, v13
	v_add_u32_e32 v45, s25, v14
	s_waitcnt vmcnt(8)
	ds_write_b32 v48, v206
	ds_write_b32 v56, v207
	v_mad_u64_u32 v[48:49], s[30:31], v45, s59, v[6:7]
	v_mad_u64_u32 v[56:57], s[30:31], v43, s59, v[6:7]
	v_add_u32_e32 v43, s27, v15
	v_add_u32_e32 v45, s25, v16
	s_waitcnt vmcnt(6)
	ds_write_b32 v48, v208
	ds_write_b32 v56, v209
	v_mad_u64_u32 v[48:49], s[30:31], v45, s59, v[6:7]
	v_mad_u64_u32 v[56:57], s[30:31], v43, s59, v[6:7]
	v_add_u32_e32 v43, s27, v17
	v_add_u32_e32 v45, s25, v18
	s_waitcnt vmcnt(4)
	ds_write_b32 v48, v210
	ds_write_b32 v56, v211
	v_mad_u64_u32 v[48:49], s[30:31], v45, s59, v[6:7]
	v_mad_u64_u32 v[56:57], s[30:31], v43, s59, v[6:7]
	v_add_u32_e32 v45, s25, v20
	v_add_u32_e32 v43, s27, v19
	s_waitcnt vmcnt(2)
	ds_write_b32 v48, v212
	ds_write_b32 v56, v213
	v_mad_u64_u32 v[48:49], s[30:31], v45, s59, v[6:7]
	v_mad_u64_u32 v[56:57], s[30:31], v43, s59, v[6:7]
	s_waitcnt vmcnt(0)
	ds_write_b32 v48, v214
	ds_write_b32 v56, v215
	s_cbranch_scc1 .LBB0_179
	s_waitcnt lgkmcnt(0)
	ds_read2_b32 v[32:33], v51 offset1:33
	s_waitcnt lgkmcnt(0)
	v_cvt_pk_bf16_f32 v32, v32, v33
	ds_read2_b32 v[34:35], v51 offset0:66 offset1:99
	s_waitcnt lgkmcnt(0)
	v_cvt_pk_bf16_f32 v33, v34, v35
	ds_read2_b32 v[34:35], v51 offset0:132 offset1:165
	s_waitcnt lgkmcnt(0)
	v_cvt_pk_bf16_f32 v34, v34, v35
	ds_read2_b32 v[36:37], v51 offset0:198 offset1:231
	s_waitcnt lgkmcnt(0)
	v_cvt_pk_bf16_f32 v35, v36, v37
	v_add_u32_e32 v36, s24, v50
	s_ashr_i32 s27, s26, 31
	v_ashrrev_i32_e32 v37, 31, v36
	v_lshl_add_u64 v[30:31], s[26:27], 1, v[28:29]
	v_lshlrev_b64 v[36:37], 12, v[36:37]
	v_lshl_add_u64 v[36:37], v[30:31], 0, v[36:37]
	global_store_dwordx4 v[36:37], v[32:35], off
	ds_read2_b32 v[32:33], v51 offset0:8 offset1:41
	s_add_i32 s6, s6, s48
	s_waitcnt lgkmcnt(0)
	v_cvt_pk_bf16_f32 v32, v32, v33
	ds_read2_b32 v[34:35], v51 offset0:74 offset1:107
	s_waitcnt lgkmcnt(0)
	v_cvt_pk_bf16_f32 v33, v34, v35
	ds_read2_b32 v[34:35], v51 offset0:140 offset1:173
	s_waitcnt lgkmcnt(0)
	v_cvt_pk_bf16_f32 v34, v34, v35
	ds_read2_b32 v[36:37], v51 offset0:206 offset1:239
	s_waitcnt lgkmcnt(0)
	v_cvt_pk_bf16_f32 v35, v36, v37
	v_add_u32_e32 v36, s24, v52
	v_ashrrev_i32_e32 v37, 31, v36
	v_lshlrev_b64 v[36:37], 12, v[36:37]
	v_lshl_add_u64 v[36:37], v[30:31], 0, v[36:37]
	global_store_dwordx4 v[36:37], v[32:35], off
	ds_read2_b32 v[32:33], v51 offset0:16 offset1:49
	s_cmp_lt_i32 s6, 32
	s_waitcnt lgkmcnt(0)
	v_cvt_pk_bf16_f32 v32, v32, v33
	ds_read2_b32 v[34:35], v51 offset0:82 offset1:115
	s_waitcnt lgkmcnt(0)
	v_cvt_pk_bf16_f32 v33, v34, v35
	ds_read2_b32 v[34:35], v51 offset0:148 offset1:181
	s_waitcnt lgkmcnt(0)
	v_cvt_pk_bf16_f32 v34, v34, v35
	ds_read2_b32 v[36:37], v51 offset0:214 offset1:247
	s_waitcnt lgkmcnt(0)
	v_cvt_pk_bf16_f32 v35, v36, v37
	v_add_u32_e32 v36, s24, v53
	v_ashrrev_i32_e32 v37, 31, v36
	v_lshlrev_b64 v[36:37], 12, v[36:37]
	v_lshl_add_u64 v[36:37], v[30:31], 0, v[36:37]
	global_store_dwordx4 v[36:37], v[32:35], off
	ds_read2_b32 v[32:33], v51 offset0:24 offset1:57
	s_waitcnt lgkmcnt(0)
	v_cvt_pk_bf16_f32 v32, v32, v33
	ds_read2_b32 v[34:35], v51 offset0:90 offset1:123
	s_waitcnt lgkmcnt(0)
	v_cvt_pk_bf16_f32 v33, v34, v35
	ds_read2_b32 v[34:35], v51 offset0:156 offset1:189
	s_waitcnt lgkmcnt(0)
	v_cvt_pk_bf16_f32 v34, v34, v35
	ds_read2_b32 v[36:37], v51 offset0:222 offset1:255
	s_waitcnt lgkmcnt(0)
	v_cvt_pk_bf16_f32 v35, v36, v37
	v_add_u32_e32 v36, s24, v54
	v_ashrrev_i32_e32 v37, 31, v36
	v_lshlrev_b64 v[36:37], 12, v[36:37]
	v_lshl_add_u64 v[30:31], v[30:31], 0, v[36:37]
	global_store_dwordx4 v[30:31], v[32:35], off
	s_waitcnt lgkmcnt(0)
	s_cbranch_scc1 .LBB0_178

.LBB0_184:
	s_lshl_b32 s20, s5, 1
	s_lshl_b32 s21, s3, 1
	v_add_u32_e32 v56, s20, v32
	v_add_u32_e32 v48, s21, v1
	v_ashrrev_i32_e32 v57, 31, v56
	v_ashrrev_i32_e32 v49, 31, v48
	v_lshlrev_b64 v[60:61], 8, v[56:57]
	v_lshlrev_b64 v[58:59], 8, v[48:49]
	v_lshl_add_u64 v[60:61], v[30:31], 0, v[60:61]
	v_lshl_add_u64 v[56:57], v[56:57], 2, s[38:39]
	v_lshl_add_u64 v[58:59], v[30:31], 0, v[58:59]
	global_load_dword v202, v[60:61], off
	s_nop 0
	global_load_dword v203, v[58:59], off
	v_lshl_add_u64 v[48:49], v[48:49], 2, s[38:39]
	global_load_dword v200, v[56:57], off
	s_nop 0
	global_load_dword v201, v[48:49], off
	v_add_u32_e32 v56, s20, v34
	v_add_u32_e32 v48, s21, v21
	v_ashrrev_i32_e32 v57, 31, v56
	v_ashrrev_i32_e32 v49, 31, v48
	v_lshlrev_b64 v[60:61], 8, v[56:57]
	v_lshlrev_b64 v[58:59], 8, v[48:49]
	v_lshl_add_u64 v[60:61], v[30:31], 0, v[60:61]
	v_lshl_add_u64 v[56:57], v[56:57], 2, s[38:39]
	v_lshl_add_u64 v[58:59], v[30:31], 0, v[58:59]
	global_load_dword v206, v[60:61], off
	s_nop 0
	global_load_dword v207, v[58:59], off
	v_lshl_add_u64 v[48:49], v[48:49], 2, s[38:39]
	global_load_dword v204, v[56:57], off
	s_nop 0
	global_load_dword v205, v[48:49], off
	v_add_u32_e32 v56, s20, v36
	v_add_u32_e32 v48, s21, v23
	v_ashrrev_i32_e32 v57, 31, v56
	v_ashrrev_i32_e32 v49, 31, v48
	v_lshlrev_b64 v[60:61], 8, v[56:57]
	v_lshlrev_b64 v[58:59], 8, v[48:49]
	v_lshl_add_u64 v[60:61], v[30:31], 0, v[60:61]
	v_lshl_add_u64 v[56:57], v[56:57], 2, s[38:39]
	v_lshl_add_u64 v[58:59], v[30:31], 0, v[58:59]
	global_load_dword v210, v[60:61], off
	s_nop 0
	global_load_dword v211, v[58:59], off
	v_lshl_add_u64 v[48:49], v[48:49], 2, s[38:39]
	global_load_dword v208, v[56:57], off
	s_nop 0
	global_load_dword v209, v[48:49], off
	v_add_u32_e32 v56, s20, v38
	v_add_u32_e32 v48, s21, v33
	v_ashrrev_i32_e32 v57, 31, v56
	v_ashrrev_i32_e32 v49, 31, v48
	v_lshlrev_b64 v[60:61], 8, v[56:57]
	v_lshlrev_b64 v[58:59], 8, v[48:49]
	v_lshl_add_u64 v[60:61], v[30:31], 0, v[60:61]
	v_lshl_add_u64 v[56:57], v[56:57], 2, s[38:39]
	v_lshl_add_u64 v[58:59], v[30:31], 0, v[58:59]
	global_load_dword v214, v[60:61], off
	s_nop 0
	global_load_dword v215, v[58:59], off
	v_lshl_add_u64 v[48:49], v[48:49], 2, s[38:39]
	global_load_dword v212, v[56:57], off
	s_nop 0
	global_load_dword v213, v[48:49], off
	v_add_u32_e32 v56, s20, v40
	v_add_u32_e32 v48, s21, v35
	v_ashrrev_i32_e32 v57, 31, v56
	v_ashrrev_i32_e32 v49, 31, v48
	v_lshlrev_b64 v[60:61], 8, v[56:57]
	v_lshlrev_b64 v[58:59], 8, v[48:49]
	v_lshl_add_u64 v[60:61], v[30:31], 0, v[60:61]
	v_lshl_add_u64 v[56:57], v[56:57], 2, s[38:39]
	v_lshl_add_u64 v[58:59], v[30:31], 0, v[58:59]
	global_load_dword v218, v[60:61], off
	s_nop 0
	global_load_dword v219, v[58:59], off
	v_lshl_add_u64 v[48:49], v[48:49], 2, s[38:39]
	global_load_dword v216, v[56:57], off
	s_nop 0
	global_load_dword v217, v[48:49], off
	v_add_u32_e32 v56, s20, v42
	v_add_u32_e32 v48, s21, v37
	v_ashrrev_i32_e32 v57, 31, v56
	v_ashrrev_i32_e32 v49, 31, v48
	v_lshlrev_b64 v[60:61], 8, v[56:57]
	v_lshlrev_b64 v[58:59], 8, v[48:49]
	v_lshl_add_u64 v[60:61], v[30:31], 0, v[60:61]
	v_lshl_add_u64 v[56:57], v[56:57], 2, s[38:39]
	v_lshl_add_u64 v[58:59], v[30:31], 0, v[58:59]
	global_load_dword v222, v[60:61], off
	s_nop 0
	global_load_dword v223, v[58:59], off
	v_lshl_add_u64 v[48:49], v[48:49], 2, s[38:39]
	global_load_dword v220, v[56:57], off
	s_nop 0
	global_load_dword v221, v[48:49], off
	v_add_u32_e32 v56, s20, v44
	v_add_u32_e32 v48, s21, v39
	v_ashrrev_i32_e32 v57, 31, v56
	v_ashrrev_i32_e32 v49, 31, v48
	v_lshlrev_b64 v[60:61], 8, v[56:57]
	v_lshlrev_b64 v[58:59], 8, v[48:49]
	v_lshl_add_u64 v[60:61], v[30:31], 0, v[60:61]
	v_lshl_add_u64 v[56:57], v[56:57], 2, s[38:39]
	v_lshl_add_u64 v[58:59], v[30:31], 0, v[58:59]
	global_load_dword v226, v[60:61], off
	s_nop 0
	global_load_dword v227, v[58:59], off
	v_lshl_add_u64 v[48:49], v[48:49], 2, s[38:39]
	global_load_dword v224, v[56:57], off
	s_nop 0
	global_load_dword v225, v[48:49], off
	v_add_u32_e32 v56, s20, v46
	v_add_u32_e32 v48, s21, v41
	v_ashrrev_i32_e32 v57, 31, v56
	v_ashrrev_i32_e32 v49, 31, v48
	v_lshlrev_b64 v[60:61], 8, v[56:57]
	v_lshlrev_b64 v[58:59], 8, v[48:49]
	v_lshl_add_u64 v[60:61], v[30:31], 0, v[60:61]
	v_lshl_add_u64 v[56:57], v[56:57], 2, s[38:39]
	v_lshl_add_u64 v[58:59], v[30:31], 0, v[58:59]
	global_load_dword v230, v[60:61], off
	s_nop 0
	global_load_dword v231, v[58:59], off
	v_lshl_add_u64 v[48:49], v[48:49], 2, s[38:39]
	global_load_dword v228, v[56:57], off
	s_nop 0
	global_load_dword v229, v[48:49], off
	v_add_u32_e32 v45, s20, v4
	v_add_u32_e32 v43, s21, v5
	v_mad_u64_u32 v[58:59], s[24:25], v43, s59, v[6:7]
	v_add_u32_e32 v43, s21, v7
	s_add_i32 s5, s5, 16
	s_add_i32 s3, s3, 16
	s_add_i32 s19, s19, -16
	s_cmp_lg_u32 s19, 0
	s_waitcnt vmcnt(28)
	v_pk_mul_f32 v[48:49], v[202:203], v[200:201]
	v_mad_u64_u32 v[56:57], s[24:25], v45, s59, v[6:7]
	ds_write_b32 v56, v48
	ds_write_b32 v58, v49
	v_add_u32_e32 v45, s20, v8
	v_mad_u64_u32 v[58:59], s[24:25], v43, s59, v[6:7]
	v_add_u32_e32 v43, s21, v9
	s_waitcnt vmcnt(24)
	v_pk_mul_f32 v[48:49], v[206:207], v[204:205]
	v_mad_u64_u32 v[56:57], s[24:25], v45, s59, v[6:7]
	ds_write_b32 v56, v48
	ds_write_b32 v58, v49
	v_add_u32_e32 v45, s20, v10
	v_mad_u64_u32 v[58:59], s[24:25], v43, s59, v[6:7]
	v_add_u32_e32 v43, s21, v11
	s_waitcnt vmcnt(20)
	v_pk_mul_f32 v[48:49], v[210:211], v[208:209]
	v_mad_u64_u32 v[56:57], s[24:25], v45, s59, v[6:7]
	ds_write_b32 v56, v48
	ds_write_b32 v58, v49
	v_add_u32_e32 v45, s20, v12
	v_mad_u64_u32 v[58:59], s[24:25], v43, s59, v[6:7]
	v_add_u32_e32 v43, s21, v13
	s_waitcnt vmcnt(16)
	v_pk_mul_f32 v[48:49], v[214:215], v[212:213]
	v_mad_u64_u32 v[56:57], s[24:25], v45, s59, v[6:7]
	ds_write_b32 v56, v48
	ds_write_b32 v58, v49
	v_add_u32_e32 v45, s20, v14
	v_mad_u64_u32 v[58:59], s[24:25], v43, s59, v[6:7]
	v_add_u32_e32 v43, s21, v15
	s_waitcnt vmcnt(12)
	v_pk_mul_f32 v[48:49], v[218:219], v[216:217]
	v_mad_u64_u32 v[56:57], s[24:25], v45, s59, v[6:7]
	ds_write_b32 v56, v48
	ds_write_b32 v58, v49
	v_add_u32_e32 v45, s20, v16
	v_mad_u64_u32 v[58:59], s[24:25], v43, s59, v[6:7]
	v_add_u32_e32 v43, s21, v17
	s_waitcnt vmcnt(8)
	v_pk_mul_f32 v[48:49], v[222:223], v[220:221]
	v_mad_u64_u32 v[56:57], s[24:25], v45, s59, v[6:7]
	ds_write_b32 v56, v48
	ds_write_b32 v58, v49
	v_add_u32_e32 v45, s20, v18
	v_mad_u64_u32 v[58:59], s[24:25], v43, s59, v[6:7]
	v_add_u32_e32 v43, s21, v19
	s_waitcnt vmcnt(4)
	v_pk_mul_f32 v[48:49], v[226:227], v[224:225]
	v_mad_u64_u32 v[56:57], s[24:25], v45, s59, v[6:7]
	ds_write_b32 v56, v48
	ds_write_b32 v58, v49
	v_add_u32_e32 v45, s20, v20
	v_mad_u64_u32 v[58:59], s[20:21], v43, s59, v[6:7]
	s_waitcnt vmcnt(0)
	v_pk_mul_f32 v[48:49], v[230:231], v[228:229]
	v_mad_u64_u32 v[56:57], s[20:21], v45, s59, v[6:7]
	ds_write_b32 v56, v48
	ds_write_b32 v58, v49
	s_cbranch_scc1 .LBB0_184
	s_waitcnt lgkmcnt(0)
	ds_read2_b32 v[32:33], v51 offset1:33
	s_waitcnt lgkmcnt(0)
	v_cvt_pk_bf16_f32 v32, v32, v33
	ds_read2_b32 v[34:35], v51 offset0:66 offset1:99
	s_waitcnt lgkmcnt(0)
	v_cvt_pk_bf16_f32 v33, v34, v35
	ds_read2_b32 v[34:35], v51 offset0:132 offset1:165
	s_waitcnt lgkmcnt(0)
	v_cvt_pk_bf16_f32 v34, v34, v35
	ds_read2_b32 v[36:37], v51 offset0:198 offset1:231
	s_waitcnt lgkmcnt(0)
	v_cvt_pk_bf16_f32 v35, v36, v37
	v_add_u32_e32 v36, s2, v50
	s_ashr_i32 s5, s4, 31
	v_ashrrev_i32_e32 v37, 31, v36
	v_lshl_add_u64 v[30:31], s[4:5], 1, v[28:29]
	v_lshlrev_b64 v[36:37], 12, v[36:37]
	v_lshl_add_u64 v[36:37], v[30:31], 0, v[36:37]
	global_store_dwordx4 v[36:37], v[32:35], off
	ds_read2_b32 v[32:33], v51 offset0:8 offset1:41
	s_add_i32 s18, s18, s48
	s_waitcnt lgkmcnt(0)
	v_cvt_pk_bf16_f32 v32, v32, v33
	ds_read2_b32 v[34:35], v51 offset0:74 offset1:107
	s_waitcnt lgkmcnt(0)
	v_cvt_pk_bf16_f32 v33, v34, v35
	ds_read2_b32 v[34:35], v51 offset0:140 offset1:173
	s_waitcnt lgkmcnt(0)
	v_cvt_pk_bf16_f32 v34, v34, v35
	ds_read2_b32 v[36:37], v51 offset0:206 offset1:239
	s_waitcnt lgkmcnt(0)
	v_cvt_pk_bf16_f32 v35, v36, v37
	v_add_u32_e32 v36, s2, v52
	v_ashrrev_i32_e32 v37, 31, v36
	v_lshlrev_b64 v[36:37], 12, v[36:37]
	v_lshl_add_u64 v[36:37], v[30:31], 0, v[36:37]
	global_store_dwordx4 v[36:37], v[32:35], off
	ds_read2_b32 v[32:33], v51 offset0:16 offset1:49
	s_cmp_lt_i32 s18, 32
	s_waitcnt lgkmcnt(0)
	v_cvt_pk_bf16_f32 v32, v32, v33
	ds_read2_b32 v[34:35], v51 offset0:82 offset1:115
	s_waitcnt lgkmcnt(0)
	v_cvt_pk_bf16_f32 v33, v34, v35
	ds_read2_b32 v[34:35], v51 offset0:148 offset1:181
	s_waitcnt lgkmcnt(0)
	v_cvt_pk_bf16_f32 v34, v34, v35
	ds_read2_b32 v[36:37], v51 offset0:214 offset1:247
	s_waitcnt lgkmcnt(0)
	v_cvt_pk_bf16_f32 v35, v36, v37
	v_add_u32_e32 v36, s2, v53
	v_ashrrev_i32_e32 v37, 31, v36
	v_lshlrev_b64 v[36:37], 12, v[36:37]
	v_lshl_add_u64 v[36:37], v[30:31], 0, v[36:37]
	global_store_dwordx4 v[36:37], v[32:35], off
	ds_read2_b32 v[32:33], v51 offset0:24 offset1:57
	s_waitcnt lgkmcnt(0)
	v_cvt_pk_bf16_f32 v32, v32, v33
	ds_read2_b32 v[34:35], v51 offset0:90 offset1:123
	s_waitcnt lgkmcnt(0)
	v_cvt_pk_bf16_f32 v33, v34, v35
	ds_read2_b32 v[34:35], v51 offset0:156 offset1:189
	s_waitcnt lgkmcnt(0)
	v_cvt_pk_bf16_f32 v34, v34, v35
	ds_read2_b32 v[36:37], v51 offset0:222 offset1:255
	s_waitcnt lgkmcnt(0)
	v_cvt_pk_bf16_f32 v35, v36, v37
	v_add_u32_e32 v36, s2, v54
	v_ashrrev_i32_e32 v37, 31, v36
	v_lshlrev_b64 v[36:37], 12, v[36:37]
	v_lshl_add_u64 v[30:31], v[30:31], 0, v[36:37]
	global_store_dwordx4 v[30:31], v[32:35], off
	s_waitcnt lgkmcnt(0)
	s_cbranch_scc1 .LBB0_183

.LBB0_189:
	s_lshl_b32 s19, s6, 1
	s_lshl_b32 s20, s3, 1
	v_add_u32_e32 v34, s19, v4
	v_add_u32_e32 v32, s20, v5
	v_ashrrev_i32_e32 v35, 31, v34
	v_ashrrev_i32_e32 v33, 31, v32
	v_lshlrev_b64 v[38:39], 12, v[34:35]
	v_lshlrev_b64 v[36:37], 12, v[32:33]
	v_lshl_add_u64 v[38:39], v[30:31], 0, v[38:39]
	v_lshl_add_u64 v[36:37], v[30:31], 0, v[36:37]
	global_load_dword v200, v[38:39], off
	global_load_dword v201, v[36:37], off
	v_mov_b32_e32 v202, v34
	v_mov_b32_e32 v203, v32
	v_add_u32_e32 v34, s19, v8
	v_add_u32_e32 v32, s20, v7
	v_ashrrev_i32_e32 v35, 31, v34
	v_ashrrev_i32_e32 v33, 31, v32
	v_lshlrev_b64 v[38:39], 12, v[34:35]
	v_lshlrev_b64 v[36:37], 12, v[32:33]
	v_lshl_add_u64 v[38:39], v[30:31], 0, v[38:39]
	v_lshl_add_u64 v[36:37], v[30:31], 0, v[36:37]
	global_load_dword v204, v[38:39], off
	global_load_dword v205, v[36:37], off
	v_mov_b32_e32 v206, v34
	v_mov_b32_e32 v207, v32
	v_add_u32_e32 v34, s19, v10
	v_add_u32_e32 v32, s20, v9
	v_ashrrev_i32_e32 v35, 31, v34
	v_ashrrev_i32_e32 v33, 31, v32
	v_lshlrev_b64 v[38:39], 12, v[34:35]
	v_lshlrev_b64 v[36:37], 12, v[32:33]
	v_lshl_add_u64 v[38:39], v[30:31], 0, v[38:39]
	v_lshl_add_u64 v[36:37], v[30:31], 0, v[36:37]
	global_load_dword v208, v[38:39], off
	global_load_dword v209, v[36:37], off
	v_mov_b32_e32 v210, v34
	v_mov_b32_e32 v211, v32
	v_add_u32_e32 v34, s19, v12
	v_add_u32_e32 v32, s20, v11
	v_ashrrev_i32_e32 v35, 31, v34
	v_ashrrev_i32_e32 v33, 31, v32
	v_lshlrev_b64 v[38:39], 12, v[34:35]
	v_lshlrev_b64 v[36:37], 12, v[32:33]
	v_lshl_add_u64 v[38:39], v[30:31], 0, v[38:39]
	v_lshl_add_u64 v[36:37], v[30:31], 0, v[36:37]
	global_load_dword v212, v[38:39], off
	global_load_dword v213, v[36:37], off
	v_mov_b32_e32 v214, v34
	v_mov_b32_e32 v215, v32
	v_add_u32_e32 v34, s19, v14
	v_add_u32_e32 v32, s20, v13
	v_ashrrev_i32_e32 v35, 31, v34
	v_ashrrev_i32_e32 v33, 31, v32
	v_lshlrev_b64 v[38:39], 12, v[34:35]
	v_lshlrev_b64 v[36:37], 12, v[32:33]
	v_lshl_add_u64 v[38:39], v[30:31], 0, v[38:39]
	v_lshl_add_u64 v[36:37], v[30:31], 0, v[36:37]
	global_load_dword v216, v[38:39], off
	global_load_dword v217, v[36:37], off
	v_mov_b32_e32 v218, v34
	v_mov_b32_e32 v219, v32
	v_add_u32_e32 v34, s19, v16
	v_add_u32_e32 v32, s20, v15
	v_ashrrev_i32_e32 v35, 31, v34
	v_ashrrev_i32_e32 v33, 31, v32
	v_lshlrev_b64 v[38:39], 12, v[34:35]
	v_lshlrev_b64 v[36:37], 12, v[32:33]
	v_lshl_add_u64 v[38:39], v[30:31], 0, v[38:39]
	v_lshl_add_u64 v[36:37], v[30:31], 0, v[36:37]
	global_load_dword v220, v[38:39], off
	global_load_dword v221, v[36:37], off
	v_mov_b32_e32 v222, v34
	v_mov_b32_e32 v223, v32
	v_add_u32_e32 v34, s19, v18
	v_add_u32_e32 v32, s20, v17
	v_ashrrev_i32_e32 v35, 31, v34
	v_ashrrev_i32_e32 v33, 31, v32
	v_lshlrev_b64 v[38:39], 12, v[34:35]
	v_lshlrev_b64 v[36:37], 12, v[32:33]
	v_lshl_add_u64 v[38:39], v[30:31], 0, v[38:39]
	v_lshl_add_u64 v[36:37], v[30:31], 0, v[36:37]
	global_load_dword v224, v[38:39], off
	global_load_dword v225, v[36:37], off
	v_mov_b32_e32 v226, v34
	v_mov_b32_e32 v227, v32
	v_add_u32_e32 v34, s19, v20
	v_add_u32_e32 v32, s20, v19
	v_ashrrev_i32_e32 v35, 31, v34
	v_ashrrev_i32_e32 v33, 31, v32
	v_lshlrev_b64 v[38:39], 12, v[34:35]
	v_lshlrev_b64 v[36:37], 12, v[32:33]
	v_lshl_add_u64 v[38:39], v[30:31], 0, v[38:39]
	v_lshl_add_u64 v[36:37], v[30:31], 0, v[36:37]
	global_load_dword v228, v[38:39], off
	global_load_dword v229, v[36:37], off
	v_mov_b32_e32 v230, v34
	v_mov_b32_e32 v231, v32
	v_mad_u64_u32 v[34:35], s[24:25], v202, s59, v[6:7]
	v_mad_u64_u32 v[32:33], s[24:25], v203, s59, v[6:7]
	s_add_i32 s6, s6, 16
	s_add_i32 s3, s3, 16
	s_add_i32 s18, s18, -16
	s_cmp_lg_u32 s18, 0
	s_waitcnt vmcnt(14)
	ds_write_b32 v34, v200
	ds_write_b32 v32, v201
	v_mad_u64_u32 v[34:35], s[24:25], v206, s59, v[6:7]
	v_mad_u64_u32 v[32:33], s[24:25], v207, s59, v[6:7]
	s_waitcnt vmcnt(12)
	ds_write_b32 v34, v204
	ds_write_b32 v32, v205
	v_mad_u64_u32 v[34:35], s[24:25], v210, s59, v[6:7]
	v_mad_u64_u32 v[32:33], s[24:25], v211, s59, v[6:7]
	s_waitcnt vmcnt(10)
	ds_write_b32 v34, v208
	ds_write_b32 v32, v209
	v_mad_u64_u32 v[34:35], s[24:25], v214, s59, v[6:7]
	v_mad_u64_u32 v[32:33], s[24:25], v215, s59, v[6:7]
	s_waitcnt vmcnt(8)
	ds_write_b32 v34, v212
	ds_write_b32 v32, v213
	v_mad_u64_u32 v[34:35], s[24:25], v218, s59, v[6:7]
	v_mad_u64_u32 v[32:33], s[24:25], v219, s59, v[6:7]
	s_waitcnt vmcnt(6)
	ds_write_b32 v34, v216
	ds_write_b32 v32, v217
	v_mad_u64_u32 v[34:35], s[24:25], v222, s59, v[6:7]
	v_mad_u64_u32 v[32:33], s[24:25], v223, s59, v[6:7]
	s_waitcnt vmcnt(4)
	ds_write_b32 v34, v220
	ds_write_b32 v32, v221
	v_mad_u64_u32 v[34:35], s[24:25], v226, s59, v[6:7]
	v_mad_u64_u32 v[32:33], s[24:25], v227, s59, v[6:7]
	s_waitcnt vmcnt(2)
	ds_write_b32 v34, v224
	ds_write_b32 v32, v225
	v_mad_u64_u32 v[34:35], s[20:21], v230, s59, v[6:7]
	v_mad_u64_u32 v[32:33], s[20:21], v231, s59, v[6:7]
	s_waitcnt vmcnt(0)
	ds_write_b32 v34, v228
	ds_write_b32 v32, v229
	s_cbranch_scc1 .LBB0_189
	s_waitcnt lgkmcnt(0)
	ds_read2_b32 v[30:31], v51 offset1:33
	s_waitcnt lgkmcnt(0)
	v_cvt_pk_bf16_f32 v30, v30, v31
	ds_read2_b32 v[32:33], v51 offset0:66 offset1:99
	s_waitcnt lgkmcnt(0)
	v_cvt_pk_bf16_f32 v31, v32, v33
	ds_read2_b32 v[32:33], v51 offset0:132 offset1:165
	s_waitcnt lgkmcnt(0)
	v_cvt_pk_bf16_f32 v32, v32, v33
	ds_read2_b32 v[34:35], v51 offset0:198 offset1:231
	s_waitcnt lgkmcnt(0)
	v_cvt_pk_bf16_f32 v33, v34, v35
	v_add_u32_e32 v34, s2, v50
	v_ashrrev_i32_e32 v35, 31, v34
	v_lshlrev_b64 v[34:35], 7, v[34:35]
	v_lshl_add_u64 v[34:35], v[28:29], 0, v[34:35]
	global_store_dwordx4 v[34:35], v[30:33], off
	ds_read2_b32 v[30:31], v51 offset0:8 offset1:41
	s_add_i32 s5, s5, s48
	s_waitcnt lgkmcnt(0)
	v_cvt_pk_bf16_f32 v30, v30, v31
	ds_read2_b32 v[32:33], v51 offset0:74 offset1:107
	s_waitcnt lgkmcnt(0)
	v_cvt_pk_bf16_f32 v31, v32, v33
	ds_read2_b32 v[32:33], v51 offset0:140 offset1:173
	s_waitcnt lgkmcnt(0)
	v_cvt_pk_bf16_f32 v32, v32, v33
	ds_read2_b32 v[34:35], v51 offset0:206 offset1:239
	s_waitcnt lgkmcnt(0)
	v_cvt_pk_bf16_f32 v33, v34, v35
	v_add_u32_e32 v34, s2, v52
	v_ashrrev_i32_e32 v35, 31, v34
	v_lshlrev_b64 v[34:35], 7, v[34:35]
	v_lshl_add_u64 v[34:35], v[28:29], 0, v[34:35]
	global_store_dwordx4 v[34:35], v[30:33], off
	ds_read2_b32 v[30:31], v51 offset0:16 offset1:49
	s_cmp_lt_i32 s5, 32
	s_waitcnt lgkmcnt(0)
	v_cvt_pk_bf16_f32 v30, v30, v31
	ds_read2_b32 v[32:33], v51 offset0:82 offset1:115
	s_waitcnt lgkmcnt(0)
	v_cvt_pk_bf16_f32 v31, v32, v33
	ds_read2_b32 v[32:33], v51 offset0:148 offset1:181
	s_waitcnt lgkmcnt(0)
	v_cvt_pk_bf16_f32 v32, v32, v33
	ds_read2_b32 v[34:35], v51 offset0:214 offset1:247
	s_waitcnt lgkmcnt(0)
	v_cvt_pk_bf16_f32 v33, v34, v35
	v_add_u32_e32 v34, s2, v53
	v_ashrrev_i32_e32 v35, 31, v34
	v_lshlrev_b64 v[34:35], 7, v[34:35]
	v_lshl_add_u64 v[34:35], v[28:29], 0, v[34:35]
	global_store_dwordx4 v[34:35], v[30:33], off
	ds_read2_b32 v[30:31], v51 offset0:24 offset1:57
	s_waitcnt lgkmcnt(0)
	v_cvt_pk_bf16_f32 v30, v30, v31
	ds_read2_b32 v[32:33], v51 offset0:90 offset1:123
	s_waitcnt lgkmcnt(0)
	v_cvt_pk_bf16_f32 v31, v32, v33
	ds_read2_b32 v[32:33], v51 offset0:156 offset1:189
	s_waitcnt lgkmcnt(0)
	v_cvt_pk_bf16_f32 v32, v32, v33
	ds_read2_b32 v[34:35], v51 offset0:222 offset1:255
	s_waitcnt lgkmcnt(0)
	v_cvt_pk_bf16_f32 v33, v34, v35
	v_add_u32_e32 v34, s2, v54
	v_ashrrev_i32_e32 v35, 31, v34
	v_lshlrev_b64 v[34:35], 7, v[34:35]
	v_lshl_add_u64 v[34:35], v[28:29], 0, v[34:35]
	global_store_dwordx4 v[34:35], v[30:33], off
	s_waitcnt lgkmcnt(0)
	s_cbranch_scc1 .LBB0_188

.LBB0_194:
	s_lshl_b32 s19, s6, 1
	s_lshl_b32 s20, s3, 1
	v_add_u32_e32 v34, s19, v4
	v_add_u32_e32 v32, s20, v5
	v_ashrrev_i32_e32 v35, 31, v34
	v_ashrrev_i32_e32 v33, 31, v32
	v_lshlrev_b64 v[38:39], 12, v[34:35]
	v_lshlrev_b64 v[36:37], 12, v[32:33]
	v_lshl_add_u64 v[38:39], v[30:31], 0, v[38:39]
	v_lshl_add_u64 v[36:37], v[30:31], 0, v[36:37]
	global_load_dword v200, v[38:39], off
	global_load_dword v201, v[36:37], off
	v_mov_b32_e32 v202, v34
	v_mov_b32_e32 v203, v32
	v_add_u32_e32 v34, s19, v8
	v_add_u32_e32 v32, s20, v7
	v_ashrrev_i32_e32 v35, 31, v34
	v_ashrrev_i32_e32 v33, 31, v32
	v_lshlrev_b64 v[38:39], 12, v[34:35]
	v_lshlrev_b64 v[36:37], 12, v[32:33]
	v_lshl_add_u64 v[38:39], v[30:31], 0, v[38:39]
	v_lshl_add_u64 v[36:37], v[30:31], 0, v[36:37]
	global_load_dword v204, v[38:39], off
	global_load_dword v205, v[36:37], off
	v_mov_b32_e32 v206, v34
	v_mov_b32_e32 v207, v32
	v_add_u32_e32 v34, s19, v10
	v_add_u32_e32 v32, s20, v9
	v_ashrrev_i32_e32 v35, 31, v34
	v_ashrrev_i32_e32 v33, 31, v32
	v_lshlrev_b64 v[38:39], 12, v[34:35]
	v_lshlrev_b64 v[36:37], 12, v[32:33]
	v_lshl_add_u64 v[38:39], v[30:31], 0, v[38:39]
	v_lshl_add_u64 v[36:37], v[30:31], 0, v[36:37]
	global_load_dword v208, v[38:39], off
	global_load_dword v209, v[36:37], off
	v_mov_b32_e32 v210, v34
	v_mov_b32_e32 v211, v32
	v_add_u32_e32 v34, s19, v12
	v_add_u32_e32 v32, s20, v11
	v_ashrrev_i32_e32 v35, 31, v34
	v_ashrrev_i32_e32 v33, 31, v32
	v_lshlrev_b64 v[38:39], 12, v[34:35]
	v_lshlrev_b64 v[36:37], 12, v[32:33]
	v_lshl_add_u64 v[38:39], v[30:31], 0, v[38:39]
	v_lshl_add_u64 v[36:37], v[30:31], 0, v[36:37]
	global_load_dword v212, v[38:39], off
	global_load_dword v213, v[36:37], off
	v_mov_b32_e32 v214, v34
	v_mov_b32_e32 v215, v32
	v_add_u32_e32 v34, s19, v14
	v_add_u32_e32 v32, s20, v13
	v_ashrrev_i32_e32 v35, 31, v34
	v_ashrrev_i32_e32 v33, 31, v32
	v_lshlrev_b64 v[38:39], 12, v[34:35]
	v_lshlrev_b64 v[36:37], 12, v[32:33]
	v_lshl_add_u64 v[38:39], v[30:31], 0, v[38:39]
	v_lshl_add_u64 v[36:37], v[30:31], 0, v[36:37]
	global_load_dword v216, v[38:39], off
	global_load_dword v217, v[36:37], off
	v_mov_b32_e32 v218, v34
	v_mov_b32_e32 v219, v32
	v_add_u32_e32 v34, s19, v16
	v_add_u32_e32 v32, s20, v15
	v_ashrrev_i32_e32 v35, 31, v34
	v_ashrrev_i32_e32 v33, 31, v32
	v_lshlrev_b64 v[38:39], 12, v[34:35]
	v_lshlrev_b64 v[36:37], 12, v[32:33]
	v_lshl_add_u64 v[38:39], v[30:31], 0, v[38:39]
	v_lshl_add_u64 v[36:37], v[30:31], 0, v[36:37]
	global_load_dword v220, v[38:39], off
	global_load_dword v221, v[36:37], off
	v_mov_b32_e32 v222, v34
	v_mov_b32_e32 v223, v32
	v_add_u32_e32 v34, s19, v18
	v_add_u32_e32 v32, s20, v17
	v_ashrrev_i32_e32 v35, 31, v34
	v_ashrrev_i32_e32 v33, 31, v32
	v_lshlrev_b64 v[38:39], 12, v[34:35]
	v_lshlrev_b64 v[36:37], 12, v[32:33]
	v_lshl_add_u64 v[38:39], v[30:31], 0, v[38:39]
	v_lshl_add_u64 v[36:37], v[30:31], 0, v[36:37]
	global_load_dword v224, v[38:39], off
	global_load_dword v225, v[36:37], off
	v_mov_b32_e32 v226, v34
	v_mov_b32_e32 v227, v32
	v_add_u32_e32 v34, s19, v20
	v_add_u32_e32 v32, s20, v19
	v_ashrrev_i32_e32 v35, 31, v34
	v_ashrrev_i32_e32 v33, 31, v32
	v_lshlrev_b64 v[38:39], 12, v[34:35]
	v_lshlrev_b64 v[36:37], 12, v[32:33]
	v_lshl_add_u64 v[38:39], v[30:31], 0, v[38:39]
	v_lshl_add_u64 v[36:37], v[30:31], 0, v[36:37]
	global_load_dword v228, v[38:39], off
	global_load_dword v229, v[36:37], off
	v_mov_b32_e32 v230, v34
	v_mov_b32_e32 v231, v32
	v_mad_u64_u32 v[34:35], s[24:25], v202, s59, v[6:7]
	v_mad_u64_u32 v[32:33], s[24:25], v203, s59, v[6:7]
	s_add_i32 s6, s6, 16
	s_add_i32 s3, s3, 16
	s_add_i32 s18, s18, -16
	s_cmp_lg_u32 s18, 0
	s_waitcnt vmcnt(14)
	ds_write_b32 v34, v200
	ds_write_b32 v32, v201
	v_mad_u64_u32 v[34:35], s[24:25], v206, s59, v[6:7]
	v_mad_u64_u32 v[32:33], s[24:25], v207, s59, v[6:7]
	s_waitcnt vmcnt(12)
	ds_write_b32 v34, v204
	ds_write_b32 v32, v205
	v_mad_u64_u32 v[34:35], s[24:25], v210, s59, v[6:7]
	v_mad_u64_u32 v[32:33], s[24:25], v211, s59, v[6:7]
	s_waitcnt vmcnt(10)
	ds_write_b32 v34, v208
	ds_write_b32 v32, v209
	v_mad_u64_u32 v[34:35], s[24:25], v214, s59, v[6:7]
	v_mad_u64_u32 v[32:33], s[24:25], v215, s59, v[6:7]
	s_waitcnt vmcnt(8)
	ds_write_b32 v34, v212
	ds_write_b32 v32, v213
	v_mad_u64_u32 v[34:35], s[24:25], v218, s59, v[6:7]
	v_mad_u64_u32 v[32:33], s[24:25], v219, s59, v[6:7]
	s_waitcnt vmcnt(6)
	ds_write_b32 v34, v216
	ds_write_b32 v32, v217
	v_mad_u64_u32 v[34:35], s[24:25], v222, s59, v[6:7]
	v_mad_u64_u32 v[32:33], s[24:25], v223, s59, v[6:7]
	s_waitcnt vmcnt(4)
	ds_write_b32 v34, v220
	ds_write_b32 v32, v221
	v_mad_u64_u32 v[34:35], s[24:25], v226, s59, v[6:7]
	v_mad_u64_u32 v[32:33], s[24:25], v227, s59, v[6:7]
	s_waitcnt vmcnt(2)
	ds_write_b32 v34, v224
	ds_write_b32 v32, v225
	v_mad_u64_u32 v[34:35], s[20:21], v230, s59, v[6:7]
	v_mad_u64_u32 v[32:33], s[20:21], v231, s59, v[6:7]
	s_waitcnt vmcnt(0)
	ds_write_b32 v34, v228
	ds_write_b32 v32, v229
	s_cbranch_scc1 .LBB0_194
	s_waitcnt lgkmcnt(0)
	ds_read2_b32 v[30:31], v51 offset1:33
	s_waitcnt lgkmcnt(0)
	v_cvt_pk_bf16_f32 v30, v30, v31
	ds_read2_b32 v[32:33], v51 offset0:66 offset1:99
	s_waitcnt lgkmcnt(0)
	v_cvt_pk_bf16_f32 v31, v32, v33
	ds_read2_b32 v[32:33], v51 offset0:132 offset1:165
	s_waitcnt lgkmcnt(0)
	v_cvt_pk_bf16_f32 v32, v32, v33
	ds_read2_b32 v[34:35], v51 offset0:198 offset1:231
	s_waitcnt lgkmcnt(0)
	v_cvt_pk_bf16_f32 v33, v34, v35
	v_add_u32_e32 v34, s2, v50
	v_ashrrev_i32_e32 v35, 31, v34
	v_lshlrev_b64 v[34:35], 7, v[34:35]
	v_lshl_add_u64 v[34:35], v[28:29], 0, v[34:35]
	global_store_dwordx4 v[34:35], v[30:33], off
	ds_read2_b32 v[30:31], v51 offset0:8 offset1:41
	s_add_i32 s5, s5, s48
	s_waitcnt lgkmcnt(0)
	v_cvt_pk_bf16_f32 v30, v30, v31
	ds_read2_b32 v[32:33], v51 offset0:74 offset1:107
	s_waitcnt lgkmcnt(0)
	v_cvt_pk_bf16_f32 v31, v32, v33
	ds_read2_b32 v[32:33], v51 offset0:140 offset1:173
	s_waitcnt lgkmcnt(0)
	v_cvt_pk_bf16_f32 v32, v32, v33
	ds_read2_b32 v[34:35], v51 offset0:206 offset1:239
	s_waitcnt lgkmcnt(0)
	v_cvt_pk_bf16_f32 v33, v34, v35
	v_add_u32_e32 v34, s2, v52
	v_ashrrev_i32_e32 v35, 31, v34
	v_lshlrev_b64 v[34:35], 7, v[34:35]
	v_lshl_add_u64 v[34:35], v[28:29], 0, v[34:35]
	global_store_dwordx4 v[34:35], v[30:33], off
	ds_read2_b32 v[30:31], v51 offset0:16 offset1:49
	s_cmp_lt_i32 s5, 32
	s_waitcnt lgkmcnt(0)
	v_cvt_pk_bf16_f32 v30, v30, v31
	ds_read2_b32 v[32:33], v51 offset0:82 offset1:115
	s_waitcnt lgkmcnt(0)
	v_cvt_pk_bf16_f32 v31, v32, v33
	ds_read2_b32 v[32:33], v51 offset0:148 offset1:181
	s_waitcnt lgkmcnt(0)
	v_cvt_pk_bf16_f32 v32, v32, v33
	ds_read2_b32 v[34:35], v51 offset0:214 offset1:247
	s_waitcnt lgkmcnt(0)
	v_cvt_pk_bf16_f32 v33, v34, v35
	v_add_u32_e32 v34, s2, v53
	v_ashrrev_i32_e32 v35, 31, v34
	v_lshlrev_b64 v[34:35], 7, v[34:35]
	v_lshl_add_u64 v[34:35], v[28:29], 0, v[34:35]
	global_store_dwordx4 v[34:35], v[30:33], off
	ds_read2_b32 v[30:31], v51 offset0:24 offset1:57
	s_waitcnt lgkmcnt(0)
	v_cvt_pk_bf16_f32 v30, v30, v31
	ds_read2_b32 v[32:33], v51 offset0:90 offset1:123
	s_waitcnt lgkmcnt(0)
	v_cvt_pk_bf16_f32 v31, v32, v33
	ds_read2_b32 v[32:33], v51 offset0:156 offset1:189
	s_waitcnt lgkmcnt(0)
	v_cvt_pk_bf16_f32 v32, v32, v33
	ds_read2_b32 v[34:35], v51 offset0:222 offset1:255
	s_waitcnt lgkmcnt(0)
	v_cvt_pk_bf16_f32 v33, v34, v35
	v_add_u32_e32 v34, s2, v54
	v_ashrrev_i32_e32 v35, 31, v34
	v_lshlrev_b64 v[34:35], 7, v[34:35]
	v_lshl_add_u64 v[34:35], v[28:29], 0, v[34:35]
	global_store_dwordx4 v[34:35], v[30:33], off
	s_waitcnt lgkmcnt(0)
	s_cbranch_scc1 .LBB0_193
	s_branch .LBB0_165

.LBB0_199:
	s_lshl_b32 s20, s11, 1
	s_lshl_b32 s21, s3, 1
	v_add_u32_e32 v44, s20, v26
	v_add_u32_e32 v42, s21, v21
	v_ashrrev_i32_e32 v45, 31, v44
	v_ashrrev_i32_e32 v43, 31, v42
	v_lshlrev_b64 v[44:45], 9, v[44:45]
	v_lshlrev_b64 v[42:43], 9, v[42:43]
	v_lshl_add_u64 v[44:45], v[24:25], 0, v[44:45]
	v_lshl_add_u64 v[42:43], v[24:25], 0, v[42:43]
	global_load_dword v200, v[44:45], off
	global_load_dword v201, v[42:43], off
	v_add_u32_e32 v44, s20, v28
	v_add_u32_e32 v42, s21, v23
	v_ashrrev_i32_e32 v45, 31, v44
	v_ashrrev_i32_e32 v43, 31, v42
	v_lshlrev_b64 v[44:45], 9, v[44:45]
	v_lshlrev_b64 v[42:43], 9, v[42:43]
	v_lshl_add_u64 v[44:45], v[24:25], 0, v[44:45]
	v_lshl_add_u64 v[42:43], v[24:25], 0, v[42:43]
	global_load_dword v202, v[44:45], off
	global_load_dword v203, v[42:43], off
	v_add_u32_e32 v44, s20, v30
	v_add_u32_e32 v42, s21, v27
	v_ashrrev_i32_e32 v45, 31, v44
	v_ashrrev_i32_e32 v43, 31, v42
	v_lshlrev_b64 v[44:45], 9, v[44:45]
	v_lshlrev_b64 v[42:43], 9, v[42:43]
	v_lshl_add_u64 v[44:45], v[24:25], 0, v[44:45]
	v_lshl_add_u64 v[42:43], v[24:25], 0, v[42:43]
	global_load_dword v204, v[44:45], off
	global_load_dword v205, v[42:43], off
	v_add_u32_e32 v44, s20, v32
	v_add_u32_e32 v42, s21, v29
	v_ashrrev_i32_e32 v45, 31, v44
	v_ashrrev_i32_e32 v43, 31, v42
	v_lshlrev_b64 v[44:45], 9, v[44:45]
	v_lshlrev_b64 v[42:43], 9, v[42:43]
	v_lshl_add_u64 v[44:45], v[24:25], 0, v[44:45]
	v_lshl_add_u64 v[42:43], v[24:25], 0, v[42:43]
	global_load_dword v206, v[44:45], off
	global_load_dword v207, v[42:43], off
	v_add_u32_e32 v44, s20, v34
	v_add_u32_e32 v42, s21, v31
	v_ashrrev_i32_e32 v45, 31, v44
	v_ashrrev_i32_e32 v43, 31, v42
	v_lshlrev_b64 v[44:45], 9, v[44:45]
	v_lshlrev_b64 v[42:43], 9, v[42:43]
	v_lshl_add_u64 v[44:45], v[24:25], 0, v[44:45]
	v_lshl_add_u64 v[42:43], v[24:25], 0, v[42:43]
	global_load_dword v208, v[44:45], off
	global_load_dword v209, v[42:43], off
	v_add_u32_e32 v44, s20, v36
	v_add_u32_e32 v42, s21, v33
	v_ashrrev_i32_e32 v45, 31, v44
	v_ashrrev_i32_e32 v43, 31, v42
	v_lshlrev_b64 v[44:45], 9, v[44:45]
	v_lshlrev_b64 v[42:43], 9, v[42:43]
	v_lshl_add_u64 v[44:45], v[24:25], 0, v[44:45]
	v_lshl_add_u64 v[42:43], v[24:25], 0, v[42:43]
	global_load_dword v210, v[44:45], off
	global_load_dword v211, v[42:43], off
	v_add_u32_e32 v44, s20, v38
	v_add_u32_e32 v42, s21, v35
	v_ashrrev_i32_e32 v45, 31, v44
	v_ashrrev_i32_e32 v43, 31, v42
	v_lshlrev_b64 v[44:45], 9, v[44:45]
	v_lshlrev_b64 v[42:43], 9, v[42:43]
	v_lshl_add_u64 v[44:45], v[24:25], 0, v[44:45]
	v_lshl_add_u64 v[42:43], v[24:25], 0, v[42:43]
	global_load_dword v212, v[44:45], off
	global_load_dword v213, v[42:43], off
	v_add_u32_e32 v44, s20, v40
	v_add_u32_e32 v42, s21, v37
	v_ashrrev_i32_e32 v45, 31, v44
	v_ashrrev_i32_e32 v43, 31, v42
	v_lshlrev_b64 v[44:45], 9, v[44:45]
	v_lshlrev_b64 v[42:43], 9, v[42:43]
	v_lshl_add_u64 v[44:45], v[24:25], 0, v[44:45]
	v_lshl_add_u64 v[42:43], v[24:25], 0, v[42:43]
	global_load_dword v214, v[44:45], off
	global_load_dword v215, v[42:43], off
	v_add_u32_e32 v39, s21, v5
	v_add_u32_e32 v41, s20, v4
	v_mad_u64_u32 v[42:43], s[24:25], v41, s59, v[6:7]
	v_mad_u64_u32 v[44:45], s[24:25], v39, s59, v[6:7]
	v_add_u32_e32 v39, s21, v7
	v_add_u32_e32 v41, s20, v8
	s_add_i32 s11, s11, 16
	s_add_i32 s3, s3, 16
	s_add_i32 s19, s19, -16
	s_cmp_lg_u32 s19, 0
	s_waitcnt vmcnt(14)
	ds_write_b32 v42, v200
	ds_write_b32 v44, v201
	v_mad_u64_u32 v[42:43], s[24:25], v41, s59, v[6:7]
	v_mad_u64_u32 v[44:45], s[24:25], v39, s59, v[6:7]
	v_add_u32_e32 v39, s21, v9
	v_add_u32_e32 v41, s20, v10
	s_waitcnt vmcnt(12)
	ds_write_b32 v42, v202
	ds_write_b32 v44, v203
	v_mad_u64_u32 v[42:43], s[24:25], v41, s59, v[6:7]
	v_mad_u64_u32 v[44:45], s[24:25], v39, s59, v[6:7]
	v_add_u32_e32 v39, s21, v11
	v_add_u32_e32 v41, s20, v12
	s_waitcnt vmcnt(10)
	ds_write_b32 v42, v204
	ds_write_b32 v44, v205
	v_mad_u64_u32 v[42:43], s[24:25], v41, s59, v[6:7]
	v_mad_u64_u32 v[44:45], s[24:25], v39, s59, v[6:7]
	v_add_u32_e32 v39, s21, v13
	v_add_u32_e32 v41, s20, v14
	s_waitcnt vmcnt(8)
	ds_write_b32 v42, v206
	ds_write_b32 v44, v207
	v_mad_u64_u32 v[42:43], s[24:25], v41, s59, v[6:7]
	v_mad_u64_u32 v[44:45], s[24:25], v39, s59, v[6:7]
	v_add_u32_e32 v39, s21, v15
	v_add_u32_e32 v41, s20, v16
	s_waitcnt vmcnt(6)
	ds_write_b32 v42, v208
	ds_write_b32 v44, v209
	v_mad_u64_u32 v[42:43], s[24:25], v41, s59, v[6:7]
	v_mad_u64_u32 v[44:45], s[24:25], v39, s59, v[6:7]
	v_add_u32_e32 v39, s21, v17
	v_add_u32_e32 v41, s20, v18
	s_waitcnt vmcnt(4)
	ds_write_b32 v42, v210
	ds_write_b32 v44, v211
	v_mad_u64_u32 v[42:43], s[24:25], v41, s59, v[6:7]
	v_mad_u64_u32 v[44:45], s[24:25], v39, s59, v[6:7]
	v_add_u32_e32 v41, s20, v20
	v_add_u32_e32 v39, s21, v19
	s_waitcnt vmcnt(2)
	ds_write_b32 v42, v212
	ds_write_b32 v44, v213
	v_mad_u64_u32 v[42:43], s[20:21], v41, s59, v[6:7]
	v_mad_u64_u32 v[44:45], s[20:21], v39, s59, v[6:7]
	s_waitcnt vmcnt(0)
	ds_write_b32 v42, v214
	ds_write_b32 v44, v215
	s_cbranch_scc1 .LBB0_199
	s_waitcnt lgkmcnt(0)
	ds_read2_b32 v[26:27], v51 offset1:33
	s_waitcnt lgkmcnt(0)
	v_cvt_pk_bf16_f32 v26, v26, v27
	ds_read2_b32 v[28:29], v51 offset0:66 offset1:99
	s_waitcnt lgkmcnt(0)
	v_cvt_pk_bf16_f32 v27, v28, v29
	ds_read2_b32 v[28:29], v51 offset0:132 offset1:165
	s_waitcnt lgkmcnt(0)
	v_cvt_pk_bf16_f32 v28, v28, v29
	ds_read2_b32 v[30:31], v51 offset0:198 offset1:231
	s_waitcnt lgkmcnt(0)
	v_cvt_pk_bf16_f32 v29, v30, v31
	v_add_u32_e32 v30, s2, v50
	s_ashr_i32 s11, s10, 31
	v_ashrrev_i32_e32 v31, 31, v30
	v_lshl_add_u64 v[24:25], s[10:11], 1, v[2:3]
	v_lshlrev_b64 v[30:31], 12, v[30:31]
	v_lshl_add_u64 v[30:31], v[24:25], 0, v[30:31]
	global_store_dwordx4 v[30:31], v[26:29], off
	ds_read2_b32 v[26:27], v51 offset0:8 offset1:41
	s_add_i32 s6, s6, s48
	s_waitcnt lgkmcnt(0)
	v_cvt_pk_bf16_f32 v26, v26, v27
	ds_read2_b32 v[28:29], v51 offset0:74 offset1:107
	s_waitcnt lgkmcnt(0)
	v_cvt_pk_bf16_f32 v27, v28, v29
	ds_read2_b32 v[28:29], v51 offset0:140 offset1:173
	s_waitcnt lgkmcnt(0)
	v_cvt_pk_bf16_f32 v28, v28, v29
	ds_read2_b32 v[30:31], v51 offset0:206 offset1:239
	s_waitcnt lgkmcnt(0)
	v_cvt_pk_bf16_f32 v29, v30, v31
	v_add_u32_e32 v30, s2, v52
	v_ashrrev_i32_e32 v31, 31, v30
	v_lshlrev_b64 v[30:31], 12, v[30:31]
	v_lshl_add_u64 v[30:31], v[24:25], 0, v[30:31]
	global_store_dwordx4 v[30:31], v[26:29], off
	ds_read2_b32 v[26:27], v51 offset0:16 offset1:49
	s_cmp_lt_i32 s6, 64
	s_waitcnt lgkmcnt(0)
	v_cvt_pk_bf16_f32 v26, v26, v27
	ds_read2_b32 v[28:29], v51 offset0:82 offset1:115
	s_waitcnt lgkmcnt(0)
	v_cvt_pk_bf16_f32 v27, v28, v29
	ds_read2_b32 v[28:29], v51 offset0:148 offset1:181
	s_waitcnt lgkmcnt(0)
	v_cvt_pk_bf16_f32 v28, v28, v29
	ds_read2_b32 v[30:31], v51 offset0:214 offset1:247
	s_waitcnt lgkmcnt(0)
	v_cvt_pk_bf16_f32 v29, v30, v31
	v_add_u32_e32 v30, s2, v53
	v_ashrrev_i32_e32 v31, 31, v30
	v_lshlrev_b64 v[30:31], 12, v[30:31]
	v_lshl_add_u64 v[30:31], v[24:25], 0, v[30:31]
	global_store_dwordx4 v[30:31], v[26:29], off
	ds_read2_b32 v[26:27], v51 offset0:24 offset1:57
	s_waitcnt lgkmcnt(0)
	v_cvt_pk_bf16_f32 v26, v26, v27
	ds_read2_b32 v[28:29], v51 offset0:90 offset1:123
	s_waitcnt lgkmcnt(0)
	v_cvt_pk_bf16_f32 v27, v28, v29
	ds_read2_b32 v[28:29], v51 offset0:156 offset1:189
	s_waitcnt lgkmcnt(0)
	v_cvt_pk_bf16_f32 v28, v28, v29
	ds_read2_b32 v[30:31], v51 offset0:222 offset1:255
	s_waitcnt lgkmcnt(0)
	v_cvt_pk_bf16_f32 v29, v30, v31
	v_add_u32_e32 v30, s2, v54
	v_ashrrev_i32_e32 v31, 31, v30
	v_lshlrev_b64 v[30:31], 12, v[30:31]
	v_lshl_add_u64 v[24:25], v[24:25], 0, v[30:31]
	global_store_dwordx4 v[24:25], v[26:29], off
	s_waitcnt lgkmcnt(0)
	s_cbranch_scc1 .LBB0_198

.LBB0_204:
	s_lshl_b32 s17, s11, 1
	s_lshl_b32 s19, s5, 1
	v_add_u32_e32 v44, s17, v26
	v_add_u32_e32 v42, s19, v21
	v_ashrrev_i32_e32 v45, 31, v44
	v_ashrrev_i32_e32 v43, 31, v42
	v_lshlrev_b64 v[48:49], 9, v[44:45]
	v_lshlrev_b64 v[46:47], 9, v[42:43]
	v_lshl_add_u64 v[48:49], v[24:25], 0, v[48:49]
	v_lshl_add_u64 v[44:45], v[44:45], 2, s[2:3]
	v_lshl_add_u64 v[46:47], v[24:25], 0, v[46:47]
	global_load_dword v202, v[48:49], off
	s_nop 0
	global_load_dword v203, v[46:47], off
	v_lshl_add_u64 v[42:43], v[42:43], 2, s[2:3]
	global_load_dword v200, v[44:45], off
	s_nop 0
	global_load_dword v201, v[42:43], off
	v_add_u32_e32 v44, s17, v28
	v_add_u32_e32 v42, s19, v23
	v_ashrrev_i32_e32 v45, 31, v44
	v_ashrrev_i32_e32 v43, 31, v42
	v_lshlrev_b64 v[48:49], 9, v[44:45]
	v_lshlrev_b64 v[46:47], 9, v[42:43]
	v_lshl_add_u64 v[48:49], v[24:25], 0, v[48:49]
	v_lshl_add_u64 v[44:45], v[44:45], 2, s[2:3]
	v_lshl_add_u64 v[46:47], v[24:25], 0, v[46:47]
	global_load_dword v206, v[48:49], off
	s_nop 0
	global_load_dword v207, v[46:47], off
	v_lshl_add_u64 v[42:43], v[42:43], 2, s[2:3]
	global_load_dword v204, v[44:45], off
	s_nop 0
	global_load_dword v205, v[42:43], off
	v_add_u32_e32 v44, s17, v30
	v_add_u32_e32 v42, s19, v27
	v_ashrrev_i32_e32 v45, 31, v44
	v_ashrrev_i32_e32 v43, 31, v42
	v_lshlrev_b64 v[48:49], 9, v[44:45]
	v_lshlrev_b64 v[46:47], 9, v[42:43]
	v_lshl_add_u64 v[48:49], v[24:25], 0, v[48:49]
	v_lshl_add_u64 v[44:45], v[44:45], 2, s[2:3]
	v_lshl_add_u64 v[46:47], v[24:25], 0, v[46:47]
	global_load_dword v210, v[48:49], off
	s_nop 0
	global_load_dword v211, v[46:47], off
	v_lshl_add_u64 v[42:43], v[42:43], 2, s[2:3]
	global_load_dword v208, v[44:45], off
	s_nop 0
	global_load_dword v209, v[42:43], off
	v_add_u32_e32 v44, s17, v32
	v_add_u32_e32 v42, s19, v29
	v_ashrrev_i32_e32 v45, 31, v44
	v_ashrrev_i32_e32 v43, 31, v42
	v_lshlrev_b64 v[48:49], 9, v[44:45]
	v_lshlrev_b64 v[46:47], 9, v[42:43]
	v_lshl_add_u64 v[48:49], v[24:25], 0, v[48:49]
	v_lshl_add_u64 v[44:45], v[44:45], 2, s[2:3]
	v_lshl_add_u64 v[46:47], v[24:25], 0, v[46:47]
	global_load_dword v214, v[48:49], off
	s_nop 0
	global_load_dword v215, v[46:47], off
	v_lshl_add_u64 v[42:43], v[42:43], 2, s[2:3]
	global_load_dword v212, v[44:45], off
	s_nop 0
	global_load_dword v213, v[42:43], off
	v_add_u32_e32 v44, s17, v34
	v_add_u32_e32 v42, s19, v31
	v_ashrrev_i32_e32 v45, 31, v44
	v_ashrrev_i32_e32 v43, 31, v42
	v_lshlrev_b64 v[48:49], 9, v[44:45]
	v_lshlrev_b64 v[46:47], 9, v[42:43]
	v_lshl_add_u64 v[48:49], v[24:25], 0, v[48:49]
	v_lshl_add_u64 v[44:45], v[44:45], 2, s[2:3]
	v_lshl_add_u64 v[46:47], v[24:25], 0, v[46:47]
	global_load_dword v218, v[48:49], off
	s_nop 0
	global_load_dword v219, v[46:47], off
	v_lshl_add_u64 v[42:43], v[42:43], 2, s[2:3]
	global_load_dword v216, v[44:45], off
	s_nop 0
	global_load_dword v217, v[42:43], off
	v_add_u32_e32 v44, s17, v36
	v_add_u32_e32 v42, s19, v33
	v_ashrrev_i32_e32 v45, 31, v44
	v_ashrrev_i32_e32 v43, 31, v42
	v_lshlrev_b64 v[48:49], 9, v[44:45]
	v_lshlrev_b64 v[46:47], 9, v[42:43]
	v_lshl_add_u64 v[48:49], v[24:25], 0, v[48:49]
	v_lshl_add_u64 v[44:45], v[44:45], 2, s[2:3]
	v_lshl_add_u64 v[46:47], v[24:25], 0, v[46:47]
	global_load_dword v222, v[48:49], off
	s_nop 0
	global_load_dword v223, v[46:47], off
	v_lshl_add_u64 v[42:43], v[42:43], 2, s[2:3]
	global_load_dword v220, v[44:45], off
	s_nop 0
	global_load_dword v221, v[42:43], off
	v_add_u32_e32 v44, s17, v38
	v_add_u32_e32 v42, s19, v35
	v_ashrrev_i32_e32 v45, 31, v44
	v_ashrrev_i32_e32 v43, 31, v42
	v_lshlrev_b64 v[48:49], 9, v[44:45]
	v_lshlrev_b64 v[46:47], 9, v[42:43]
	v_lshl_add_u64 v[48:49], v[24:25], 0, v[48:49]
	v_lshl_add_u64 v[44:45], v[44:45], 2, s[2:3]
	v_lshl_add_u64 v[46:47], v[24:25], 0, v[46:47]
	global_load_dword v226, v[48:49], off
	s_nop 0
	global_load_dword v227, v[46:47], off
	v_lshl_add_u64 v[42:43], v[42:43], 2, s[2:3]
	global_load_dword v224, v[44:45], off
	s_nop 0
	global_load_dword v225, v[42:43], off
	v_add_u32_e32 v44, s17, v40
	v_add_u32_e32 v42, s19, v37
	v_ashrrev_i32_e32 v45, 31, v44
	v_ashrrev_i32_e32 v43, 31, v42
	v_lshlrev_b64 v[48:49], 9, v[44:45]
	v_lshlrev_b64 v[46:47], 9, v[42:43]
	v_lshl_add_u64 v[48:49], v[24:25], 0, v[48:49]
	v_lshl_add_u64 v[44:45], v[44:45], 2, s[2:3]
	v_lshl_add_u64 v[46:47], v[24:25], 0, v[46:47]
	global_load_dword v230, v[48:49], off
	s_nop 0
	global_load_dword v231, v[46:47], off
	v_lshl_add_u64 v[42:43], v[42:43], 2, s[2:3]
	global_load_dword v228, v[44:45], off
	s_nop 0
	global_load_dword v229, v[42:43], off
	v_add_u32_e32 v41, s17, v4
	v_add_u32_e32 v39, s19, v5
	v_mad_u64_u32 v[46:47], s[20:21], v39, s59, v[6:7]
	v_add_u32_e32 v39, s19, v7
	s_add_i32 s11, s11, 16
	s_add_i32 s5, s5, 16
	s_add_i32 s16, s16, -16
	s_cmp_lg_u32 s16, 0
	s_waitcnt vmcnt(28)
	v_pk_mul_f32 v[42:43], v[202:203], v[200:201]
	v_mad_u64_u32 v[44:45], s[20:21], v41, s59, v[6:7]
	ds_write_b32 v44, v42
	ds_write_b32 v46, v43
	v_add_u32_e32 v41, s17, v8
	v_mad_u64_u32 v[46:47], s[20:21], v39, s59, v[6:7]
	v_add_u32_e32 v39, s19, v9
	s_waitcnt vmcnt(24)
	v_pk_mul_f32 v[42:43], v[206:207], v[204:205]
	v_mad_u64_u32 v[44:45], s[20:21], v41, s59, v[6:7]
	ds_write_b32 v44, v42
	ds_write_b32 v46, v43
	v_add_u32_e32 v41, s17, v10
	v_mad_u64_u32 v[46:47], s[20:21], v39, s59, v[6:7]
	v_add_u32_e32 v39, s19, v11
	s_waitcnt vmcnt(20)
	v_pk_mul_f32 v[42:43], v[210:211], v[208:209]
	v_mad_u64_u32 v[44:45], s[20:21], v41, s59, v[6:7]
	ds_write_b32 v44, v42
	ds_write_b32 v46, v43
	v_add_u32_e32 v41, s17, v12
	v_mad_u64_u32 v[46:47], s[20:21], v39, s59, v[6:7]
	v_add_u32_e32 v39, s19, v13
	s_waitcnt vmcnt(16)
	v_pk_mul_f32 v[42:43], v[214:215], v[212:213]
	v_mad_u64_u32 v[44:45], s[20:21], v41, s59, v[6:7]
	ds_write_b32 v44, v42
	ds_write_b32 v46, v43
	v_add_u32_e32 v41, s17, v14
	v_mad_u64_u32 v[46:47], s[20:21], v39, s59, v[6:7]
	v_add_u32_e32 v39, s19, v15
	s_waitcnt vmcnt(12)
	v_pk_mul_f32 v[42:43], v[218:219], v[216:217]
	v_mad_u64_u32 v[44:45], s[20:21], v41, s59, v[6:7]
	ds_write_b32 v44, v42
	ds_write_b32 v46, v43
	v_add_u32_e32 v41, s17, v16
	v_mad_u64_u32 v[46:47], s[20:21], v39, s59, v[6:7]
	v_add_u32_e32 v39, s19, v17
	s_waitcnt vmcnt(8)
	v_pk_mul_f32 v[42:43], v[222:223], v[220:221]
	v_mad_u64_u32 v[44:45], s[20:21], v41, s59, v[6:7]
	ds_write_b32 v44, v42
	ds_write_b32 v46, v43
	v_add_u32_e32 v41, s17, v18
	v_mad_u64_u32 v[46:47], s[20:21], v39, s59, v[6:7]
	v_add_u32_e32 v39, s19, v19
	s_waitcnt vmcnt(4)
	v_pk_mul_f32 v[42:43], v[226:227], v[224:225]
	v_mad_u64_u32 v[44:45], s[20:21], v41, s59, v[6:7]
	ds_write_b32 v44, v42
	ds_write_b32 v46, v43
	v_add_u32_e32 v41, s17, v20
	v_mad_u64_u32 v[46:47], s[20:21], v39, s59, v[6:7]
	s_waitcnt vmcnt(0)
	v_pk_mul_f32 v[42:43], v[230:231], v[228:229]
	v_mad_u64_u32 v[44:45], s[20:21], v41, s59, v[6:7]
	ds_write_b32 v44, v42
	ds_write_b32 v46, v43
	s_cbranch_scc1 .LBB0_204
	s_waitcnt lgkmcnt(0)
	ds_read2_b32 v[26:27], v51 offset1:33
	s_waitcnt lgkmcnt(0)
	v_cvt_pk_bf16_f32 v26, v26, v27
	ds_read2_b32 v[28:29], v51 offset0:66 offset1:99
	s_waitcnt lgkmcnt(0)
	v_cvt_pk_bf16_f32 v27, v28, v29
	ds_read2_b32 v[28:29], v51 offset0:132 offset1:165
	s_waitcnt lgkmcnt(0)
	v_cvt_pk_bf16_f32 v28, v28, v29
	ds_read2_b32 v[30:31], v51 offset0:198 offset1:231
	s_waitcnt lgkmcnt(0)
	v_cvt_pk_bf16_f32 v29, v30, v31
	v_add_u32_e32 v30, s4, v50
	s_ashr_i32 s11, s10, 31
	v_ashrrev_i32_e32 v31, 31, v30
	v_lshl_add_u64 v[24:25], s[10:11], 1, v[2:3]
	v_lshlrev_b64 v[30:31], 12, v[30:31]
	v_lshl_add_u64 v[30:31], v[24:25], 0, v[30:31]
	global_store_dwordx4 v[30:31], v[26:29], off
	ds_read2_b32 v[26:27], v51 offset0:8 offset1:41
	s_add_i32 s18, s18, s48
	s_waitcnt lgkmcnt(0)
	v_cvt_pk_bf16_f32 v26, v26, v27
	ds_read2_b32 v[28:29], v51 offset0:74 offset1:107
	s_waitcnt lgkmcnt(0)
	v_cvt_pk_bf16_f32 v27, v28, v29
	ds_read2_b32 v[28:29], v51 offset0:140 offset1:173
	s_waitcnt lgkmcnt(0)
	v_cvt_pk_bf16_f32 v28, v28, v29
	ds_read2_b32 v[30:31], v51 offset0:206 offset1:239
	s_waitcnt lgkmcnt(0)
	v_cvt_pk_bf16_f32 v29, v30, v31
	v_add_u32_e32 v30, s4, v52
	v_ashrrev_i32_e32 v31, 31, v30
	v_lshlrev_b64 v[30:31], 12, v[30:31]
	v_lshl_add_u64 v[30:31], v[24:25], 0, v[30:31]
	global_store_dwordx4 v[30:31], v[26:29], off
	ds_read2_b32 v[26:27], v51 offset0:16 offset1:49
	s_cmp_lt_i32 s18, 64
	s_waitcnt lgkmcnt(0)
	v_cvt_pk_bf16_f32 v26, v26, v27
	ds_read2_b32 v[28:29], v51 offset0:82 offset1:115
	s_waitcnt lgkmcnt(0)
	v_cvt_pk_bf16_f32 v27, v28, v29
	ds_read2_b32 v[28:29], v51 offset0:148 offset1:181
	s_waitcnt lgkmcnt(0)
	v_cvt_pk_bf16_f32 v28, v28, v29
	ds_read2_b32 v[30:31], v51 offset0:214 offset1:247
	s_waitcnt lgkmcnt(0)
	v_cvt_pk_bf16_f32 v29, v30, v31
	v_add_u32_e32 v30, s4, v53
	v_ashrrev_i32_e32 v31, 31, v30
	v_lshlrev_b64 v[30:31], 12, v[30:31]
	v_lshl_add_u64 v[30:31], v[24:25], 0, v[30:31]
	global_store_dwordx4 v[30:31], v[26:29], off
	ds_read2_b32 v[26:27], v51 offset0:24 offset1:57
	s_waitcnt lgkmcnt(0)
	v_cvt_pk_bf16_f32 v26, v26, v27
	ds_read2_b32 v[28:29], v51 offset0:90 offset1:123
	s_waitcnt lgkmcnt(0)
	v_cvt_pk_bf16_f32 v27, v28, v29
	ds_read2_b32 v[28:29], v51 offset0:156 offset1:189
	s_waitcnt lgkmcnt(0)
	v_cvt_pk_bf16_f32 v28, v28, v29
	ds_read2_b32 v[30:31], v51 offset0:222 offset1:255
	s_waitcnt lgkmcnt(0)
	v_cvt_pk_bf16_f32 v29, v30, v31
	v_add_u32_e32 v30, s4, v54
	v_ashrrev_i32_e32 v31, 31, v30
	v_lshlrev_b64 v[30:31], 12, v[30:31]
	v_lshl_add_u64 v[24:25], v[24:25], 0, v[30:31]
	global_store_dwordx4 v[24:25], v[26:29], off
	s_waitcnt lgkmcnt(0)
	s_cbranch_scc1 .LBB0_203

.LBB0_212:
	s_lshl_b32 s10, s1, 1
	s_lshl_b32 s11, s3, 1
	v_add_u32_e32 v44, s10, v26
	v_add_u32_e32 v42, s11, v21
	v_ashrrev_i32_e32 v45, 31, v44
	v_ashrrev_i32_e32 v43, 31, v42
	v_lshlrev_b64 v[44:45], 12, v[44:45]
	v_lshlrev_b64 v[42:43], 12, v[42:43]
	v_lshl_add_u64 v[44:45], v[24:25], 0, v[44:45]
	v_lshl_add_u64 v[42:43], v[24:25], 0, v[42:43]
	global_load_dword v200, v[44:45], off
	global_load_dword v201, v[42:43], off
	v_add_u32_e32 v44, s10, v28
	v_add_u32_e32 v42, s11, v23
	v_ashrrev_i32_e32 v45, 31, v44
	v_ashrrev_i32_e32 v43, 31, v42
	v_lshlrev_b64 v[44:45], 12, v[44:45]
	v_lshlrev_b64 v[42:43], 12, v[42:43]
	v_lshl_add_u64 v[44:45], v[24:25], 0, v[44:45]
	v_lshl_add_u64 v[42:43], v[24:25], 0, v[42:43]
	global_load_dword v202, v[44:45], off
	global_load_dword v203, v[42:43], off
	v_add_u32_e32 v44, s10, v30
	v_add_u32_e32 v42, s11, v27
	v_ashrrev_i32_e32 v45, 31, v44
	v_ashrrev_i32_e32 v43, 31, v42
	v_lshlrev_b64 v[44:45], 12, v[44:45]
	v_lshlrev_b64 v[42:43], 12, v[42:43]
	v_lshl_add_u64 v[44:45], v[24:25], 0, v[44:45]
	v_lshl_add_u64 v[42:43], v[24:25], 0, v[42:43]
	global_load_dword v204, v[44:45], off
	global_load_dword v205, v[42:43], off
	v_add_u32_e32 v44, s10, v32
	v_add_u32_e32 v42, s11, v29
	v_ashrrev_i32_e32 v45, 31, v44
	v_ashrrev_i32_e32 v43, 31, v42
	v_lshlrev_b64 v[44:45], 12, v[44:45]
	v_lshlrev_b64 v[42:43], 12, v[42:43]
	v_lshl_add_u64 v[44:45], v[24:25], 0, v[44:45]
	v_lshl_add_u64 v[42:43], v[24:25], 0, v[42:43]
	global_load_dword v206, v[44:45], off
	global_load_dword v207, v[42:43], off
	v_add_u32_e32 v44, s10, v34
	v_add_u32_e32 v42, s11, v31
	v_ashrrev_i32_e32 v45, 31, v44
	v_ashrrev_i32_e32 v43, 31, v42
	v_lshlrev_b64 v[44:45], 12, v[44:45]
	v_lshlrev_b64 v[42:43], 12, v[42:43]
	v_lshl_add_u64 v[44:45], v[24:25], 0, v[44:45]
	v_lshl_add_u64 v[42:43], v[24:25], 0, v[42:43]
	global_load_dword v208, v[44:45], off
	global_load_dword v209, v[42:43], off
	v_add_u32_e32 v44, s10, v36
	v_add_u32_e32 v42, s11, v33
	v_ashrrev_i32_e32 v45, 31, v44
	v_ashrrev_i32_e32 v43, 31, v42
	v_lshlrev_b64 v[44:45], 12, v[44:45]
	v_lshlrev_b64 v[42:43], 12, v[42:43]
	v_lshl_add_u64 v[44:45], v[24:25], 0, v[44:45]
	v_lshl_add_u64 v[42:43], v[24:25], 0, v[42:43]
	global_load_dword v210, v[44:45], off
	global_load_dword v211, v[42:43], off
	v_add_u32_e32 v44, s10, v38
	v_add_u32_e32 v42, s11, v35
	v_ashrrev_i32_e32 v45, 31, v44
	v_ashrrev_i32_e32 v43, 31, v42
	v_lshlrev_b64 v[44:45], 12, v[44:45]
	v_lshlrev_b64 v[42:43], 12, v[42:43]
	v_lshl_add_u64 v[44:45], v[24:25], 0, v[44:45]
	v_lshl_add_u64 v[42:43], v[24:25], 0, v[42:43]
	global_load_dword v212, v[44:45], off
	global_load_dword v213, v[42:43], off
	v_add_u32_e32 v44, s10, v40
	v_add_u32_e32 v42, s11, v37
	v_ashrrev_i32_e32 v45, 31, v44
	v_ashrrev_i32_e32 v43, 31, v42
	v_lshlrev_b64 v[44:45], 12, v[44:45]
	v_lshlrev_b64 v[42:43], 12, v[42:43]
	v_lshl_add_u64 v[44:45], v[24:25], 0, v[44:45]
	v_lshl_add_u64 v[42:43], v[24:25], 0, v[42:43]
	global_load_dword v214, v[44:45], off
	global_load_dword v215, v[42:43], off
	v_add_u32_e32 v39, s11, v5
	v_add_u32_e32 v41, s10, v4
	v_mad_u64_u32 v[42:43], s[16:17], v41, s59, v[6:7]
	v_mad_u64_u32 v[44:45], s[16:17], v39, s59, v[6:7]
	v_add_u32_e32 v39, s11, v7
	v_add_u32_e32 v41, s10, v8
	s_add_i32 s1, s1, 16
	s_add_i32 s3, s3, 16
	s_add_i32 s6, s6, -16
	s_cmp_lg_u32 s6, 0
	s_waitcnt vmcnt(14)
	ds_write_b32 v42, v200
	ds_write_b32 v44, v201
	v_mad_u64_u32 v[42:43], s[16:17], v41, s59, v[6:7]
	v_mad_u64_u32 v[44:45], s[16:17], v39, s59, v[6:7]
	v_add_u32_e32 v39, s11, v9
	v_add_u32_e32 v41, s10, v10
	s_waitcnt vmcnt(12)
	ds_write_b32 v42, v202
	ds_write_b32 v44, v203
	v_mad_u64_u32 v[42:43], s[16:17], v41, s59, v[6:7]
	v_mad_u64_u32 v[44:45], s[16:17], v39, s59, v[6:7]
	v_add_u32_e32 v39, s11, v11
	v_add_u32_e32 v41, s10, v12
	s_waitcnt vmcnt(10)
	ds_write_b32 v42, v204
	ds_write_b32 v44, v205
	v_mad_u64_u32 v[42:43], s[16:17], v41, s59, v[6:7]
	v_mad_u64_u32 v[44:45], s[16:17], v39, s59, v[6:7]
	v_add_u32_e32 v39, s11, v13
	v_add_u32_e32 v41, s10, v14
	s_waitcnt vmcnt(8)
	ds_write_b32 v42, v206
	ds_write_b32 v44, v207
	v_mad_u64_u32 v[42:43], s[16:17], v41, s59, v[6:7]
	v_mad_u64_u32 v[44:45], s[16:17], v39, s59, v[6:7]
	v_add_u32_e32 v39, s11, v15
	v_add_u32_e32 v41, s10, v16
	s_waitcnt vmcnt(6)
	ds_write_b32 v42, v208
	ds_write_b32 v44, v209
	v_mad_u64_u32 v[42:43], s[16:17], v41, s59, v[6:7]
	v_mad_u64_u32 v[44:45], s[16:17], v39, s59, v[6:7]
	v_add_u32_e32 v39, s11, v17
	v_add_u32_e32 v41, s10, v18
	s_waitcnt vmcnt(4)
	ds_write_b32 v42, v210
	ds_write_b32 v44, v211
	v_mad_u64_u32 v[42:43], s[16:17], v41, s59, v[6:7]
	v_mad_u64_u32 v[44:45], s[16:17], v39, s59, v[6:7]
	v_add_u32_e32 v41, s10, v20
	v_add_u32_e32 v39, s11, v19
	s_waitcnt vmcnt(2)
	ds_write_b32 v42, v212
	ds_write_b32 v44, v213
	v_mad_u64_u32 v[42:43], s[10:11], v41, s59, v[6:7]
	v_mad_u64_u32 v[44:45], s[10:11], v39, s59, v[6:7]
	s_waitcnt vmcnt(0)
	ds_write_b32 v42, v214
	ds_write_b32 v44, v215
	s_cbranch_scc1 .LBB0_212
	s_waitcnt lgkmcnt(0)
	ds_read2_b32 v[26:27], v51 offset1:33
	s_waitcnt lgkmcnt(0)
	v_cvt_pk_bf16_f32 v26, v26, v27
	ds_read2_b32 v[28:29], v51 offset0:66 offset1:99
	s_waitcnt lgkmcnt(0)
	v_cvt_pk_bf16_f32 v27, v28, v29
	ds_read2_b32 v[28:29], v51 offset0:132 offset1:165
	s_waitcnt lgkmcnt(0)
	v_cvt_pk_bf16_f32 v28, v28, v29
	ds_read2_b32 v[30:31], v51 offset0:198 offset1:231
	s_waitcnt lgkmcnt(0)
	v_cvt_pk_bf16_f32 v29, v30, v31
	v_add_u32_e32 v30, s0, v50
	s_ashr_i32 s3, s2, 31
	v_ashrrev_i32_e32 v31, 31, v30
	v_lshl_add_u64 v[24:25], s[2:3], 1, v[2:3]
	v_lshlrev_b64 v[30:31], 8, v[30:31]
	v_lshl_add_u64 v[30:31], v[24:25], 0, v[30:31]
	global_store_dwordx4 v[30:31], v[26:29], off
	ds_read2_b32 v[26:27], v51 offset0:8 offset1:41
	s_add_i32 s5, s5, s48
	s_waitcnt lgkmcnt(0)
	v_cvt_pk_bf16_f32 v26, v26, v27
	ds_read2_b32 v[28:29], v51 offset0:74 offset1:107
	s_waitcnt lgkmcnt(0)
	v_cvt_pk_bf16_f32 v27, v28, v29
	ds_read2_b32 v[28:29], v51 offset0:140 offset1:173
	s_waitcnt lgkmcnt(0)
	v_cvt_pk_bf16_f32 v28, v28, v29
	ds_read2_b32 v[30:31], v51 offset0:206 offset1:239
	s_waitcnt lgkmcnt(0)
	v_cvt_pk_bf16_f32 v29, v30, v31
	v_add_u32_e32 v30, s0, v52
	v_ashrrev_i32_e32 v31, 31, v30
	v_lshlrev_b64 v[30:31], 8, v[30:31]
	v_lshl_add_u64 v[30:31], v[24:25], 0, v[30:31]
	global_store_dwordx4 v[30:31], v[26:29], off
	ds_read2_b32 v[26:27], v51 offset0:16 offset1:49
	s_cmp_lt_i32 s5, 64
	s_waitcnt lgkmcnt(0)
	v_cvt_pk_bf16_f32 v26, v26, v27
	ds_read2_b32 v[28:29], v51 offset0:82 offset1:115
	s_waitcnt lgkmcnt(0)
	v_cvt_pk_bf16_f32 v27, v28, v29
	ds_read2_b32 v[28:29], v51 offset0:148 offset1:181
	s_waitcnt lgkmcnt(0)
	v_cvt_pk_bf16_f32 v28, v28, v29
	ds_read2_b32 v[30:31], v51 offset0:214 offset1:247
	s_waitcnt lgkmcnt(0)
	v_cvt_pk_bf16_f32 v29, v30, v31
	v_add_u32_e32 v30, s0, v53
	v_ashrrev_i32_e32 v31, 31, v30
	v_lshlrev_b64 v[30:31], 8, v[30:31]
	v_lshl_add_u64 v[30:31], v[24:25], 0, v[30:31]
	global_store_dwordx4 v[30:31], v[26:29], off
	ds_read2_b32 v[26:27], v51 offset0:24 offset1:57
	s_waitcnt lgkmcnt(0)
	v_cvt_pk_bf16_f32 v26, v26, v27
	ds_read2_b32 v[28:29], v51 offset0:90 offset1:123
	s_waitcnt lgkmcnt(0)
	v_cvt_pk_bf16_f32 v27, v28, v29
	ds_read2_b32 v[28:29], v51 offset0:156 offset1:189
	s_waitcnt lgkmcnt(0)
	v_cvt_pk_bf16_f32 v28, v28, v29
	ds_read2_b32 v[30:31], v51 offset0:222 offset1:255
	s_waitcnt lgkmcnt(0)
	v_cvt_pk_bf16_f32 v29, v30, v31
	v_add_u32_e32 v30, s0, v54
	v_ashrrev_i32_e32 v31, 31, v30
	v_lshlrev_b64 v[30:31], 8, v[30:31]
	v_lshl_add_u64 v[24:25], v[24:25], 0, v[30:31]
	global_store_dwordx4 v[24:25], v[26:29], off
	s_waitcnt lgkmcnt(0)
	s_cbranch_scc1 .LBB0_211

.LBB0_217:
	s_lshl_b32 s10, s1, 1
	s_lshl_b32 s11, s3, 1
	v_add_u32_e32 v44, s10, v26
	v_add_u32_e32 v42, s11, v21
	v_ashrrev_i32_e32 v45, 31, v44
	v_ashrrev_i32_e32 v43, 31, v42
	v_lshlrev_b64 v[44:45], 12, v[44:45]
	v_lshlrev_b64 v[42:43], 12, v[42:43]
	v_lshl_add_u64 v[44:45], v[24:25], 0, v[44:45]
	v_lshl_add_u64 v[42:43], v[24:25], 0, v[42:43]
	global_load_dword v200, v[44:45], off
	global_load_dword v201, v[42:43], off
	v_add_u32_e32 v44, s10, v28
	v_add_u32_e32 v42, s11, v23
	v_ashrrev_i32_e32 v45, 31, v44
	v_ashrrev_i32_e32 v43, 31, v42
	v_lshlrev_b64 v[44:45], 12, v[44:45]
	v_lshlrev_b64 v[42:43], 12, v[42:43]
	v_lshl_add_u64 v[44:45], v[24:25], 0, v[44:45]
	v_lshl_add_u64 v[42:43], v[24:25], 0, v[42:43]
	global_load_dword v202, v[44:45], off
	global_load_dword v203, v[42:43], off
	v_add_u32_e32 v44, s10, v30
	v_add_u32_e32 v42, s11, v27
	v_ashrrev_i32_e32 v45, 31, v44
	v_ashrrev_i32_e32 v43, 31, v42
	v_lshlrev_b64 v[44:45], 12, v[44:45]
	v_lshlrev_b64 v[42:43], 12, v[42:43]
	v_lshl_add_u64 v[44:45], v[24:25], 0, v[44:45]
	v_lshl_add_u64 v[42:43], v[24:25], 0, v[42:43]
	global_load_dword v204, v[44:45], off
	global_load_dword v205, v[42:43], off
	v_add_u32_e32 v44, s10, v32
	v_add_u32_e32 v42, s11, v29
	v_ashrrev_i32_e32 v45, 31, v44
	v_ashrrev_i32_e32 v43, 31, v42
	v_lshlrev_b64 v[44:45], 12, v[44:45]
	v_lshlrev_b64 v[42:43], 12, v[42:43]
	v_lshl_add_u64 v[44:45], v[24:25], 0, v[44:45]
	v_lshl_add_u64 v[42:43], v[24:25], 0, v[42:43]
	global_load_dword v206, v[44:45], off
	global_load_dword v207, v[42:43], off
	v_add_u32_e32 v44, s10, v34
	v_add_u32_e32 v42, s11, v31
	v_ashrrev_i32_e32 v45, 31, v44
	v_ashrrev_i32_e32 v43, 31, v42
	v_lshlrev_b64 v[44:45], 12, v[44:45]
	v_lshlrev_b64 v[42:43], 12, v[42:43]
	v_lshl_add_u64 v[44:45], v[24:25], 0, v[44:45]
	v_lshl_add_u64 v[42:43], v[24:25], 0, v[42:43]
	global_load_dword v208, v[44:45], off
	global_load_dword v209, v[42:43], off
	v_add_u32_e32 v44, s10, v36
	v_add_u32_e32 v42, s11, v33
	v_ashrrev_i32_e32 v45, 31, v44
	v_ashrrev_i32_e32 v43, 31, v42
	v_lshlrev_b64 v[44:45], 12, v[44:45]
	v_lshlrev_b64 v[42:43], 12, v[42:43]
	v_lshl_add_u64 v[44:45], v[24:25], 0, v[44:45]
	v_lshl_add_u64 v[42:43], v[24:25], 0, v[42:43]
	global_load_dword v210, v[44:45], off
	global_load_dword v211, v[42:43], off
	v_add_u32_e32 v44, s10, v38
	v_add_u32_e32 v42, s11, v35
	v_ashrrev_i32_e32 v45, 31, v44
	v_ashrrev_i32_e32 v43, 31, v42
	v_lshlrev_b64 v[44:45], 12, v[44:45]
	v_lshlrev_b64 v[42:43], 12, v[42:43]
	v_lshl_add_u64 v[44:45], v[24:25], 0, v[44:45]
	v_lshl_add_u64 v[42:43], v[24:25], 0, v[42:43]
	global_load_dword v212, v[44:45], off
	global_load_dword v213, v[42:43], off
	v_add_u32_e32 v44, s10, v40
	v_add_u32_e32 v42, s11, v37
	v_ashrrev_i32_e32 v45, 31, v44
	v_ashrrev_i32_e32 v43, 31, v42
	v_lshlrev_b64 v[44:45], 12, v[44:45]
	v_lshlrev_b64 v[42:43], 12, v[42:43]
	v_lshl_add_u64 v[44:45], v[24:25], 0, v[44:45]
	v_lshl_add_u64 v[42:43], v[24:25], 0, v[42:43]
	global_load_dword v214, v[44:45], off
	global_load_dword v215, v[42:43], off
	v_add_u32_e32 v39, s11, v5
	v_add_u32_e32 v41, s10, v4
	v_mad_u64_u32 v[42:43], s[16:17], v41, s59, v[6:7]
	v_mad_u64_u32 v[44:45], s[16:17], v39, s59, v[6:7]
	v_add_u32_e32 v39, s11, v7
	v_add_u32_e32 v41, s10, v8
	s_add_i32 s1, s1, 16
	s_add_i32 s3, s3, 16
	s_add_i32 s6, s6, -16
	s_cmp_lg_u32 s6, 0
	s_waitcnt vmcnt(14)
	ds_write_b32 v42, v200
	ds_write_b32 v44, v201
	v_mad_u64_u32 v[42:43], s[16:17], v41, s59, v[6:7]
	v_mad_u64_u32 v[44:45], s[16:17], v39, s59, v[6:7]
	v_add_u32_e32 v39, s11, v9
	v_add_u32_e32 v41, s10, v10
	s_waitcnt vmcnt(12)
	ds_write_b32 v42, v202
	ds_write_b32 v44, v203
	v_mad_u64_u32 v[42:43], s[16:17], v41, s59, v[6:7]
	v_mad_u64_u32 v[44:45], s[16:17], v39, s59, v[6:7]
	v_add_u32_e32 v39, s11, v11
	v_add_u32_e32 v41, s10, v12
	s_waitcnt vmcnt(10)
	ds_write_b32 v42, v204
	ds_write_b32 v44, v205
	v_mad_u64_u32 v[42:43], s[16:17], v41, s59, v[6:7]
	v_mad_u64_u32 v[44:45], s[16:17], v39, s59, v[6:7]
	v_add_u32_e32 v39, s11, v13
	v_add_u32_e32 v41, s10, v14
	s_waitcnt vmcnt(8)
	ds_write_b32 v42, v206
	ds_write_b32 v44, v207
	v_mad_u64_u32 v[42:43], s[16:17], v41, s59, v[6:7]
	v_mad_u64_u32 v[44:45], s[16:17], v39, s59, v[6:7]
	v_add_u32_e32 v39, s11, v15
	v_add_u32_e32 v41, s10, v16
	s_waitcnt vmcnt(6)
	ds_write_b32 v42, v208
	ds_write_b32 v44, v209
	v_mad_u64_u32 v[42:43], s[16:17], v41, s59, v[6:7]
	v_mad_u64_u32 v[44:45], s[16:17], v39, s59, v[6:7]
	v_add_u32_e32 v39, s11, v17
	v_add_u32_e32 v41, s10, v18
	s_waitcnt vmcnt(4)
	ds_write_b32 v42, v210
	ds_write_b32 v44, v211
	v_mad_u64_u32 v[42:43], s[16:17], v41, s59, v[6:7]
	v_mad_u64_u32 v[44:45], s[16:17], v39, s59, v[6:7]
	v_add_u32_e32 v41, s10, v20
	v_add_u32_e32 v39, s11, v19
	s_waitcnt vmcnt(2)
	ds_write_b32 v42, v212
	ds_write_b32 v44, v213
	v_mad_u64_u32 v[42:43], s[10:11], v41, s59, v[6:7]
	v_mad_u64_u32 v[44:45], s[10:11], v39, s59, v[6:7]
	s_waitcnt vmcnt(0)
	ds_write_b32 v42, v214
	ds_write_b32 v44, v215
	s_cbranch_scc1 .LBB0_217
	s_waitcnt lgkmcnt(0)
	ds_read2_b32 v[26:27], v51 offset1:33
	s_waitcnt lgkmcnt(0)
	v_cvt_pk_bf16_f32 v26, v26, v27
	ds_read2_b32 v[28:29], v51 offset0:66 offset1:99
	s_waitcnt lgkmcnt(0)
	v_cvt_pk_bf16_f32 v27, v28, v29
	ds_read2_b32 v[28:29], v51 offset0:132 offset1:165
	s_waitcnt lgkmcnt(0)
	v_cvt_pk_bf16_f32 v28, v28, v29
	ds_read2_b32 v[30:31], v51 offset0:198 offset1:231
	s_waitcnt lgkmcnt(0)
	v_cvt_pk_bf16_f32 v29, v30, v31
	v_add_u32_e32 v30, s0, v50
	s_ashr_i32 s3, s2, 31
	v_ashrrev_i32_e32 v31, 31, v30
	v_lshl_add_u64 v[24:25], s[2:3], 1, v[2:3]
	v_lshlrev_b64 v[30:31], 11, v[30:31]
	v_lshl_add_u64 v[30:31], v[24:25], 0, v[30:31]
	global_store_dwordx4 v[30:31], v[26:29], off
	ds_read2_b32 v[26:27], v51 offset0:8 offset1:41
	s_add_i32 s5, s5, s48
	s_waitcnt lgkmcnt(0)
	v_cvt_pk_bf16_f32 v26, v26, v27
	ds_read2_b32 v[28:29], v51 offset0:74 offset1:107
	s_waitcnt lgkmcnt(0)
	v_cvt_pk_bf16_f32 v27, v28, v29
	ds_read2_b32 v[28:29], v51 offset0:140 offset1:173
	s_waitcnt lgkmcnt(0)
	v_cvt_pk_bf16_f32 v28, v28, v29
	ds_read2_b32 v[30:31], v51 offset0:206 offset1:239
	s_waitcnt lgkmcnt(0)
	v_cvt_pk_bf16_f32 v29, v30, v31
	v_add_u32_e32 v30, s0, v52
	v_ashrrev_i32_e32 v31, 31, v30
	v_lshlrev_b64 v[30:31], 11, v[30:31]
	v_lshl_add_u64 v[30:31], v[24:25], 0, v[30:31]
	global_store_dwordx4 v[30:31], v[26:29], off
	ds_read2_b32 v[26:27], v51 offset0:16 offset1:49
	s_cmpk_lt_i32 s5, 0x200
	s_waitcnt lgkmcnt(0)
	v_cvt_pk_bf16_f32 v26, v26, v27
	ds_read2_b32 v[28:29], v51 offset0:82 offset1:115
	s_waitcnt lgkmcnt(0)
	v_cvt_pk_bf16_f32 v27, v28, v29
	ds_read2_b32 v[28:29], v51 offset0:148 offset1:181
	s_waitcnt lgkmcnt(0)
	v_cvt_pk_bf16_f32 v28, v28, v29
	ds_read2_b32 v[30:31], v51 offset0:214 offset1:247
	s_waitcnt lgkmcnt(0)
	v_cvt_pk_bf16_f32 v29, v30, v31
	v_add_u32_e32 v30, s0, v53
	v_ashrrev_i32_e32 v31, 31, v30
	v_lshlrev_b64 v[30:31], 11, v[30:31]
	v_lshl_add_u64 v[30:31], v[24:25], 0, v[30:31]
	global_store_dwordx4 v[30:31], v[26:29], off
	ds_read2_b32 v[26:27], v51 offset0:24 offset1:57
	s_waitcnt lgkmcnt(0)
	v_cvt_pk_bf16_f32 v26, v26, v27
	ds_read2_b32 v[28:29], v51 offset0:90 offset1:123
	s_waitcnt lgkmcnt(0)
	v_cvt_pk_bf16_f32 v27, v28, v29
	ds_read2_b32 v[28:29], v51 offset0:156 offset1:189
	s_waitcnt lgkmcnt(0)
	v_cvt_pk_bf16_f32 v28, v28, v29
	ds_read2_b32 v[30:31], v51 offset0:222 offset1:255
	s_waitcnt lgkmcnt(0)
	v_cvt_pk_bf16_f32 v29, v30, v31
	v_add_u32_e32 v30, s0, v54
	v_ashrrev_i32_e32 v31, 31, v30
	v_lshlrev_b64 v[30:31], 11, v[30:31]
	v_lshl_add_u64 v[24:25], v[24:25], 0, v[30:31]
	global_store_dwordx4 v[24:25], v[26:29], off
	s_waitcnt lgkmcnt(0)
	s_cbranch_scc1 .LBB0_216

.LBB0_222:
	s_lshl_b32 s6, s3, 1
	s_lshl_b32 s10, s1, 1
	v_add_u32_e32 v42, s6, v24
	v_add_u32_e32 v40, s10, v21
	v_ashrrev_i32_e32 v43, 31, v42
	v_ashrrev_i32_e32 v41, 31, v40
	v_lshlrev_b64 v[42:43], 14, v[42:43]
	v_lshlrev_b64 v[40:41], 14, v[40:41]
	v_lshl_add_u64 v[42:43], v[22:23], 0, v[42:43]
	v_lshl_add_u64 v[40:41], v[22:23], 0, v[40:41]
	global_load_dword v200, v[42:43], off
	global_load_dword v201, v[40:41], off
	v_add_u32_e32 v42, s6, v26
	v_add_u32_e32 v40, s10, v25
	v_ashrrev_i32_e32 v43, 31, v42
	v_ashrrev_i32_e32 v41, 31, v40
	v_lshlrev_b64 v[42:43], 14, v[42:43]
	v_lshlrev_b64 v[40:41], 14, v[40:41]
	v_lshl_add_u64 v[42:43], v[22:23], 0, v[42:43]
	v_lshl_add_u64 v[40:41], v[22:23], 0, v[40:41]
	global_load_dword v202, v[42:43], off
	global_load_dword v203, v[40:41], off
	v_add_u32_e32 v42, s6, v28
	v_add_u32_e32 v40, s10, v27
	v_ashrrev_i32_e32 v43, 31, v42
	v_ashrrev_i32_e32 v41, 31, v40
	v_lshlrev_b64 v[42:43], 14, v[42:43]
	v_lshlrev_b64 v[40:41], 14, v[40:41]
	v_lshl_add_u64 v[42:43], v[22:23], 0, v[42:43]
	v_lshl_add_u64 v[40:41], v[22:23], 0, v[40:41]
	global_load_dword v204, v[42:43], off
	global_load_dword v205, v[40:41], off
	v_add_u32_e32 v42, s6, v30
	v_add_u32_e32 v40, s10, v29
	v_ashrrev_i32_e32 v43, 31, v42
	v_ashrrev_i32_e32 v41, 31, v40
	v_lshlrev_b64 v[42:43], 14, v[42:43]
	v_lshlrev_b64 v[40:41], 14, v[40:41]
	v_lshl_add_u64 v[42:43], v[22:23], 0, v[42:43]
	v_lshl_add_u64 v[40:41], v[22:23], 0, v[40:41]
	global_load_dword v206, v[42:43], off
	global_load_dword v207, v[40:41], off
	v_add_u32_e32 v42, s6, v32
	v_add_u32_e32 v40, s10, v31
	v_ashrrev_i32_e32 v43, 31, v42
	v_ashrrev_i32_e32 v41, 31, v40
	v_lshlrev_b64 v[42:43], 14, v[42:43]
	v_lshlrev_b64 v[40:41], 14, v[40:41]
	v_lshl_add_u64 v[42:43], v[22:23], 0, v[42:43]
	v_lshl_add_u64 v[40:41], v[22:23], 0, v[40:41]
	global_load_dword v208, v[42:43], off
	global_load_dword v209, v[40:41], off
	v_add_u32_e32 v42, s6, v34
	v_add_u32_e32 v40, s10, v33
	v_ashrrev_i32_e32 v43, 31, v42
	v_ashrrev_i32_e32 v41, 31, v40
	v_lshlrev_b64 v[42:43], 14, v[42:43]
	v_lshlrev_b64 v[40:41], 14, v[40:41]
	v_lshl_add_u64 v[42:43], v[22:23], 0, v[42:43]
	v_lshl_add_u64 v[40:41], v[22:23], 0, v[40:41]
	global_load_dword v210, v[42:43], off
	global_load_dword v211, v[40:41], off
	v_add_u32_e32 v42, s6, v36
	v_add_u32_e32 v40, s10, v35
	v_ashrrev_i32_e32 v43, 31, v42
	v_ashrrev_i32_e32 v41, 31, v40
	v_lshlrev_b64 v[42:43], 14, v[42:43]
	v_lshlrev_b64 v[40:41], 14, v[40:41]
	v_lshl_add_u64 v[42:43], v[22:23], 0, v[42:43]
	v_lshl_add_u64 v[40:41], v[22:23], 0, v[40:41]
	global_load_dword v212, v[42:43], off
	global_load_dword v213, v[40:41], off
	v_add_u32_e32 v42, s6, v38
	v_add_u32_e32 v40, s10, v37
	v_ashrrev_i32_e32 v43, 31, v42
	v_ashrrev_i32_e32 v41, 31, v40
	v_lshlrev_b64 v[42:43], 14, v[42:43]
	v_lshlrev_b64 v[40:41], 14, v[40:41]
	v_lshl_add_u64 v[42:43], v[22:23], 0, v[42:43]
	v_lshl_add_u64 v[40:41], v[22:23], 0, v[40:41]
	global_load_dword v214, v[42:43], off
	global_load_dword v215, v[40:41], off
	v_add_u32_e32 v39, s10, v5
	v_add_u32_e32 v44, s6, v4
	v_mad_u64_u32 v[40:41], s[16:17], v44, s59, v[6:7]
	v_mad_u64_u32 v[42:43], s[16:17], v39, s59, v[6:7]
	v_add_u32_e32 v39, s10, v7
	v_add_u32_e32 v44, s6, v8
	s_add_i32 s3, s3, 16
	s_add_i32 s1, s1, 16
	s_add_i32 s5, s5, -16
	s_cmp_lg_u32 s5, 0
	s_waitcnt vmcnt(14)
	ds_write_b32 v40, v200
	ds_write_b32 v42, v201
	v_mad_u64_u32 v[40:41], s[16:17], v44, s59, v[6:7]
	v_mad_u64_u32 v[42:43], s[16:17], v39, s59, v[6:7]
	v_add_u32_e32 v39, s10, v9
	v_add_u32_e32 v44, s6, v10
	s_waitcnt vmcnt(12)
	ds_write_b32 v40, v202
	ds_write_b32 v42, v203
	v_mad_u64_u32 v[40:41], s[16:17], v44, s59, v[6:7]
	v_mad_u64_u32 v[42:43], s[16:17], v39, s59, v[6:7]
	v_add_u32_e32 v39, s10, v11
	v_add_u32_e32 v44, s6, v12
	s_waitcnt vmcnt(10)
	ds_write_b32 v40, v204
	ds_write_b32 v42, v205
	v_mad_u64_u32 v[40:41], s[16:17], v44, s59, v[6:7]
	v_mad_u64_u32 v[42:43], s[16:17], v39, s59, v[6:7]
	v_add_u32_e32 v39, s10, v13
	v_add_u32_e32 v44, s6, v14
	s_waitcnt vmcnt(8)
	ds_write_b32 v40, v206
	ds_write_b32 v42, v207
	v_mad_u64_u32 v[40:41], s[16:17], v44, s59, v[6:7]
	v_mad_u64_u32 v[42:43], s[16:17], v39, s59, v[6:7]
	v_add_u32_e32 v39, s10, v15
	v_add_u32_e32 v44, s6, v16
	s_waitcnt vmcnt(6)
	ds_write_b32 v40, v208
	ds_write_b32 v42, v209
	v_mad_u64_u32 v[40:41], s[16:17], v44, s59, v[6:7]
	v_mad_u64_u32 v[42:43], s[16:17], v39, s59, v[6:7]
	v_add_u32_e32 v39, s10, v17
	v_add_u32_e32 v44, s6, v18
	s_waitcnt vmcnt(4)
	ds_write_b32 v40, v210
	ds_write_b32 v42, v211
	v_mad_u64_u32 v[40:41], s[16:17], v44, s59, v[6:7]
	v_mad_u64_u32 v[42:43], s[16:17], v39, s59, v[6:7]
	v_add_u32_e32 v44, s6, v20
	v_add_u32_e32 v39, s10, v19
	s_waitcnt vmcnt(2)
	ds_write_b32 v40, v212
	ds_write_b32 v42, v213
	v_mad_u64_u32 v[40:41], s[10:11], v44, s59, v[6:7]
	v_mad_u64_u32 v[42:43], s[10:11], v39, s59, v[6:7]
	s_waitcnt vmcnt(0)
	ds_write_b32 v40, v214
	ds_write_b32 v42, v215
	s_cbranch_scc1 .LBB0_222
	s_waitcnt lgkmcnt(0)
	ds_read2_b32 v[24:25], v51 offset1:33
	s_waitcnt lgkmcnt(0)
	v_cvt_pk_bf16_f32 v24, v24, v25
	ds_read2_b32 v[26:27], v51 offset0:66 offset1:99
	s_waitcnt lgkmcnt(0)
	v_cvt_pk_bf16_f32 v25, v26, v27
	ds_read2_b32 v[26:27], v51 offset0:132 offset1:165
	s_waitcnt lgkmcnt(0)
	v_cvt_pk_bf16_f32 v26, v26, v27
	ds_read2_b32 v[28:29], v51 offset0:198 offset1:231
	s_waitcnt lgkmcnt(0)
	v_cvt_pk_bf16_f32 v27, v28, v29
	v_add_u32_e32 v28, s0, v50
	s_ashr_i32 s3, s2, 31
	v_ashrrev_i32_e32 v29, 31, v28
	v_lshl_add_u64 v[22:23], s[2:3], 1, v[2:3]
	v_lshlrev_b64 v[28:29], 11, v[28:29]
	v_lshl_add_u64 v[28:29], v[22:23], 0, v[28:29]
	global_store_dwordx4 v[28:29], v[24:27], off
	ds_read2_b32 v[24:25], v51 offset0:8 offset1:41
	s_add_i32 s4, s4, s48
	s_waitcnt lgkmcnt(0)
	v_cvt_pk_bf16_f32 v24, v24, v25
	ds_read2_b32 v[26:27], v51 offset0:74 offset1:107
	s_waitcnt lgkmcnt(0)
	v_cvt_pk_bf16_f32 v25, v26, v27
	ds_read2_b32 v[26:27], v51 offset0:140 offset1:173
	s_waitcnt lgkmcnt(0)
	v_cvt_pk_bf16_f32 v26, v26, v27
	ds_read2_b32 v[28:29], v51 offset0:206 offset1:239
	s_waitcnt lgkmcnt(0)
	v_cvt_pk_bf16_f32 v27, v28, v29
	v_add_u32_e32 v28, s0, v52
	v_ashrrev_i32_e32 v29, 31, v28
	v_lshlrev_b64 v[28:29], 11, v[28:29]
	v_lshl_add_u64 v[28:29], v[22:23], 0, v[28:29]
	global_store_dwordx4 v[28:29], v[24:27], off
	ds_read2_b32 v[24:25], v51 offset0:16 offset1:49
	s_cmpk_gt_i32 s4, 0x7ff
	s_waitcnt lgkmcnt(0)
	v_cvt_pk_bf16_f32 v24, v24, v25
	ds_read2_b32 v[26:27], v51 offset0:82 offset1:115
	s_waitcnt lgkmcnt(0)
	v_cvt_pk_bf16_f32 v25, v26, v27
	ds_read2_b32 v[26:27], v51 offset0:148 offset1:181
	s_waitcnt lgkmcnt(0)
	v_cvt_pk_bf16_f32 v26, v26, v27
	ds_read2_b32 v[28:29], v51 offset0:214 offset1:247
	s_waitcnt lgkmcnt(0)
	v_cvt_pk_bf16_f32 v27, v28, v29
	v_add_u32_e32 v28, s0, v53
	v_ashrrev_i32_e32 v29, 31, v28
	v_lshlrev_b64 v[28:29], 11, v[28:29]
	v_lshl_add_u64 v[28:29], v[22:23], 0, v[28:29]
	global_store_dwordx4 v[28:29], v[24:27], off
	ds_read2_b32 v[24:25], v51 offset0:24 offset1:57
	s_waitcnt lgkmcnt(0)
	v_cvt_pk_bf16_f32 v24, v24, v25
	ds_read2_b32 v[26:27], v51 offset0:90 offset1:123
	s_waitcnt lgkmcnt(0)
	v_cvt_pk_bf16_f32 v25, v26, v27
	ds_read2_b32 v[26:27], v51 offset0:156 offset1:189
	s_waitcnt lgkmcnt(0)
	v_cvt_pk_bf16_f32 v26, v26, v27
	ds_read2_b32 v[28:29], v51 offset0:222 offset1:255
	s_waitcnt lgkmcnt(0)
	v_cvt_pk_bf16_f32 v27, v28, v29
	v_add_u32_e32 v28, s0, v54
	v_ashrrev_i32_e32 v29, 31, v28
	v_lshlrev_b64 v[28:29], 11, v[28:29]
	v_lshl_add_u64 v[22:23], v[22:23], 0, v[28:29]
	global_store_dwordx4 v[22:23], v[24:27], off
	s_waitcnt lgkmcnt(0)
	s_cbranch_scc0 .LBB0_221

.LBB0_906:
	s_lshl_b32 s33, s30, 1
	s_lshl_b32 s34, s29, 1
	v_add_u32_e32 v58, s33, v32
	v_add_u32_e32 v50, s34, v1
	v_ashrrev_i32_e32 v59, 31, v58
	v_ashrrev_i32_e32 v51, 31, v50
	v_lshlrev_b64 v[62:63], 8, v[58:59]
	v_lshlrev_b64 v[60:61], 8, v[50:51]
	v_lshl_add_u64 v[62:63], v[30:31], 0, v[62:63]
	v_lshl_add_u64 v[58:59], v[58:59], 2, s[0:1]
	v_lshl_add_u64 v[60:61], v[30:31], 0, v[60:61]
	global_load_dword v202, v[62:63], off
	s_nop 0
	global_load_dword v203, v[60:61], off
	v_lshl_add_u64 v[50:51], v[50:51], 2, s[0:1]
	global_load_dword v200, v[58:59], off
	s_nop 0
	global_load_dword v201, v[50:51], off
	v_add_u32_e32 v58, s33, v34
	v_add_u32_e32 v50, s34, v21
	v_ashrrev_i32_e32 v59, 31, v58
	v_ashrrev_i32_e32 v51, 31, v50
	v_lshlrev_b64 v[62:63], 8, v[58:59]
	v_lshlrev_b64 v[60:61], 8, v[50:51]
	v_lshl_add_u64 v[62:63], v[30:31], 0, v[62:63]
	v_lshl_add_u64 v[58:59], v[58:59], 2, s[0:1]
	v_lshl_add_u64 v[60:61], v[30:31], 0, v[60:61]
	global_load_dword v206, v[62:63], off
	s_nop 0
	global_load_dword v207, v[60:61], off
	v_lshl_add_u64 v[50:51], v[50:51], 2, s[0:1]
	global_load_dword v204, v[58:59], off
	s_nop 0
	global_load_dword v205, v[50:51], off
	v_add_u32_e32 v58, s33, v38
	v_add_u32_e32 v50, s34, v23
	v_ashrrev_i32_e32 v59, 31, v58
	v_ashrrev_i32_e32 v51, 31, v50
	v_lshlrev_b64 v[62:63], 8, v[58:59]
	v_lshlrev_b64 v[60:61], 8, v[50:51]
	v_lshl_add_u64 v[62:63], v[30:31], 0, v[62:63]
	v_lshl_add_u64 v[58:59], v[58:59], 2, s[0:1]
	v_lshl_add_u64 v[60:61], v[30:31], 0, v[60:61]
	global_load_dword v210, v[62:63], off
	s_nop 0
	global_load_dword v211, v[60:61], off
	v_lshl_add_u64 v[50:51], v[50:51], 2, s[0:1]
	global_load_dword v208, v[58:59], off
	s_nop 0
	global_load_dword v209, v[50:51], off
	v_add_u32_e32 v58, s33, v40
	v_add_u32_e32 v50, s34, v33
	v_ashrrev_i32_e32 v59, 31, v58
	v_ashrrev_i32_e32 v51, 31, v50
	v_lshlrev_b64 v[62:63], 8, v[58:59]
	v_lshlrev_b64 v[60:61], 8, v[50:51]
	v_lshl_add_u64 v[62:63], v[30:31], 0, v[62:63]
	v_lshl_add_u64 v[58:59], v[58:59], 2, s[0:1]
	v_lshl_add_u64 v[60:61], v[30:31], 0, v[60:61]
	global_load_dword v214, v[62:63], off
	s_nop 0
	global_load_dword v215, v[60:61], off
	v_lshl_add_u64 v[50:51], v[50:51], 2, s[0:1]
	global_load_dword v212, v[58:59], off
	s_nop 0
	global_load_dword v213, v[50:51], off
	v_add_u32_e32 v58, s33, v42
	v_add_u32_e32 v50, s34, v35
	v_ashrrev_i32_e32 v59, 31, v58
	v_ashrrev_i32_e32 v51, 31, v50
	v_lshlrev_b64 v[62:63], 8, v[58:59]
	v_lshlrev_b64 v[60:61], 8, v[50:51]
	v_lshl_add_u64 v[62:63], v[30:31], 0, v[62:63]
	v_lshl_add_u64 v[58:59], v[58:59], 2, s[0:1]
	v_lshl_add_u64 v[60:61], v[30:31], 0, v[60:61]
	global_load_dword v218, v[62:63], off
	s_nop 0
	global_load_dword v219, v[60:61], off
	v_lshl_add_u64 v[50:51], v[50:51], 2, s[0:1]
	global_load_dword v216, v[58:59], off
	s_nop 0
	global_load_dword v217, v[50:51], off
	v_add_u32_e32 v58, s33, v44
	v_add_u32_e32 v50, s34, v37
	v_ashrrev_i32_e32 v59, 31, v58
	v_ashrrev_i32_e32 v51, 31, v50
	v_lshlrev_b64 v[62:63], 8, v[58:59]
	v_lshlrev_b64 v[60:61], 8, v[50:51]
	v_lshl_add_u64 v[62:63], v[30:31], 0, v[62:63]
	v_lshl_add_u64 v[58:59], v[58:59], 2, s[0:1]
	v_lshl_add_u64 v[60:61], v[30:31], 0, v[60:61]
	global_load_dword v222, v[62:63], off
	s_nop 0
	global_load_dword v223, v[60:61], off
	v_lshl_add_u64 v[50:51], v[50:51], 2, s[0:1]
	global_load_dword v220, v[58:59], off
	s_nop 0
	global_load_dword v221, v[50:51], off
	v_add_u32_e32 v58, s33, v46
	v_add_u32_e32 v50, s34, v39
	v_ashrrev_i32_e32 v59, 31, v58
	v_ashrrev_i32_e32 v51, 31, v50
	v_lshlrev_b64 v[62:63], 8, v[58:59]
	v_lshlrev_b64 v[60:61], 8, v[50:51]
	v_lshl_add_u64 v[62:63], v[30:31], 0, v[62:63]
	v_lshl_add_u64 v[58:59], v[58:59], 2, s[0:1]
	v_lshl_add_u64 v[60:61], v[30:31], 0, v[60:61]
	global_load_dword v226, v[62:63], off
	s_nop 0
	global_load_dword v227, v[60:61], off
	v_lshl_add_u64 v[50:51], v[50:51], 2, s[0:1]
	global_load_dword v224, v[58:59], off
	s_nop 0
	global_load_dword v225, v[50:51], off
	v_add_u32_e32 v58, s33, v48
	v_add_u32_e32 v50, s34, v41
	v_ashrrev_i32_e32 v59, 31, v58
	v_ashrrev_i32_e32 v51, 31, v50
	v_lshlrev_b64 v[62:63], 8, v[58:59]
	v_lshlrev_b64 v[60:61], 8, v[50:51]
	v_lshl_add_u64 v[62:63], v[30:31], 0, v[62:63]
	v_lshl_add_u64 v[58:59], v[58:59], 2, s[0:1]
	v_lshl_add_u64 v[60:61], v[30:31], 0, v[60:61]
	global_load_dword v230, v[62:63], off
	s_nop 0
	global_load_dword v231, v[60:61], off
	v_lshl_add_u64 v[50:51], v[50:51], 2, s[0:1]
	global_load_dword v228, v[58:59], off
	s_nop 0
	global_load_dword v229, v[50:51], off
	v_add_u32_e32 v45, s33, v4
	v_add_u32_e32 v43, s34, v5
	v_mad_u64_u32 v[60:61], s[42:43], v43, s59, v[6:7]
	v_add_u32_e32 v43, s34, v7
	s_add_i32 s30, s30, 16
	s_add_i32 s29, s29, 16
	s_add_i32 s31, s31, -16
	s_cmp_lg_u32 s31, 0
	s_waitcnt vmcnt(28)
	v_pk_mul_f32 v[50:51], v[202:203], v[200:201]
	v_mad_u64_u32 v[58:59], s[42:43], v45, s59, v[6:7]
	ds_write_b32 v58, v50
	ds_write_b32 v60, v51
	v_add_u32_e32 v45, s33, v8
	v_mad_u64_u32 v[60:61], s[42:43], v43, s59, v[6:7]
	v_add_u32_e32 v43, s34, v9
	s_waitcnt vmcnt(24)
	v_pk_mul_f32 v[50:51], v[206:207], v[204:205]
	v_mad_u64_u32 v[58:59], s[42:43], v45, s59, v[6:7]
	ds_write_b32 v58, v50
	ds_write_b32 v60, v51
	v_add_u32_e32 v45, s33, v10
	v_mad_u64_u32 v[60:61], s[42:43], v43, s59, v[6:7]
	v_add_u32_e32 v43, s34, v11
	s_waitcnt vmcnt(20)
	v_pk_mul_f32 v[50:51], v[210:211], v[208:209]
	v_mad_u64_u32 v[58:59], s[42:43], v45, s59, v[6:7]
	ds_write_b32 v58, v50
	ds_write_b32 v60, v51
	v_add_u32_e32 v45, s33, v12
	v_mad_u64_u32 v[60:61], s[42:43], v43, s59, v[6:7]
	v_add_u32_e32 v43, s34, v13
	s_waitcnt vmcnt(16)
	v_pk_mul_f32 v[50:51], v[214:215], v[212:213]
	v_mad_u64_u32 v[58:59], s[42:43], v45, s59, v[6:7]
	ds_write_b32 v58, v50
	ds_write_b32 v60, v51
	v_add_u32_e32 v45, s33, v14
	v_mad_u64_u32 v[60:61], s[42:43], v43, s59, v[6:7]
	v_add_u32_e32 v43, s34, v15
	s_waitcnt vmcnt(12)
	v_pk_mul_f32 v[50:51], v[218:219], v[216:217]
	v_mad_u64_u32 v[58:59], s[42:43], v45, s59, v[6:7]
	ds_write_b32 v58, v50
	ds_write_b32 v60, v51
	v_add_u32_e32 v45, s33, v16
	v_mad_u64_u32 v[60:61], s[42:43], v43, s59, v[6:7]
	v_add_u32_e32 v43, s34, v17
	s_waitcnt vmcnt(8)
	v_pk_mul_f32 v[50:51], v[222:223], v[220:221]
	v_mad_u64_u32 v[58:59], s[42:43], v45, s59, v[6:7]
	ds_write_b32 v58, v50
	ds_write_b32 v60, v51
	v_add_u32_e32 v45, s33, v18
	v_mad_u64_u32 v[60:61], s[42:43], v43, s59, v[6:7]
	v_add_u32_e32 v43, s34, v19
	s_waitcnt vmcnt(4)
	v_pk_mul_f32 v[50:51], v[226:227], v[224:225]
	v_mad_u64_u32 v[58:59], s[42:43], v45, s59, v[6:7]
	ds_write_b32 v58, v50
	ds_write_b32 v60, v51
	v_add_u32_e32 v45, s33, v20
	v_mad_u64_u32 v[60:61], s[34:35], v43, s59, v[6:7]
	s_waitcnt vmcnt(0)
	v_pk_mul_f32 v[50:51], v[230:231], v[228:229]
	v_mad_u64_u32 v[58:59], s[34:35], v45, s59, v[6:7]
	ds_write_b32 v58, v50
	ds_write_b32 v60, v51
	s_cbranch_scc1 .LBB0_906
	s_waitcnt lgkmcnt(0)
	v_add_u32_e32 v38, s28, v52
	ds_read2_b32 v[30:31], v53 offset1:33
	s_ashr_i32 s41, s40, 31
	v_ashrrev_i32_e32 v39, 31, v38
	s_waitcnt lgkmcnt(0)
	v_cvt_pk_bf16_f32 v30, v30, v31
	ds_read2_b32 v[32:33], v53 offset0:66 offset1:99
	v_lshl_add_u64 v[40:41], s[40:41], 1, v[28:29]
	v_lshlrev_b64 v[38:39], 12, v[38:39]
	s_waitcnt lgkmcnt(0)
	v_cvt_pk_bf16_f32 v31, v32, v33
	ds_read2_b32 v[32:33], v53 offset0:132 offset1:165
	v_lshl_add_u64 v[38:39], v[40:41], 0, v[38:39]
	s_waitcnt lgkmcnt(0)
	v_cvt_pk_bf16_f32 v32, v32, v33
	ds_read2_b32 v[34:35], v53 offset0:198 offset1:231
	s_waitcnt lgkmcnt(0)
	v_cvt_pk_bf16_f32 v33, v34, v35
	global_store_dwordx4 v[38:39], v[30:33], off
	v_add_u32_e32 v38, s28, v54
	ds_read2_b32 v[34:35], v53 offset0:8 offset1:41
	s_waitcnt lgkmcnt(0)
	v_cvt_pk_bf16_f32 v30, v34, v35
	ds_read2_b32 v[32:33], v53 offset0:74 offset1:107
	v_ashrrev_i32_e32 v39, 31, v38
	s_waitcnt lgkmcnt(0)
	v_cvt_pk_bf16_f32 v31, v32, v33
	ds_read2_b32 v[32:33], v53 offset0:140 offset1:173
	v_lshlrev_b64 v[38:39], 12, v[38:39]
	s_waitcnt lgkmcnt(0)
	v_cvt_pk_bf16_f32 v32, v32, v33
	ds_read2_b32 v[34:35], v53 offset0:206 offset1:239
	s_waitcnt lgkmcnt(0)
	v_cvt_pk_bf16_f32 v33, v34, v35
	v_lshl_add_u64 v[38:39], v[40:41], 0, v[38:39]
	ds_read2_b32 v[34:35], v53 offset0:16 offset1:49
	global_store_dwordx4 v[38:39], v[30:33], off
	v_add_u32_e32 v38, s28, v55
	v_ashrrev_i32_e32 v39, 31, v38
	s_waitcnt lgkmcnt(0)
	v_cvt_pk_bf16_f32 v30, v34, v35
	ds_read2_b32 v[32:33], v53 offset0:82 offset1:115
	s_waitcnt lgkmcnt(0)
	v_cvt_pk_bf16_f32 v31, v32, v33
	ds_read2_b32 v[32:33], v53 offset0:148 offset1:181
	s_waitcnt lgkmcnt(0)
	v_cvt_pk_bf16_f32 v32, v32, v33
	ds_read2_b32 v[34:35], v53 offset0:214 offset1:247
	v_lshlrev_b64 v[38:39], 12, v[38:39]
	s_waitcnt lgkmcnt(0)
	v_cvt_pk_bf16_f32 v33, v34, v35
	ds_read2_b32 v[34:35], v53 offset0:24 offset1:57
	v_lshl_add_u64 v[38:39], v[40:41], 0, v[38:39]
	global_store_dwordx4 v[38:39], v[30:33], off
	s_add_i32 s21, s21, s45
	s_cmp_lt_i32 s21, 32
	s_waitcnt lgkmcnt(0)
	v_cvt_pk_bf16_f32 v30, v34, v35
	v_add_u32_e32 v34, s28, v56
	v_ashrrev_i32_e32 v35, 31, v34
	ds_read2_b32 v[32:33], v53 offset0:90 offset1:123
	v_lshlrev_b64 v[34:35], 12, v[34:35]
	s_waitcnt lgkmcnt(0)
	v_cvt_pk_bf16_f32 v31, v32, v33
	ds_read2_b32 v[32:33], v53 offset0:156 offset1:189
	v_lshl_add_u64 v[34:35], v[40:41], 0, v[34:35]
	s_waitcnt lgkmcnt(0)
	v_cvt_pk_bf16_f32 v32, v32, v33
	ds_read2_b32 v[38:39], v53 offset0:222 offset1:255
	s_waitcnt lgkmcnt(0)
	v_cvt_pk_bf16_f32 v33, v38, v39
	global_store_dwordx4 v[34:35], v[30:33], off
	s_waitcnt lgkmcnt(0)
	s_cbranch_scc1 .LBB0_905

.LBB0_916:
	s_lshl_b32 s29, s21, 1
	s_lshl_b32 s30, s20, 1
	v_add_u32_e32 v58, s29, v32
	v_add_u32_e32 v50, s30, v1
	v_ashrrev_i32_e32 v59, 31, v58
	v_ashrrev_i32_e32 v51, 31, v50
	v_lshlrev_b64 v[62:63], 8, v[58:59]
	v_lshlrev_b64 v[60:61], 8, v[50:51]
	v_lshl_add_u64 v[62:63], v[30:31], 0, v[62:63]
	v_lshl_add_u64 v[58:59], v[58:59], 2, s[4:5]
	v_lshl_add_u64 v[60:61], v[30:31], 0, v[60:61]
	global_load_dword v202, v[62:63], off
	s_nop 0
	global_load_dword v203, v[60:61], off
	v_lshl_add_u64 v[50:51], v[50:51], 2, s[4:5]
	global_load_dword v200, v[58:59], off
	s_nop 0
	global_load_dword v201, v[50:51], off
	v_add_u32_e32 v58, s29, v34
	v_add_u32_e32 v50, s30, v21
	v_ashrrev_i32_e32 v59, 31, v58
	v_ashrrev_i32_e32 v51, 31, v50
	v_lshlrev_b64 v[62:63], 8, v[58:59]
	v_lshlrev_b64 v[60:61], 8, v[50:51]
	v_lshl_add_u64 v[62:63], v[30:31], 0, v[62:63]
	v_lshl_add_u64 v[58:59], v[58:59], 2, s[4:5]
	v_lshl_add_u64 v[60:61], v[30:31], 0, v[60:61]
	global_load_dword v206, v[62:63], off
	s_nop 0
	global_load_dword v207, v[60:61], off
	v_lshl_add_u64 v[50:51], v[50:51], 2, s[4:5]
	global_load_dword v204, v[58:59], off
	s_nop 0
	global_load_dword v205, v[50:51], off
	v_add_u32_e32 v58, s29, v38
	v_add_u32_e32 v50, s30, v23
	v_ashrrev_i32_e32 v59, 31, v58
	v_ashrrev_i32_e32 v51, 31, v50
	v_lshlrev_b64 v[62:63], 8, v[58:59]
	v_lshlrev_b64 v[60:61], 8, v[50:51]
	v_lshl_add_u64 v[62:63], v[30:31], 0, v[62:63]
	v_lshl_add_u64 v[58:59], v[58:59], 2, s[4:5]
	v_lshl_add_u64 v[60:61], v[30:31], 0, v[60:61]
	global_load_dword v210, v[62:63], off
	s_nop 0
	global_load_dword v211, v[60:61], off
	v_lshl_add_u64 v[50:51], v[50:51], 2, s[4:5]
	global_load_dword v208, v[58:59], off
	s_nop 0
	global_load_dword v209, v[50:51], off
	v_add_u32_e32 v58, s29, v40
	v_add_u32_e32 v50, s30, v33
	v_ashrrev_i32_e32 v59, 31, v58
	v_ashrrev_i32_e32 v51, 31, v50
	v_lshlrev_b64 v[62:63], 8, v[58:59]
	v_lshlrev_b64 v[60:61], 8, v[50:51]
	v_lshl_add_u64 v[62:63], v[30:31], 0, v[62:63]
	v_lshl_add_u64 v[58:59], v[58:59], 2, s[4:5]
	v_lshl_add_u64 v[60:61], v[30:31], 0, v[60:61]
	global_load_dword v214, v[62:63], off
	s_nop 0
	global_load_dword v215, v[60:61], off
	v_lshl_add_u64 v[50:51], v[50:51], 2, s[4:5]
	global_load_dword v212, v[58:59], off
	s_nop 0
	global_load_dword v213, v[50:51], off
	v_add_u32_e32 v58, s29, v42
	v_add_u32_e32 v50, s30, v35
	v_ashrrev_i32_e32 v59, 31, v58
	v_ashrrev_i32_e32 v51, 31, v50
	v_lshlrev_b64 v[62:63], 8, v[58:59]
	v_lshlrev_b64 v[60:61], 8, v[50:51]
	v_lshl_add_u64 v[62:63], v[30:31], 0, v[62:63]
	v_lshl_add_u64 v[58:59], v[58:59], 2, s[4:5]
	v_lshl_add_u64 v[60:61], v[30:31], 0, v[60:61]
	global_load_dword v218, v[62:63], off
	s_nop 0
	global_load_dword v219, v[60:61], off
	v_lshl_add_u64 v[50:51], v[50:51], 2, s[4:5]
	global_load_dword v216, v[58:59], off
	s_nop 0
	global_load_dword v217, v[50:51], off
	v_add_u32_e32 v58, s29, v44
	v_add_u32_e32 v50, s30, v37
	v_ashrrev_i32_e32 v59, 31, v58
	v_ashrrev_i32_e32 v51, 31, v50
	v_lshlrev_b64 v[62:63], 8, v[58:59]
	v_lshlrev_b64 v[60:61], 8, v[50:51]
	v_lshl_add_u64 v[62:63], v[30:31], 0, v[62:63]
	v_lshl_add_u64 v[58:59], v[58:59], 2, s[4:5]
	v_lshl_add_u64 v[60:61], v[30:31], 0, v[60:61]
	global_load_dword v222, v[62:63], off
	s_nop 0
	global_load_dword v223, v[60:61], off
	v_lshl_add_u64 v[50:51], v[50:51], 2, s[4:5]
	global_load_dword v220, v[58:59], off
	s_nop 0
	global_load_dword v221, v[50:51], off
	v_add_u32_e32 v58, s29, v46
	v_add_u32_e32 v50, s30, v39
	v_ashrrev_i32_e32 v59, 31, v58
	v_ashrrev_i32_e32 v51, 31, v50
	v_lshlrev_b64 v[62:63], 8, v[58:59]
	v_lshlrev_b64 v[60:61], 8, v[50:51]
	v_lshl_add_u64 v[62:63], v[30:31], 0, v[62:63]
	v_lshl_add_u64 v[58:59], v[58:59], 2, s[4:5]
	v_lshl_add_u64 v[60:61], v[30:31], 0, v[60:61]
	global_load_dword v226, v[62:63], off
	s_nop 0
	global_load_dword v227, v[60:61], off
	v_lshl_add_u64 v[50:51], v[50:51], 2, s[4:5]
	global_load_dword v224, v[58:59], off
	s_nop 0
	global_load_dword v225, v[50:51], off
	v_add_u32_e32 v58, s29, v48
	v_add_u32_e32 v50, s30, v41
	v_ashrrev_i32_e32 v59, 31, v58
	v_ashrrev_i32_e32 v51, 31, v50
	v_lshlrev_b64 v[62:63], 8, v[58:59]
	v_lshlrev_b64 v[60:61], 8, v[50:51]
	v_lshl_add_u64 v[62:63], v[30:31], 0, v[62:63]
	v_lshl_add_u64 v[58:59], v[58:59], 2, s[4:5]
	v_lshl_add_u64 v[60:61], v[30:31], 0, v[60:61]
	global_load_dword v230, v[62:63], off
	s_nop 0
	global_load_dword v231, v[60:61], off
	v_lshl_add_u64 v[50:51], v[50:51], 2, s[4:5]
	global_load_dword v228, v[58:59], off
	s_nop 0
	global_load_dword v229, v[50:51], off
	v_add_u32_e32 v45, s29, v4
	v_add_u32_e32 v43, s30, v5
	v_mad_u64_u32 v[60:61], s[34:35], v43, s59, v[6:7]
	v_add_u32_e32 v43, s30, v7
	s_add_i32 s21, s21, 16
	s_add_i32 s20, s20, 16
	s_add_i32 s27, s27, -16
	s_cmp_lg_u32 s27, 0
	s_waitcnt vmcnt(28)
	v_pk_mul_f32 v[50:51], v[202:203], v[200:201]
	v_mad_u64_u32 v[58:59], s[34:35], v45, s59, v[6:7]
	ds_write_b32 v58, v50
	ds_write_b32 v60, v51
	v_add_u32_e32 v45, s29, v8
	v_mad_u64_u32 v[60:61], s[34:35], v43, s59, v[6:7]
	v_add_u32_e32 v43, s30, v9
	s_waitcnt vmcnt(24)
	v_pk_mul_f32 v[50:51], v[206:207], v[204:205]
	v_mad_u64_u32 v[58:59], s[34:35], v45, s59, v[6:7]
	ds_write_b32 v58, v50
	ds_write_b32 v60, v51
	v_add_u32_e32 v45, s29, v10
	v_mad_u64_u32 v[60:61], s[34:35], v43, s59, v[6:7]
	v_add_u32_e32 v43, s30, v11
	s_waitcnt vmcnt(20)
	v_pk_mul_f32 v[50:51], v[210:211], v[208:209]
	v_mad_u64_u32 v[58:59], s[34:35], v45, s59, v[6:7]
	ds_write_b32 v58, v50
	ds_write_b32 v60, v51
	v_add_u32_e32 v45, s29, v12
	v_mad_u64_u32 v[60:61], s[34:35], v43, s59, v[6:7]
	v_add_u32_e32 v43, s30, v13
	s_waitcnt vmcnt(16)
	v_pk_mul_f32 v[50:51], v[214:215], v[212:213]
	v_mad_u64_u32 v[58:59], s[34:35], v45, s59, v[6:7]
	ds_write_b32 v58, v50
	ds_write_b32 v60, v51
	v_add_u32_e32 v45, s29, v14
	v_mad_u64_u32 v[60:61], s[34:35], v43, s59, v[6:7]
	v_add_u32_e32 v43, s30, v15
	s_waitcnt vmcnt(12)
	v_pk_mul_f32 v[50:51], v[218:219], v[216:217]
	v_mad_u64_u32 v[58:59], s[34:35], v45, s59, v[6:7]
	ds_write_b32 v58, v50
	ds_write_b32 v60, v51
	v_add_u32_e32 v45, s29, v16
	v_mad_u64_u32 v[60:61], s[34:35], v43, s59, v[6:7]
	v_add_u32_e32 v43, s30, v17
	s_waitcnt vmcnt(8)
	v_pk_mul_f32 v[50:51], v[222:223], v[220:221]
	v_mad_u64_u32 v[58:59], s[34:35], v45, s59, v[6:7]
	ds_write_b32 v58, v50
	ds_write_b32 v60, v51
	v_add_u32_e32 v45, s29, v18
	v_mad_u64_u32 v[60:61], s[34:35], v43, s59, v[6:7]
	v_add_u32_e32 v43, s30, v19
	s_waitcnt vmcnt(4)
	v_pk_mul_f32 v[50:51], v[226:227], v[224:225]
	v_mad_u64_u32 v[58:59], s[34:35], v45, s59, v[6:7]
	ds_write_b32 v58, v50
	ds_write_b32 v60, v51
	v_add_u32_e32 v45, s29, v20
	v_mad_u64_u32 v[60:61], s[30:31], v43, s59, v[6:7]
	s_waitcnt vmcnt(0)
	v_pk_mul_f32 v[50:51], v[230:231], v[228:229]
	v_mad_u64_u32 v[58:59], s[30:31], v45, s59, v[6:7]
	ds_write_b32 v58, v50
	ds_write_b32 v60, v51
	s_cbranch_scc1 .LBB0_916
	s_waitcnt lgkmcnt(0)
	v_add_u32_e32 v38, s26, v52
	ds_read2_b32 v[30:31], v53 offset1:33
	s_ashr_i32 s29, s28, 31
	v_ashrrev_i32_e32 v39, 31, v38
	s_waitcnt lgkmcnt(0)
	v_cvt_pk_bf16_f32 v30, v30, v31
	ds_read2_b32 v[32:33], v53 offset0:66 offset1:99
	v_lshl_add_u64 v[40:41], s[28:29], 1, v[28:29]
	v_lshlrev_b64 v[38:39], 12, v[38:39]
	s_waitcnt lgkmcnt(0)
	v_cvt_pk_bf16_f32 v31, v32, v33
	ds_read2_b32 v[32:33], v53 offset0:132 offset1:165
	v_lshl_add_u64 v[38:39], v[40:41], 0, v[38:39]
	s_waitcnt lgkmcnt(0)
	v_cvt_pk_bf16_f32 v32, v32, v33
	ds_read2_b32 v[34:35], v53 offset0:198 offset1:231
	s_waitcnt lgkmcnt(0)
	v_cvt_pk_bf16_f32 v33, v34, v35
	global_store_dwordx4 v[38:39], v[30:33], off
	v_add_u32_e32 v38, s26, v54
	ds_read2_b32 v[34:35], v53 offset0:8 offset1:41
	s_waitcnt lgkmcnt(0)
	v_cvt_pk_bf16_f32 v30, v34, v35
	ds_read2_b32 v[32:33], v53 offset0:74 offset1:107
	v_ashrrev_i32_e32 v39, 31, v38
	s_waitcnt lgkmcnt(0)
	v_cvt_pk_bf16_f32 v31, v32, v33
	ds_read2_b32 v[32:33], v53 offset0:140 offset1:173
	v_lshlrev_b64 v[38:39], 12, v[38:39]
	s_waitcnt lgkmcnt(0)
	v_cvt_pk_bf16_f32 v32, v32, v33
	ds_read2_b32 v[34:35], v53 offset0:206 offset1:239
	s_waitcnt lgkmcnt(0)
	v_cvt_pk_bf16_f32 v33, v34, v35
	v_lshl_add_u64 v[38:39], v[40:41], 0, v[38:39]
	ds_read2_b32 v[34:35], v53 offset0:16 offset1:49
	global_store_dwordx4 v[38:39], v[30:33], off
	v_add_u32_e32 v38, s26, v55
	v_ashrrev_i32_e32 v39, 31, v38
	s_waitcnt lgkmcnt(0)
	v_cvt_pk_bf16_f32 v30, v34, v35
	ds_read2_b32 v[32:33], v53 offset0:82 offset1:115
	s_waitcnt lgkmcnt(0)
	v_cvt_pk_bf16_f32 v31, v32, v33
	ds_read2_b32 v[32:33], v53 offset0:148 offset1:181
	s_waitcnt lgkmcnt(0)
	v_cvt_pk_bf16_f32 v32, v32, v33
	ds_read2_b32 v[34:35], v53 offset0:214 offset1:247
	v_lshlrev_b64 v[38:39], 12, v[38:39]
	s_waitcnt lgkmcnt(0)
	v_cvt_pk_bf16_f32 v33, v34, v35
	ds_read2_b32 v[34:35], v53 offset0:24 offset1:57
	v_lshl_add_u64 v[38:39], v[40:41], 0, v[38:39]
	global_store_dwordx4 v[38:39], v[30:33], off
	s_add_i32 s19, s19, s45
	s_cmp_lt_i32 s19, 32
	s_waitcnt lgkmcnt(0)
	v_cvt_pk_bf16_f32 v30, v34, v35
	v_add_u32_e32 v34, s26, v56
	v_ashrrev_i32_e32 v35, 31, v34
	ds_read2_b32 v[32:33], v53 offset0:90 offset1:123
	v_lshlrev_b64 v[34:35], 12, v[34:35]
	s_waitcnt lgkmcnt(0)
	v_cvt_pk_bf16_f32 v31, v32, v33
	ds_read2_b32 v[32:33], v53 offset0:156 offset1:189
	v_lshl_add_u64 v[34:35], v[40:41], 0, v[34:35]
	s_waitcnt lgkmcnt(0)
	v_cvt_pk_bf16_f32 v32, v32, v33
	ds_read2_b32 v[38:39], v53 offset0:222 offset1:255
	s_waitcnt lgkmcnt(0)
	v_cvt_pk_bf16_f32 v33, v38, v39
	global_store_dwordx4 v[34:35], v[30:33], off
	s_waitcnt lgkmcnt(0)
	s_cbranch_scc1 .LBB0_915
